# MMA segments at setprio 3 (on top of v24)
# speedup vs baseline: 1.0133x; 1.0098x over previous
; #define PG8_WAIT_V(n) asm volatile("s_waitcnt vmcnt(" #n ")" ::: "memory")
; template <class Epi, bool ALIGN_EPI, bool SP2, class Hook>
; __device__ __forceinline__ void gemm_phase(LAS unsigned char* lds, const Gemm g, const StaticOrder& S, const Epi& E, Acc& acc, const bool fresh, const Hook& H, const int wave_id) {
;     ...
;         if constexpr (SP2 && Epi::NSTORE > 0) {
;             const Src a1 = cA + kstep, a2 = cA + 2 * kstep, b2 = cB + 2 * kstep, a3 = a2 + kstep, b3 = b2 + kstep;
;             if constexpr (Epi::NSTORE == 16) PG8_TRIP_SP2(PG8_WAIT_V(24)); else PG8_TRIP_SP2(PG8_WAIT_V(16));
;             t0 = 2;
.LBB0_382:
	ds_read_b128 v[2:5], v150
	ds_read_b128 v[6:9], v150 offset:1024
	ds_read_b128 v[10:13], v150 offset:2048
	ds_read_b128 v[14:17], v150 offset:3072
	ds_read_b128 v[18:21], v151
	ds_read_b128 v[22:25], v151 offset:1024
	ds_read_b128 v[26:29], v151 offset:2048
	ds_read_b128 v[30:33], v151 offset:3072
	s_or_b32 s9, s68, 0x100
	s_or_b32 s8, s68, 0x180
	s_or_b32 s10, s69, 0x100
	s_or_b32 s11, s68, 0x40080
	s_mov_b32 m0, s45
	ds_read_b128 v[34:37], v149
	ds_read_b128 v[38:41], v149 offset:1024
	ds_read_b128 v[42:45], v149 offset:2048
	ds_read_b128 v[46:49], v149 offset:3072
	ds_read_b128 v[50:53], v149 offset:4096
	ds_read_b128 v[54:57], v149 offset:5120
	ds_read_b128 v[58:61], v149 offset:6144
	ds_read_b128 v[62:65], v149 offset:7168
	buffer_load_dwordx4 v144, s[0:3], s11 offen lds
	s_mov_b32 m0, s46
	s_nop 0
	buffer_load_dwordx4 v146, s[0:3], s11 offen lds
	s_waitcnt vmcnt(24)
	s_waitcnt lgkmcnt(0)
	s_setprio 3
	s_barrier
	v_mfma_f32_16x16x32_bf16 v[86:89], v[10:13], v[50:53], 0
	v_mfma_f32_16x16x32_bf16 v[92:95], v[14:17], v[54:57], v[86:89]
	v_mfma_f32_16x16x32_bf16 v[86:89], v[2:5], v[58:61], 0
	v_mfma_f32_16x16x32_bf16 v[66:69], v[2:5], v[34:37], 0
	v_mfma_f32_16x16x32_bf16 v[70:73], v[10:13], v[34:37], 0
	v_mfma_f32_16x16x32_bf16 v[74:77], v[2:5], v[42:45], 0
	v_mfma_f32_16x16x32_bf16 v[78:81], v[10:13], v[42:45], 0
	v_mfma_f32_16x16x32_bf16 v[82:85], v[2:5], v[50:53], 0
	v_mfma_f32_16x16x32_bf16 v[96:99], v[6:9], v[62:65], v[86:89]
	v_mfma_f32_16x16x32_bf16 v[86:89], v[10:13], v[58:61], 0
	v_mfma_f32_16x16x32_bf16 v[66:69], v[6:9], v[38:41], v[66:69]
	v_mfma_f32_16x16x32_bf16 v[70:73], v[14:17], v[38:41], v[70:73]
	v_mfma_f32_16x16x32_bf16 v[74:77], v[6:9], v[46:49], v[74:77]
	v_mfma_f32_16x16x32_bf16 v[78:81], v[14:17], v[46:49], v[78:81]
	v_mfma_f32_16x16x32_bf16 v[82:85], v[6:9], v[54:57], v[82:85]
	v_mfma_f32_16x16x32_bf16 v[104:107], v[14:17], v[62:65], v[86:89]
	v_mfma_f32_16x16x32_bf16 v[86:89], v[18:21], v[34:37], 0
	v_mfma_f32_16x16x32_bf16 v[34:37], v[26:29], v[34:37], 0
	v_mfma_f32_16x16x32_bf16 v[116:119], v[30:33], v[38:41], v[34:37]
	v_mfma_f32_16x16x32_bf16 v[34:37], v[18:21], v[42:45], 0
	v_mfma_f32_16x16x32_bf16 v[132:135], v[22:25], v[46:49], v[34:37]
	v_mfma_f32_16x16x32_bf16 v[34:37], v[26:29], v[42:45], 0
	v_mfma_f32_16x16x32_bf16 v[108:111], v[22:25], v[38:41], v[86:89]
	v_mfma_f32_16x16x32_bf16 v[40:43], v[30:33], v[46:49], v[34:37]
	v_mfma_f32_16x16x32_bf16 v[34:37], v[18:21], v[50:53], 0
	v_mfma_f32_16x16x32_bf16 v[44:47], v[22:25], v[54:57], v[34:37]
	v_mfma_f32_16x16x32_bf16 v[34:37], v[26:29], v[50:53], 0
	v_mfma_f32_16x16x32_bf16 v[48:51], v[30:33], v[54:57], v[34:37]
	v_mfma_f32_16x16x32_bf16 v[34:37], v[18:21], v[58:61], 0
	v_mfma_f32_16x16x32_bf16 v[52:55], v[22:25], v[62:65], v[34:37]
	v_mfma_f32_16x16x32_bf16 v[34:37], v[26:29], v[58:61], 0
	v_mfma_f32_16x16x32_bf16 v[60:63], v[30:33], v[62:65], v[34:37]
	s_barrier
	s_setprio 0
	s_mov_b32 m0, s92
	s_nop 3
	ds_read_b128 v[34:37], v149 offset:16384
	ds_read_b128 v[56:59], v149 offset:17408
	ds_read_b128 v[86:89], v149 offset:18432
	ds_read_b128 v[100:103], v149 offset:19456
	ds_read_b128 v[112:115], v149 offset:20480
	ds_read_b128 v[120:123], v149 offset:21504
	ds_read_b128 v[124:127], v149 offset:22528
	ds_read_b128 v[128:131], v149 offset:23552
	buffer_load_dwordx4 v145, s[4:7], s10 offen lds
	s_mov_b32 m0, s93
	s_nop 0
	buffer_load_dwordx4 v147, s[4:7], s10 offen lds
	s_or_b32 s10, s69, 0x40100
	s_mov_b32 m0, s94
	s_nop 0
	buffer_load_dwordx4 v145, s[4:7], s10 offen lds
	s_mov_b32 m0, s95
	s_nop 0
	buffer_load_dwordx4 v147, s[4:7], s10 offen lds
	s_mov_b32 m0, s44
	s_nop 0
	buffer_load_dwordx4 v144, s[0:3], s9 offen lds
	s_mov_b32 m0, s36
	s_nop 0
	buffer_load_dwordx4 v146, s[0:3], s9 offen lds
	s_waitcnt vmcnt(24)
	s_waitcnt lgkmcnt(0)
	s_setprio 3
	s_barrier
	v_mfma_f32_16x16x32_bf16 v[136:139], v[2:5], v[34:37], 0
	v_mfma_f32_16x16x32_bf16 v[154:157], v[2:5], v[86:89], 0
	v_mfma_f32_16x16x32_bf16 v[162:165], v[2:5], v[112:115], 0
	v_mfma_f32_16x16x32_bf16 v[2:5], v[2:5], v[124:127], 0
	v_mfma_f32_16x16x32_bf16 v[136:139], v[6:9], v[56:59], v[136:139]
	v_mfma_f32_16x16x32_bf16 v[140:143], v[10:13], v[34:37], 0
	v_mfma_f32_16x16x32_bf16 v[154:157], v[6:9], v[100:103], v[154:157]
	v_mfma_f32_16x16x32_bf16 v[158:161], v[10:13], v[86:89], 0
	v_mfma_f32_16x16x32_bf16 v[162:165], v[6:9], v[120:123], v[162:165]
	v_mfma_f32_16x16x32_bf16 v[166:169], v[10:13], v[112:115], 0
	v_mfma_f32_16x16x32_bf16 v[2:5], v[6:9], v[128:131], v[2:5]
	v_mfma_f32_16x16x32_bf16 v[6:9], v[10:13], v[124:127], 0
	v_mfma_f32_16x16x32_bf16 v[140:143], v[14:17], v[56:59], v[140:143]
	v_mfma_f32_16x16x32_bf16 v[158:161], v[14:17], v[100:103], v[158:161]
	v_mfma_f32_16x16x32_bf16 v[166:169], v[14:17], v[120:123], v[166:169]
	v_mfma_f32_16x16x32_bf16 v[170:173], v[14:17], v[128:131], v[6:9]
	v_mfma_f32_16x16x32_bf16 v[6:9], v[18:21], v[34:37], 0
	v_mfma_f32_16x16x32_bf16 v[174:177], v[22:25], v[56:59], v[6:9]
	v_mfma_f32_16x16x32_bf16 v[6:9], v[26:29], v[34:37], 0
	v_mfma_f32_16x16x32_bf16 v[178:181], v[30:33], v[56:59], v[6:9]
	v_mfma_f32_16x16x32_bf16 v[6:9], v[18:21], v[86:89], 0
	v_mfma_f32_16x16x32_bf16 v[182:185], v[22:25], v[100:103], v[6:9]
	v_mfma_f32_16x16x32_bf16 v[6:9], v[26:29], v[86:89], 0
	v_mfma_f32_16x16x32_bf16 v[186:189], v[30:33], v[100:103], v[6:9]
	v_mfma_f32_16x16x32_bf16 v[6:9], v[18:21], v[112:115], 0
	v_mfma_f32_16x16x32_bf16 v[190:193], v[22:25], v[120:123], v[6:9]
	v_mfma_f32_16x16x32_bf16 v[6:9], v[26:29], v[112:115], 0
	v_mfma_f32_16x16x32_bf16 v[212:215], v[30:33], v[120:123], v[6:9]
	v_mfma_f32_16x16x32_bf16 v[6:9], v[18:21], v[124:127], 0
	v_mfma_f32_16x16x32_bf16 v[20:23], v[22:25], v[128:131], v[6:9]
	v_mfma_f32_16x16x32_bf16 v[6:9], v[26:29], v[124:127], 0
	v_mfma_f32_16x16x32_bf16 v[216:219], v[30:33], v[128:131], v[6:9]
	s_barrier
; #define PG8_WAIT_V(n) asm volatile("s_waitcnt vmcnt(" #n ")" ::: "memory")
; template <class Epi, bool ALIGN_EPI, bool SP2, class Hook>
; __device__ __forceinline__ void gemm_phase(LAS unsigned char* lds, const Gemm g, const StaticOrder& S, const Epi& E, Acc& acc, const bool fresh, const Hook& H, const int wave_id) {
;     ...
;         if constexpr (SP2 && Epi::NSTORE > 0) {
;             const Src a1 = cA + kstep, a2 = cA + 2 * kstep, b2 = cB + 2 * kstep, a3 = a2 + kstep, b3 = b2 + kstep;
;             if constexpr (Epi::NSTORE == 16) PG8_TRIP_SP2(PG8_WAIT_V(24)); else PG8_TRIP_SP2(PG8_WAIT_V(16));
;             t0 = 2;
	s_setprio 0
	s_nop 4
	ds_read_b128 v[6:9], v152
	ds_read_b128 v[24:27], v152 offset:1024
	ds_read_b128 v[228:231], v152 offset:2048
	ds_read_b128 v[232:235], v152 offset:3072
	ds_read_b128 v[236:239], v153
	ds_read_b128 v[240:243], v153 offset:1024
	ds_read_b128 v[244:247], v153 offset:2048
	ds_read_b128 v[150:153], v153 offset:3072
	s_or_b32 s9, s68, 0x40100
	s_mov_b32 m0, s37
	ds_read_b128 v[10:13], v149 offset:32768
	ds_read_b128 v[14:17], v149 offset:33792
	ds_read_b128 v[32:35], v149 offset:34816
	ds_read_b128 v[194:197], v149 offset:35840
	ds_read_b128 v[208:211], v149 offset:36864
	ds_read_b128 v[200:203], v149 offset:37888
	ds_read_b128 v[204:207], v149 offset:38912
	ds_read_b128 v[220:223], v149 offset:39936
	buffer_load_dwordx4 v144, s[0:3], s9 offen lds
	s_mov_b32 m0, s38
	s_nop 0
	buffer_load_dwordx4 v146, s[0:3], s9 offen lds
	s_waitcnt vmcnt(8)
	s_waitcnt lgkmcnt(0)
	s_setprio 3
	s_barrier
	v_mfma_f32_16x16x32_bf16 v[28:31], v[6:9], v[10:13], v[66:69]
	v_mfma_f32_16x16x32_bf16 v[120:123], v[24:27], v[14:17], v[28:31]
	v_mfma_f32_16x16x32_bf16 v[28:31], v[228:231], v[10:13], v[70:73]
	v_mfma_f32_16x16x32_bf16 v[112:115], v[232:235], v[14:17], v[28:31]
	v_mfma_f32_16x16x32_bf16 v[28:31], v[6:9], v[32:35], v[74:77]
	v_mfma_f32_16x16x32_bf16 v[100:103], v[24:27], v[194:197], v[28:31]
	v_mfma_f32_16x16x32_bf16 v[28:31], v[228:231], v[32:35], v[78:81]
	v_mfma_f32_16x16x32_bf16 v[88:91], v[232:235], v[194:197], v[28:31]
	v_mfma_f32_16x16x32_bf16 v[28:31], v[6:9], v[208:211], v[82:85]
	v_mfma_f32_16x16x32_bf16 v[68:71], v[24:27], v[200:203], v[28:31]
	v_mfma_f32_16x16x32_bf16 v[28:31], v[228:231], v[208:211], v[92:95]
	v_mfma_f32_16x16x32_bf16 v[56:59], v[232:235], v[200:203], v[28:31]
	v_mfma_f32_16x16x32_bf16 v[28:31], v[6:9], v[204:207], v[96:99]
	v_mfma_f32_16x16x32_bf16 v[36:39], v[24:27], v[220:223], v[28:31]
	v_mfma_f32_16x16x32_bf16 v[28:31], v[228:231], v[204:207], v[104:107]
	v_mfma_f32_16x16x32_bf16 v[28:31], v[232:235], v[220:223], v[28:31]
	v_mfma_f32_16x16x32_bf16 v[64:67], v[236:239], v[10:13], v[108:111]
	v_mfma_f32_16x16x32_bf16 v[10:13], v[244:247], v[10:13], v[116:119]
	v_mfma_f32_16x16x32_bf16 v[124:127], v[150:153], v[14:17], v[10:13]
	v_mfma_f32_16x16x32_bf16 v[10:13], v[236:239], v[32:35], v[132:135]
	v_mfma_f32_16x16x32_bf16 v[116:119], v[240:243], v[194:197], v[10:13]
	v_mfma_f32_16x16x32_bf16 v[10:13], v[244:247], v[32:35], v[40:43]
	v_mfma_f32_16x16x32_bf16 v[108:111], v[150:153], v[194:197], v[10:13]
	v_mfma_f32_16x16x32_bf16 v[10:13], v[236:239], v[208:211], v[44:47]
	v_mfma_f32_16x16x32_bf16 v[92:95], v[240:243], v[200:203], v[10:13]
	v_mfma_f32_16x16x32_bf16 v[10:13], v[244:247], v[208:211], v[48:51]
	v_mfma_f32_16x16x32_bf16 v[80:83], v[150:153], v[200:203], v[10:13]
	v_mfma_f32_16x16x32_bf16 v[10:13], v[236:239], v[204:207], v[52:55]
	v_mfma_f32_16x16x32_bf16 v[128:131], v[240:243], v[14:17], v[64:67]
	v_mfma_f32_16x16x32_bf16 v[64:67], v[240:243], v[220:223], v[10:13]
	v_mfma_f32_16x16x32_bf16 v[10:13], v[244:247], v[204:207], v[60:63]
	v_mfma_f32_16x16x32_bf16 v[48:51], v[150:153], v[220:223], v[10:13]
	s_barrier
	s_setprio 0
	s_mov_b32 m0, s39
	s_or_b32 s9, s69, 0x180
	ds_read_b128 v[44:47], v149 offset:49152
	ds_read_b128 v[52:55], v149 offset:50176
	ds_read_b128 v[76:79], v149 offset:51200
	ds_read_b128 v[132:135], v149 offset:52224
	ds_read_b128 v[194:197], v149 offset:53248
	ds_read_b128 v[200:203], v149 offset:54272
	ds_read_b128 v[204:207], v149 offset:55296
	ds_read_b128 v[208:211], v149 offset:56320
	buffer_load_dwordx4 v145, s[4:7], s9 offen lds
	s_mov_b32 m0, s40
	s_nop 0
	buffer_load_dwordx4 v147, s[4:7], s9 offen lds
	s_or_b32 s9, s69, 0x40180
	s_mov_b32 m0, s43
	s_nop 0
	buffer_load_dwordx4 v145, s[4:7], s9 offen lds
	s_mov_b32 m0, s42
	s_nop 0
	buffer_load_dwordx4 v147, s[4:7], s9 offen lds
	s_mov_b32 m0, s41
	s_nop 0
	buffer_load_dwordx4 v144, s[0:3], s8 offen lds
	s_mov_b32 m0, s33
	s_nop 0
	buffer_load_dwordx4 v146, s[0:3], s8 offen lds
	s_waitcnt vmcnt(8)
	s_waitcnt lgkmcnt(0)
	s_setprio 3
	s_barrier
	v_mfma_f32_16x16x32_bf16 v[10:13], v[6:9], v[44:47], v[136:139]
	v_mfma_f32_16x16x32_bf16 v[72:75], v[24:27], v[52:55], v[10:13]
	v_mfma_f32_16x16x32_bf16 v[10:13], v[228:231], v[44:47], v[140:143]
	v_mfma_f32_16x16x32_bf16 v[60:63], v[232:235], v[52:55], v[10:13]
	v_mfma_f32_16x16x32_bf16 v[10:13], v[6:9], v[76:79], v[154:157]
	v_mfma_f32_16x16x32_bf16 v[40:43], v[24:27], v[132:135], v[10:13]
	v_mfma_f32_16x16x32_bf16 v[10:13], v[228:231], v[76:79], v[158:161]
	v_mfma_f32_16x16x32_bf16 v[32:35], v[232:235], v[132:135], v[10:13]
	v_mfma_f32_16x16x32_bf16 v[10:13], v[6:9], v[194:197], v[162:165]
	v_mfma_f32_16x16x32_bf16 v[16:19], v[24:27], v[200:203], v[10:13]
	v_mfma_f32_16x16x32_bf16 v[10:13], v[228:231], v[194:197], v[166:169]
	v_mfma_f32_16x16x32_bf16 v[2:5], v[6:9], v[204:207], v[2:5]
	v_mfma_f32_16x16x32_bf16 v[12:15], v[232:235], v[200:203], v[10:13]
	v_mfma_f32_16x16x32_bf16 v[8:11], v[24:27], v[208:211], v[2:5]
	v_mfma_f32_16x16x32_bf16 v[2:5], v[228:231], v[204:207], v[170:173]
	v_mfma_f32_16x16x32_bf16 v[4:7], v[232:235], v[208:211], v[2:5]
	v_mfma_f32_16x16x32_bf16 v[24:27], v[236:239], v[44:47], v[174:177]
	v_mfma_f32_16x16x32_bf16 v[96:99], v[240:243], v[52:55], v[24:27]
	v_mfma_f32_16x16x32_bf16 v[24:27], v[244:247], v[44:47], v[178:181]
	v_mfma_f32_16x16x32_bf16 v[104:107], v[150:153], v[52:55], v[24:27]
	v_mfma_f32_16x16x32_bf16 v[24:27], v[236:239], v[76:79], v[182:185]
	v_mfma_f32_16x16x32_bf16 v[84:87], v[240:243], v[132:135], v[24:27]
	v_mfma_f32_16x16x32_bf16 v[24:27], v[244:247], v[76:79], v[186:189]
	v_mfma_f32_16x16x32_bf16 v[76:79], v[150:153], v[132:135], v[24:27]
	v_mfma_f32_16x16x32_bf16 v[24:27], v[236:239], v[194:197], v[190:193]
	v_mfma_f32_16x16x32_bf16 v[52:55], v[240:243], v[200:203], v[24:27]
	v_mfma_f32_16x16x32_bf16 v[24:27], v[244:247], v[194:197], v[212:215]
	v_mfma_f32_16x16x32_bf16 v[20:23], v[236:239], v[204:207], v[20:23]
	v_mfma_f32_16x16x32_bf16 v[44:47], v[150:153], v[200:203], v[24:27]
	v_mfma_f32_16x16x32_bf16 v[24:27], v[240:243], v[208:211], v[20:23]
	v_mfma_f32_16x16x32_bf16 v[20:23], v[244:247], v[204:207], v[216:219]
	v_mfma_f32_16x16x32_bf16 v[20:23], v[150:153], v[208:211], v[20:23]
	s_barrier
	s_setprio 0
	s_mov_b64 s[8:9], 0
	v_mov_b64_e32 v[234:235], v[198:199]
	v_mov_b64_e32 v[236:237], v[226:227]
	v_mov_b32_e32 v198, v0
	v_mov_b32_e32 v226, v225
	v_mov_b64_e32 v[244:245], 0x100
	v_mov_b64_e32 v[246:247], 0xff

; #define PG8_WAIT_V(n) asm volatile("s_waitcnt vmcnt(" #n ")" ::: "memory")
; template <class Epi, bool ALIGN_EPI, bool SP2, class Hook>
; __device__ __forceinline__ void gemm_phase(LAS unsigned char* lds, const Gemm g, const StaticOrder& S, const Epi& E, Acc& acc, const bool fresh, const Hook& H, const int wave_id) {
;     ...
;         for (int t = t0; t < nt; t += 2) {
;             const bool last = (t == nt - 2);
;             const Src a1 = cA + (size_t)(t + 1) * kstep;
;             const Src a2 = last ? nA : cA + (size_t)(t + 2) * kstep, b2 = last ? nB : cB + (size_t)(t + 2) * kstep;
;             const Src a3 = a2 + kstep, b3 = b2 + kstep;
;             if (last && has_next) H(nxt);
;             if constexpr (SP2) {
;             PG8_TRIP_SP2(PG8_WAIT_V(8));
.LBB0_391:
	v_add_u32_e32 v150, 0x10000, v148
	v_add_u32_e32 v151, 0x14000, v148
	ds_read_b128 v[132:135], v150
	ds_read_b128 v[136:139], v150 offset:1024
	ds_read_b128 v[140:143], v150 offset:2048
	ds_read_b128 v[152:155], v150 offset:3072
	ds_read_b128 v[156:159], v151
	ds_read_b128 v[160:163], v151 offset:1024
	ds_read_b128 v[164:167], v151 offset:2048
	ds_read_b128 v[168:171], v151 offset:3072
	s_add_i32 s12, s56, 0xfffc0080
	s_cmp_eq_u32 s29, 12
	s_cselect_b32 s60, s68, s12
	s_cselect_b32 s13, s5, s77
	s_cselect_b32 s12, s4, s76
	s_cselect_b32 s15, s7, s55
	s_cselect_b32 s14, s6, s54
	s_cselect_b32 s58, s69, s57
	s_cselect_b32 s16, s0, s8
	s_cselect_b32 s17, s1, s9
	s_cselect_b32 s18, s2, s10
	s_cselect_b32 s19, s3, s11
	s_or_b32 s59, s60, 0x80
	s_mov_b32 m0, s45
	ds_read_b128 v[172:175], v149
	ds_read_b128 v[176:179], v149 offset:1024
	ds_read_b128 v[180:183], v149 offset:2048
	ds_read_b128 v[184:187], v149 offset:3072
	ds_read_b128 v[188:191], v149 offset:4096
	ds_read_b128 v[212:215], v149 offset:5120
	ds_read_b128 v[216:219], v149 offset:6144
	ds_read_b128 v[228:231], v149 offset:7168
	buffer_load_dwordx4 v144, s[8:11], s56 offen lds
	s_mov_b32 m0, s46
	s_nop 0
	buffer_load_dwordx4 v146, s[8:11], s56 offen lds
	s_waitcnt vmcnt(8)
	s_waitcnt lgkmcnt(0)
	s_setprio 3
	s_barrier
	v_mfma_f32_16x16x32_bf16 v[120:123], v[132:135], v[172:175], v[120:123]
	v_mfma_f32_16x16x32_bf16 v[112:115], v[140:143], v[172:175], v[112:115]
	v_mfma_f32_16x16x32_bf16 v[100:103], v[132:135], v[180:183], v[100:103]
	v_mfma_f32_16x16x32_bf16 v[88:91], v[140:143], v[180:183], v[88:91]
	v_mfma_f32_16x16x32_bf16 v[68:71], v[132:135], v[188:191], v[68:71]
	v_mfma_f32_16x16x32_bf16 v[56:59], v[140:143], v[188:191], v[56:59]
	v_mfma_f32_16x16x32_bf16 v[36:39], v[132:135], v[216:219], v[36:39]
	v_mfma_f32_16x16x32_bf16 v[28:31], v[140:143], v[216:219], v[28:31]
	v_mfma_f32_16x16x32_bf16 v[120:123], v[136:139], v[176:179], v[120:123]
	v_mfma_f32_16x16x32_bf16 v[112:115], v[152:155], v[176:179], v[112:115]
	v_mfma_f32_16x16x32_bf16 v[100:103], v[136:139], v[184:187], v[100:103]
	v_mfma_f32_16x16x32_bf16 v[88:91], v[152:155], v[184:187], v[88:91]
	v_mfma_f32_16x16x32_bf16 v[68:71], v[136:139], v[212:215], v[68:71]
	v_mfma_f32_16x16x32_bf16 v[56:59], v[152:155], v[212:215], v[56:59]
	v_mfma_f32_16x16x32_bf16 v[36:39], v[136:139], v[228:231], v[36:39]
	v_mfma_f32_16x16x32_bf16 v[28:31], v[152:155], v[228:231], v[28:31]
	v_mfma_f32_16x16x32_bf16 v[128:131], v[156:159], v[172:175], v[128:131]
	v_mfma_f32_16x16x32_bf16 v[124:127], v[164:167], v[172:175], v[124:127]
	v_mfma_f32_16x16x32_bf16 v[116:119], v[156:159], v[180:183], v[116:119]
	v_mfma_f32_16x16x32_bf16 v[108:111], v[164:167], v[180:183], v[108:111]
	v_mfma_f32_16x16x32_bf16 v[92:95], v[156:159], v[188:191], v[92:95]
	v_mfma_f32_16x16x32_bf16 v[80:83], v[164:167], v[188:191], v[80:83]
	v_mfma_f32_16x16x32_bf16 v[64:67], v[156:159], v[216:219], v[64:67]
	v_mfma_f32_16x16x32_bf16 v[48:51], v[164:167], v[216:219], v[48:51]
	v_mfma_f32_16x16x32_bf16 v[128:131], v[160:163], v[176:179], v[128:131]
	v_mfma_f32_16x16x32_bf16 v[124:127], v[168:171], v[176:179], v[124:127]
	v_mfma_f32_16x16x32_bf16 v[116:119], v[160:163], v[184:187], v[116:119]
	v_mfma_f32_16x16x32_bf16 v[108:111], v[168:171], v[184:187], v[108:111]
	v_mfma_f32_16x16x32_bf16 v[92:95], v[160:163], v[212:215], v[92:95]
	v_mfma_f32_16x16x32_bf16 v[80:83], v[168:171], v[212:215], v[80:83]
	v_mfma_f32_16x16x32_bf16 v[64:67], v[160:163], v[228:231], v[64:67]
	v_mfma_f32_16x16x32_bf16 v[48:51], v[168:171], v[228:231], v[48:51]
	s_barrier
	s_setprio 0
	s_mov_b32 m0, s92
	ds_read_b128 v[172:175], v149 offset:16384
	ds_read_b128 v[176:179], v149 offset:17408
	ds_read_b128 v[180:183], v149 offset:18432
	ds_read_b128 v[184:187], v149 offset:19456
	ds_read_b128 v[188:191], v149 offset:20480
	ds_read_b128 v[212:215], v149 offset:21504
	ds_read_b128 v[216:219], v149 offset:22528
	ds_read_b128 v[228:231], v149 offset:23552
	buffer_load_dwordx4 v145, s[12:15], s58 offen lds
	s_mov_b32 m0, s93
	s_add_i32 s61, s58, 0x40000
	buffer_load_dwordx4 v147, s[12:15], s58 offen lds
	s_mov_b32 m0, s94
	s_nop 0
	buffer_load_dwordx4 v145, s[12:15], s61 offen lds
	s_mov_b32 m0, s95
	s_nop 0
	buffer_load_dwordx4 v147, s[12:15], s61 offen lds
	s_mov_b32 m0, s44
	s_nop 0
	buffer_load_dwordx4 v144, s[16:19], s60 offen lds
	s_mov_b32 m0, s36
	s_nop 0
	buffer_load_dwordx4 v146, s[16:19], s60 offen lds
	s_waitcnt vmcnt(8)
	s_waitcnt lgkmcnt(0)
	s_setprio 3
	s_barrier
	v_mfma_f32_16x16x32_bf16 v[72:75], v[132:135], v[172:175], v[72:75]
	v_mfma_f32_16x16x32_bf16 v[60:63], v[140:143], v[172:175], v[60:63]
	v_mfma_f32_16x16x32_bf16 v[40:43], v[132:135], v[180:183], v[40:43]
	v_mfma_f32_16x16x32_bf16 v[32:35], v[140:143], v[180:183], v[32:35]
	v_mfma_f32_16x16x32_bf16 v[16:19], v[132:135], v[188:191], v[16:19]
	v_mfma_f32_16x16x32_bf16 v[12:15], v[140:143], v[188:191], v[12:15]
	v_mfma_f32_16x16x32_bf16 v[8:11], v[132:135], v[216:219], v[8:11]
	v_mfma_f32_16x16x32_bf16 v[2:5], v[140:143], v[216:219], v[4:7]
	v_mfma_f32_16x16x32_bf16 v[72:75], v[136:139], v[176:179], v[72:75]
	v_mfma_f32_16x16x32_bf16 v[60:63], v[152:155], v[176:179], v[60:63]
	v_mfma_f32_16x16x32_bf16 v[40:43], v[136:139], v[184:187], v[40:43]
	v_mfma_f32_16x16x32_bf16 v[32:35], v[152:155], v[184:187], v[32:35]
	v_mfma_f32_16x16x32_bf16 v[16:19], v[136:139], v[212:215], v[16:19]
	v_mfma_f32_16x16x32_bf16 v[12:15], v[152:155], v[212:215], v[12:15]
	v_mfma_f32_16x16x32_bf16 v[8:11], v[136:139], v[228:231], v[8:11]
	v_mfma_f32_16x16x32_bf16 v[2:5], v[152:155], v[228:231], v[2:5]
	v_mfma_f32_16x16x32_bf16 v[96:99], v[156:159], v[172:175], v[96:99]
	v_mfma_f32_16x16x32_bf16 v[104:107], v[164:167], v[172:175], v[104:107]
	v_mfma_f32_16x16x32_bf16 v[84:87], v[156:159], v[180:183], v[84:87]
	v_mfma_f32_16x16x32_bf16 v[76:79], v[164:167], v[180:183], v[76:79]
	v_mfma_f32_16x16x32_bf16 v[52:55], v[156:159], v[188:191], v[52:55]
	v_mfma_f32_16x16x32_bf16 v[44:47], v[164:167], v[188:191], v[44:47]
	v_mfma_f32_16x16x32_bf16 v[24:27], v[156:159], v[216:219], v[24:27]
	v_mfma_f32_16x16x32_bf16 v[20:23], v[164:167], v[216:219], v[20:23]
	v_mfma_f32_16x16x32_bf16 v[96:99], v[160:163], v[176:179], v[96:99]
	v_mfma_f32_16x16x32_bf16 v[104:107], v[168:171], v[176:179], v[104:107]
	v_mfma_f32_16x16x32_bf16 v[84:87], v[160:163], v[184:187], v[84:87]
	v_mfma_f32_16x16x32_bf16 v[76:79], v[168:171], v[184:187], v[76:79]
	v_mfma_f32_16x16x32_bf16 v[52:55], v[160:163], v[212:215], v[52:55]
	v_mfma_f32_16x16x32_bf16 v[44:47], v[168:171], v[212:215], v[44:47]
	v_mfma_f32_16x16x32_bf16 v[24:27], v[160:163], v[228:231], v[24:27]
	v_mfma_f32_16x16x32_bf16 v[20:23], v[168:171], v[228:231], v[20:23]
	s_barrier
; #define PG8_STAGE(bufoff, gbase, voff) do { const Src _g = (gbase); _Pragma("unroll") for (int _i = 0; _i < 2; ++_i) \
;         __builtin_amdgcn_raw_ptr_buffer_load_lds(_g.r, (LAS unsigned*)(lds + (bufoff) + ldsw + _i * 8192), 16, (voff)[_i], _g.o, 0, 0); } while (0)
; #define PG8_WAIT_V(n) asm volatile("s_waitcnt vmcnt(" #n ")" ::: "memory")
; template <class Epi, bool ALIGN_EPI, bool SP2, class Hook>
; __device__ __forceinline__ void gemm_phase(LAS unsigned char* lds, const Gemm g, const StaticOrder& S, const Epi& E, Acc& acc, const bool fresh, const Hook& H, const int wave_id) {
;     ...
;         for (int t = t0; t < nt; t += 2) {
;             const bool last = (t == nt - 2);
;             const Src a1 = cA + (size_t)(t + 1) * kstep;
;             const Src a2 = last ? nA : cA + (size_t)(t + 2) * kstep, b2 = last ? nB : cB + (size_t)(t + 2) * kstep;
;             const Src a3 = a2 + kstep, b3 = b2 + kstep;
;             if (last && has_next) H(nxt);
;             if constexpr (SP2) {
;             PG8_TRIP_SP2(PG8_WAIT_V(8));
;             } else {
;             PG8_LDB(B0, 0, 0); PG8_SCHED; PG8_LDA(At, 0, 0); PG8_STAGE(PG8_SA(1, 1), a1 + hstepA, voffA);
;             PG8_WAIT_L(8); PG8_BAR; PG8_WAIT_L(0); PG8_MMA(0, 0, At, B0); PG8_BAR; PG8_SCHED;
;             PG8_LDB(B1, 0, 1); PG8_STAGE(PG8_SB(0, 0), b2, voffB);
;             PG8_BAR; PG8_WAIT_L(0); PG8_MMA(0, 1, At, B1); PG8_BAR;
;             PG8_LDA(At, 0, 1); PG8_STAGE(PG8_SA(0, 0), a2, voffA);
;             PG8_BAR; PG8_WAIT_L(0); PG8_MMA(1, 0, At, B0); PG8_BAR; PG8_SCHED;
;             PG8_STAGE(PG8_SB(0, 1), b2 + hstep, voffB);
;             PG8_WAIT_V(6); PG8_BAR; PG8_MMA(1, 1, At, B1); PG8_BAR;
;             PG8_LDB(B0, 1, 0); PG8_SCHED; PG8_LDA(At, 1, 0); PG8_STAGE(PG8_SA(0, 1), a2 + hstepA, voffA);
;             PG8_WAIT_L(8); PG8_BAR; PG8_WAIT_L(0); PG8_MMA(0, 0, At, B0); PG8_BAR; PG8_SCHED;
;             PG8_LDB(B1, 1, 1); PG8_STAGE(PG8_SB(1, 0), b3, voffB);
;             PG8_BAR; PG8_WAIT_L(0); PG8_MMA(0, 1, At, B1); PG8_BAR;
;             PG8_LDA(At, 1, 1); PG8_STAGE(PG8_SA(1, 0), a3, voffA);
;             PG8_BAR; PG8_WAIT_L(0); PG8_MMA(1, 0, At, B0); PG8_BAR; PG8_SCHED;
;             PG8_STAGE(PG8_SB(1, 1), b3 + hstep, voffB);
;             PG8_WAIT_V(6); PG8_BAR; PG8_MMA(1, 1, At, B1); PG8_BAR;
;             }
;         }
;         if constexpr (ALIGN_EPI) { if (wr == 0) PG8_BAR; }
	s_setprio 0
	v_add_u32_e32 v152, 0x18000, v148
	v_add_u32_e32 v153, 0x1c000, v148
	ds_read_b128 v[132:135], v152
	ds_read_b128 v[136:139], v152 offset:1024
	ds_read_b128 v[140:143], v152 offset:2048
	ds_read_b128 v[154:157], v152 offset:3072
	ds_read_b128 v[158:161], v153
	ds_read_b128 v[162:165], v153 offset:1024
	ds_read_b128 v[166:169], v153 offset:2048
	ds_read_b128 v[170:173], v153 offset:3072
	s_add_i32 s60, s60, 0x40000
	s_mov_b32 m0, s37
	ds_read_b128 v[174:177], v149 offset:32768
	ds_read_b128 v[178:181], v149 offset:33792
	ds_read_b128 v[182:185], v149 offset:34816
	ds_read_b128 v[186:189], v149 offset:35840
	ds_read_b128 v[190:193], v149 offset:36864
	ds_read_b128 v[212:215], v149 offset:37888
	ds_read_b128 v[216:219], v149 offset:38912
	ds_read_b128 v[228:231], v149 offset:39936
	buffer_load_dwordx4 v144, s[16:19], s60 offen lds
	s_mov_b32 m0, s38
	s_nop 0
	buffer_load_dwordx4 v146, s[16:19], s60 offen lds
	s_waitcnt vmcnt(8)
	s_waitcnt lgkmcnt(0)
	s_setprio 3
	s_barrier
	v_mfma_f32_16x16x32_bf16 v[120:123], v[132:135], v[174:177], v[120:123]
	v_mfma_f32_16x16x32_bf16 v[112:115], v[140:143], v[174:177], v[112:115]
	v_mfma_f32_16x16x32_bf16 v[100:103], v[132:135], v[182:185], v[100:103]
	v_mfma_f32_16x16x32_bf16 v[88:91], v[140:143], v[182:185], v[88:91]
	v_mfma_f32_16x16x32_bf16 v[68:71], v[132:135], v[190:193], v[68:71]
	v_mfma_f32_16x16x32_bf16 v[56:59], v[140:143], v[190:193], v[56:59]
	v_mfma_f32_16x16x32_bf16 v[36:39], v[132:135], v[216:219], v[36:39]
	v_mfma_f32_16x16x32_bf16 v[28:31], v[140:143], v[216:219], v[28:31]
	v_mfma_f32_16x16x32_bf16 v[120:123], v[136:139], v[178:181], v[120:123]
	v_mfma_f32_16x16x32_bf16 v[112:115], v[154:157], v[178:181], v[112:115]
	v_mfma_f32_16x16x32_bf16 v[100:103], v[136:139], v[186:189], v[100:103]
	v_mfma_f32_16x16x32_bf16 v[88:91], v[154:157], v[186:189], v[88:91]
	v_mfma_f32_16x16x32_bf16 v[68:71], v[136:139], v[212:215], v[68:71]
	v_mfma_f32_16x16x32_bf16 v[56:59], v[154:157], v[212:215], v[56:59]
	v_mfma_f32_16x16x32_bf16 v[36:39], v[136:139], v[228:231], v[36:39]
	v_mfma_f32_16x16x32_bf16 v[28:31], v[154:157], v[228:231], v[28:31]
	v_mfma_f32_16x16x32_bf16 v[128:131], v[158:161], v[174:177], v[128:131]
	v_mfma_f32_16x16x32_bf16 v[124:127], v[166:169], v[174:177], v[124:127]
	v_mfma_f32_16x16x32_bf16 v[116:119], v[158:161], v[182:185], v[116:119]
	v_mfma_f32_16x16x32_bf16 v[108:111], v[166:169], v[182:185], v[108:111]
	v_mfma_f32_16x16x32_bf16 v[92:95], v[158:161], v[190:193], v[92:95]
	v_mfma_f32_16x16x32_bf16 v[80:83], v[166:169], v[190:193], v[80:83]
	v_mfma_f32_16x16x32_bf16 v[64:67], v[158:161], v[216:219], v[64:67]
	v_mfma_f32_16x16x32_bf16 v[48:51], v[166:169], v[216:219], v[48:51]
	v_mfma_f32_16x16x32_bf16 v[128:131], v[162:165], v[178:181], v[128:131]
	v_mfma_f32_16x16x32_bf16 v[124:127], v[170:173], v[178:181], v[124:127]
	v_mfma_f32_16x16x32_bf16 v[116:119], v[162:165], v[186:189], v[116:119]
	v_mfma_f32_16x16x32_bf16 v[108:111], v[170:173], v[186:189], v[108:111]
	v_mfma_f32_16x16x32_bf16 v[92:95], v[162:165], v[212:215], v[92:95]
	v_mfma_f32_16x16x32_bf16 v[80:83], v[170:173], v[212:215], v[80:83]
	v_mfma_f32_16x16x32_bf16 v[64:67], v[162:165], v[228:231], v[64:67]
	v_mfma_f32_16x16x32_bf16 v[48:51], v[170:173], v[228:231], v[48:51]
	s_barrier
	s_setprio 0
	s_mov_b32 m0, s39
	s_or_b32 s60, s58, 0x80
	ds_read_b128 v[174:177], v149 offset:49152
	ds_read_b128 v[178:181], v149 offset:50176
	ds_read_b128 v[182:185], v149 offset:51200
	ds_read_b128 v[186:189], v149 offset:52224
	ds_read_b128 v[190:193], v149 offset:53248
	ds_read_b128 v[212:215], v149 offset:54272
	ds_read_b128 v[216:219], v149 offset:55296
	ds_read_b128 v[228:231], v149 offset:56320
	buffer_load_dwordx4 v145, s[12:15], s60 offen lds
	s_mov_b32 m0, s40
	s_add_i32 s58, s58, 0x40080
	buffer_load_dwordx4 v147, s[12:15], s60 offen lds
	s_mov_b32 m0, s43
	s_nop 0
	buffer_load_dwordx4 v145, s[12:15], s58 offen lds
	s_mov_b32 m0, s42
	s_nop 0
	buffer_load_dwordx4 v147, s[12:15], s58 offen lds
	s_mov_b32 m0, s41
	s_nop 0
	buffer_load_dwordx4 v144, s[16:19], s59 offen lds
	s_mov_b32 m0, s33
	s_nop 0
	buffer_load_dwordx4 v146, s[16:19], s59 offen lds
	s_waitcnt vmcnt(8)
	s_waitcnt lgkmcnt(0)
	s_setprio 3
	s_barrier
	v_mfma_f32_16x16x32_bf16 v[72:75], v[132:135], v[174:177], v[72:75]
	v_mfma_f32_16x16x32_bf16 v[60:63], v[140:143], v[174:177], v[60:63]
	v_mfma_f32_16x16x32_bf16 v[40:43], v[132:135], v[182:185], v[40:43]
	v_mfma_f32_16x16x32_bf16 v[32:35], v[140:143], v[182:185], v[32:35]
	v_mfma_f32_16x16x32_bf16 v[16:19], v[132:135], v[190:193], v[16:19]
	v_mfma_f32_16x16x32_bf16 v[12:15], v[140:143], v[190:193], v[12:15]
	v_mfma_f32_16x16x32_bf16 v[6:9], v[132:135], v[216:219], v[8:11]
	v_mfma_f32_16x16x32_bf16 v[2:5], v[140:143], v[216:219], v[2:5]
	v_mfma_f32_16x16x32_bf16 v[72:75], v[136:139], v[178:181], v[72:75]
	v_mfma_f32_16x16x32_bf16 v[60:63], v[154:157], v[178:181], v[60:63]
	v_mfma_f32_16x16x32_bf16 v[40:43], v[136:139], v[186:189], v[40:43]
	v_mfma_f32_16x16x32_bf16 v[32:35], v[154:157], v[186:189], v[32:35]
	v_mfma_f32_16x16x32_bf16 v[16:19], v[136:139], v[212:215], v[16:19]
	v_mfma_f32_16x16x32_bf16 v[12:15], v[154:157], v[212:215], v[12:15]
	v_mfma_f32_16x16x32_bf16 v[8:11], v[136:139], v[228:231], v[6:9]
	v_mfma_f32_16x16x32_bf16 v[4:7], v[154:157], v[228:231], v[2:5]
	v_mfma_f32_16x16x32_bf16 v[96:99], v[158:161], v[174:177], v[96:99]
	v_mfma_f32_16x16x32_bf16 v[104:107], v[166:169], v[174:177], v[104:107]
	v_mfma_f32_16x16x32_bf16 v[84:87], v[158:161], v[182:185], v[84:87]
	v_mfma_f32_16x16x32_bf16 v[76:79], v[166:169], v[182:185], v[76:79]
	v_mfma_f32_16x16x32_bf16 v[52:55], v[158:161], v[190:193], v[52:55]
	v_mfma_f32_16x16x32_bf16 v[44:47], v[166:169], v[190:193], v[44:47]
	v_mfma_f32_16x16x32_bf16 v[24:27], v[158:161], v[216:219], v[24:27]
	v_mfma_f32_16x16x32_bf16 v[20:23], v[166:169], v[216:219], v[20:23]
	v_mfma_f32_16x16x32_bf16 v[96:99], v[162:165], v[178:181], v[96:99]
	v_mfma_f32_16x16x32_bf16 v[104:107], v[170:173], v[178:181], v[104:107]
	v_mfma_f32_16x16x32_bf16 v[84:87], v[162:165], v[186:189], v[84:87]
	v_mfma_f32_16x16x32_bf16 v[76:79], v[170:173], v[186:189], v[76:79]
	v_mfma_f32_16x16x32_bf16 v[52:55], v[162:165], v[212:215], v[52:55]
	v_mfma_f32_16x16x32_bf16 v[44:47], v[170:173], v[212:215], v[44:47]
	v_mfma_f32_16x16x32_bf16 v[24:27], v[162:165], v[228:231], v[24:27]
	v_mfma_f32_16x16x32_bf16 v[20:23], v[170:173], v[228:231], v[20:23]
	s_barrier
	s_setprio 0
	s_add_i32 s29, s29, 2
	s_addk_i32 s56, 0x100
	s_addk_i32 s57, 0x100
	s_cmp_gt_u32 s29, 13
	s_cbranch_scc0 .LBB0_391
	v_readlane_b32 s8, v251, 45
	v_readlane_b32 s9, v251, 46
	s_and_b64 vcc, exec, s[8:9]
	s_cbranch_vccz .LBB0_394
	s_barrier

; #define PG8_WAIT_V(n) asm volatile("s_waitcnt vmcnt(" #n ")" ::: "memory")
; template <class Epi, bool ALIGN_EPI, bool SP2, class Hook>
; __device__ __forceinline__ void gemm_phase(LAS unsigned char* lds, const Gemm g, const StaticOrder& S, const Epi& E, Acc& acc, const bool fresh, const Hook& H, const int wave_id) {
;     ...
;         for (int t = t0; t < nt; t += 2) {
;             const bool last = (t == nt - 2);
;             const Src a1 = cA + (size_t)(t + 1) * kstep;
;             const Src a2 = last ? nA : cA + (size_t)(t + 2) * kstep, b2 = last ? nB : cB + (size_t)(t + 2) * kstep;
;             const Src a3 = a2 + kstep, b3 = b2 + kstep;
;             if (last && has_next) H(nxt);
;             if constexpr (SP2) {
;             PG8_TRIP_SP2(PG8_WAIT_V(8));
.LBB0_702:
	v_add_u32_e32 v70, 0x10000, v216
	v_add_u32_e32 v118, 0x14000, v216
	ds_read_b128 v[34:37], v70
	ds_read_b128 v[46:49], v70 offset:1024
	ds_read_b128 v[58:61], v70 offset:2048
	ds_read_b128 v[70:73], v70 offset:3072
	ds_read_b128 v[82:85], v118
	ds_read_b128 v[94:97], v118 offset:1024
	ds_read_b128 v[106:109], v118 offset:2048
	ds_read_b128 v[118:121], v118 offset:3072
	s_add_i32 s12, s55, 0xfffe0080
	s_cmp_eq_u32 s57, 4
	s_cselect_b32 s60, s53, s12
	s_cselect_b32 s13, s29, s77
	s_cselect_b32 s12, s28, s76
	s_cselect_b32 s15, s31, s35
	s_cselect_b32 s14, s30, s34
	s_cselect_b32 s58, s54, s56
	s_cselect_b32 s16, s2, s8
	s_cselect_b32 s17, s3, s9
	s_cselect_b32 s18, s26, s10
	s_cselect_b32 s19, s27, s11
	s_or_b32 s59, s60, 0x80
	s_mov_b32 m0, s45
	s_waitcnt vmcnt(14)
	ds_read_b128 v[130:133], v217
	ds_read_b128 v[142:145], v217 offset:1024
	ds_read_b128 v[154:157], v217 offset:2048
	ds_read_b128 v[166:169], v217 offset:3072
	ds_read_b128 v[174:177], v217 offset:4096
	ds_read_b128 v[182:185], v217 offset:5120
	ds_read_b128 v[186:189], v217 offset:6144
	ds_read_b128 v[190:193], v217 offset:7168
	buffer_load_dwordx4 v0, s[8:11], s55 offen lds
	s_mov_b32 m0, s46
	s_nop 0
	buffer_load_dwordx4 v214, s[8:11], s55 offen lds
	s_waitcnt vmcnt(8)
	s_waitcnt lgkmcnt(0)
	s_setprio 3
	s_barrier
	v_mfma_f32_16x16x32_bf16 v[178:181], v[34:37], v[130:133], v[178:181]
	v_mfma_f32_16x16x32_bf16 v[170:173], v[58:61], v[130:133], v[170:173]
	v_mfma_f32_16x16x32_bf16 v[150:153], v[34:37], v[154:157], v[150:153]
	v_mfma_f32_16x16x32_bf16 v[146:149], v[58:61], v[154:157], v[146:149]
	v_mfma_f32_16x16x32_bf16 v[126:129], v[34:37], v[174:177], v[126:129]
	v_mfma_f32_16x16x32_bf16 v[122:125], v[58:61], v[174:177], v[122:125]
	v_mfma_f32_16x16x32_bf16 v[102:105], v[34:37], v[186:189], v[102:105]
	v_mfma_f32_16x16x32_bf16 v[98:101], v[58:61], v[186:189], v[98:101]
	v_mfma_f32_16x16x32_bf16 v[178:181], v[46:49], v[142:145], v[178:181]
	v_mfma_f32_16x16x32_bf16 v[170:173], v[70:73], v[142:145], v[170:173]
	v_mfma_f32_16x16x32_bf16 v[150:153], v[46:49], v[166:169], v[150:153]
	v_mfma_f32_16x16x32_bf16 v[146:149], v[70:73], v[166:169], v[146:149]
	v_mfma_f32_16x16x32_bf16 v[126:129], v[46:49], v[182:185], v[126:129]
	v_mfma_f32_16x16x32_bf16 v[122:125], v[70:73], v[182:185], v[122:125]
	v_mfma_f32_16x16x32_bf16 v[102:105], v[46:49], v[190:193], v[102:105]
	v_mfma_f32_16x16x32_bf16 v[98:101], v[70:73], v[190:193], v[98:101]
	v_mfma_f32_16x16x32_bf16 v[162:165], v[82:85], v[130:133], v[162:165]
	v_mfma_f32_16x16x32_bf16 v[138:141], v[82:85], v[154:157], v[138:141]
	v_mfma_f32_16x16x32_bf16 v[134:137], v[106:109], v[154:157], v[134:137]
	v_mfma_f32_16x16x32_bf16 v[114:117], v[82:85], v[174:177], v[114:117]
	v_mfma_f32_16x16x32_bf16 v[110:113], v[106:109], v[174:177], v[110:113]
	v_mfma_f32_16x16x32_bf16 v[90:93], v[82:85], v[186:189], v[90:93]
	v_mfma_f32_16x16x32_bf16 v[86:89], v[106:109], v[186:189], v[86:89]
	v_mfma_f32_16x16x32_bf16 v[162:165], v[94:97], v[142:145], v[162:165]
	v_mfma_f32_16x16x32_bf16 v[130:133], v[106:109], v[130:133], v[158:161]
	v_mfma_f32_16x16x32_bf16 v[138:141], v[94:97], v[166:169], v[138:141]
	v_mfma_f32_16x16x32_bf16 v[134:137], v[118:121], v[166:169], v[134:137]
	v_mfma_f32_16x16x32_bf16 v[114:117], v[94:97], v[182:185], v[114:117]
	v_mfma_f32_16x16x32_bf16 v[110:113], v[118:121], v[182:185], v[110:113]
	v_mfma_f32_16x16x32_bf16 v[90:93], v[94:97], v[190:193], v[90:93]
	v_mfma_f32_16x16x32_bf16 v[86:89], v[118:121], v[190:193], v[86:89]
	v_mfma_f32_16x16x32_bf16 v[130:133], v[118:121], v[142:145], v[130:133]
	s_barrier
	s_setprio 0
	s_mov_b32 m0, s92
	ds_read_b128 v[142:145], v217 offset:16384
	ds_read_b128 v[154:157], v217 offset:17408
	ds_read_b128 v[158:161], v217 offset:18432
	ds_read_b128 v[166:169], v217 offset:19456
	ds_read_b128 v[174:177], v217 offset:20480
	ds_read_b128 v[182:185], v217 offset:21504
	ds_read_b128 v[186:189], v217 offset:22528
	ds_read_b128 v[190:193], v217 offset:23552
	buffer_load_dwordx4 v199, s[12:15], s58 offen lds
	s_mov_b32 m0, s93
	s_add_i32 s61, s58, 0x20000
	buffer_load_dwordx4 v215, s[12:15], s58 offen lds
	s_mov_b32 m0, s94
	s_nop 0
	buffer_load_dwordx4 v199, s[12:15], s61 offen lds
	s_mov_b32 m0, s95
	s_nop 0
	buffer_load_dwordx4 v215, s[12:15], s61 offen lds
	s_mov_b32 m0, s44
	s_nop 0
	buffer_load_dwordx4 v0, s[16:19], s60 offen lds
	s_mov_b32 m0, s36
	s_nop 0
	buffer_load_dwordx4 v214, s[16:19], s60 offen lds
	s_waitcnt vmcnt(8)
	s_waitcnt lgkmcnt(0)
	s_setprio 3
	s_barrier
	v_mfma_f32_16x16x32_bf16 v[78:81], v[34:37], v[142:145], v[78:81]
	v_mfma_f32_16x16x32_bf16 v[74:77], v[58:61], v[142:145], v[74:77]
	v_mfma_f32_16x16x32_bf16 v[54:57], v[34:37], v[158:161], v[54:57]
	v_mfma_f32_16x16x32_bf16 v[50:53], v[58:61], v[158:161], v[50:53]
	v_mfma_f32_16x16x32_bf16 v[30:33], v[34:37], v[174:177], v[30:33]
	v_mfma_f32_16x16x32_bf16 v[26:29], v[58:61], v[174:177], v[26:29]
	v_mfma_f32_16x16x32_bf16 v[14:17], v[34:37], v[186:189], v[14:17]
	v_mfma_f32_16x16x32_bf16 v[10:13], v[58:61], v[186:189], v[10:13]
	v_mfma_f32_16x16x32_bf16 v[78:81], v[46:49], v[154:157], v[78:81]
	v_mfma_f32_16x16x32_bf16 v[74:77], v[70:73], v[154:157], v[74:77]
	v_mfma_f32_16x16x32_bf16 v[54:57], v[46:49], v[166:169], v[54:57]
	v_mfma_f32_16x16x32_bf16 v[50:53], v[70:73], v[166:169], v[50:53]
	v_mfma_f32_16x16x32_bf16 v[30:33], v[46:49], v[182:185], v[30:33]
	v_mfma_f32_16x16x32_bf16 v[26:29], v[70:73], v[182:185], v[26:29]
	v_mfma_f32_16x16x32_bf16 v[14:17], v[46:49], v[190:193], v[14:17]
	v_mfma_f32_16x16x32_bf16 v[10:13], v[70:73], v[190:193], v[10:13]
	v_mfma_f32_16x16x32_bf16 v[42:45], v[82:85], v[158:161], v[42:45]
	v_mfma_f32_16x16x32_bf16 v[38:41], v[106:109], v[158:161], v[38:41]
	v_mfma_f32_16x16x32_bf16 v[22:25], v[82:85], v[174:177], v[22:25]
	v_mfma_f32_16x16x32_bf16 v[18:21], v[106:109], v[174:177], v[18:21]
	v_mfma_f32_16x16x32_bf16 v[6:9], v[82:85], v[186:189], v[6:9]
	v_mfma_f32_16x16x32_bf16 v[2:5], v[106:109], v[186:189], v[2:5]
	v_mfma_f32_16x16x32_bf16 v[34:37], v[82:85], v[142:145], v[66:69]
	v_mfma_f32_16x16x32_bf16 v[46:49], v[106:109], v[142:145], v[62:65]
	v_mfma_f32_16x16x32_bf16 v[42:45], v[94:97], v[166:169], v[42:45]
	v_mfma_f32_16x16x32_bf16 v[38:41], v[118:121], v[166:169], v[38:41]
	v_mfma_f32_16x16x32_bf16 v[22:25], v[94:97], v[182:185], v[22:25]
	v_mfma_f32_16x16x32_bf16 v[18:21], v[118:121], v[182:185], v[18:21]
	v_mfma_f32_16x16x32_bf16 v[6:9], v[94:97], v[190:193], v[6:9]
	v_mfma_f32_16x16x32_bf16 v[2:5], v[118:121], v[190:193], v[2:5]
	v_mfma_f32_16x16x32_bf16 v[34:37], v[94:97], v[154:157], v[34:37]
	v_mfma_f32_16x16x32_bf16 v[46:49], v[118:121], v[154:157], v[46:49]
	s_barrier
; #define PG8_STAGE(bufoff, gbase, voff) do { const Src _g = (gbase); _Pragma("unroll") for (int _i = 0; _i < 2; ++_i) \
;         __builtin_amdgcn_raw_ptr_buffer_load_lds(_g.r, (LAS unsigned*)(lds + (bufoff) + ldsw + _i * 8192), 16, (voff)[_i], _g.o, 0, 0); } while (0)
; #define PG8_WAIT_V(n) asm volatile("s_waitcnt vmcnt(" #n ")" ::: "memory")
; template <class Epi, bool ALIGN_EPI, bool SP2, class Hook>
; __device__ __forceinline__ void gemm_phase(LAS unsigned char* lds, const Gemm g, const StaticOrder& S, const Epi& E, Acc& acc, const bool fresh, const Hook& H, const int wave_id) {
;     ...
;         for (int t = t0; t < nt; t += 2) {
;             const bool last = (t == nt - 2);
;             const Src a1 = cA + (size_t)(t + 1) * kstep;
;             const Src a2 = last ? nA : cA + (size_t)(t + 2) * kstep, b2 = last ? nB : cB + (size_t)(t + 2) * kstep;
;             const Src a3 = a2 + kstep, b3 = b2 + kstep;
;             if (last && has_next) H(nxt);
;             if constexpr (SP2) {
;             PG8_TRIP_SP2(PG8_WAIT_V(8));
;             } else {
;             PG8_LDB(B0, 0, 0); PG8_SCHED; PG8_LDA(At, 0, 0); PG8_STAGE(PG8_SA(1, 1), a1 + hstepA, voffA);
;             PG8_WAIT_L(8); PG8_BAR; PG8_WAIT_L(0); PG8_MMA(0, 0, At, B0); PG8_BAR; PG8_SCHED;
;             PG8_LDB(B1, 0, 1); PG8_STAGE(PG8_SB(0, 0), b2, voffB);
;             PG8_BAR; PG8_WAIT_L(0); PG8_MMA(0, 1, At, B1); PG8_BAR;
;             PG8_LDA(At, 0, 1); PG8_STAGE(PG8_SA(0, 0), a2, voffA);
;             PG8_BAR; PG8_WAIT_L(0); PG8_MMA(1, 0, At, B0); PG8_BAR; PG8_SCHED;
;             PG8_STAGE(PG8_SB(0, 1), b2 + hstep, voffB);
;             PG8_WAIT_V(6); PG8_BAR; PG8_MMA(1, 1, At, B1); PG8_BAR;
;             PG8_LDB(B0, 1, 0); PG8_SCHED; PG8_LDA(At, 1, 0); PG8_STAGE(PG8_SA(0, 1), a2 + hstepA, voffA);
;             PG8_WAIT_L(8); PG8_BAR; PG8_WAIT_L(0); PG8_MMA(0, 0, At, B0); PG8_BAR; PG8_SCHED;
;             PG8_LDB(B1, 1, 1); PG8_STAGE(PG8_SB(1, 0), b3, voffB);
;             PG8_BAR; PG8_WAIT_L(0); PG8_MMA(0, 1, At, B1); PG8_BAR;
;             PG8_LDA(At, 1, 1); PG8_STAGE(PG8_SA(1, 0), a3, voffA);
;             PG8_BAR; PG8_WAIT_L(0); PG8_MMA(1, 0, At, B0); PG8_BAR; PG8_SCHED;
;             PG8_STAGE(PG8_SB(1, 1), b3 + hstep, voffB);
;             PG8_WAIT_V(6); PG8_BAR; PG8_MMA(1, 1, At, B1); PG8_BAR;
;             }
;         }
;         if constexpr (ALIGN_EPI) { if (wr == 0) PG8_BAR; }
	s_setprio 0
	v_add_u32_e32 v70, 0x18000, v216
	v_add_u32_e32 v118, 0x1c000, v216
	ds_read_b128 v[58:61], v70
	ds_read_b128 v[62:65], v70 offset:1024
	ds_read_b128 v[66:69], v70 offset:2048
	ds_read_b128 v[70:73], v70 offset:3072
	ds_read_b128 v[82:85], v118
	ds_read_b128 v[94:97], v118 offset:1024
	ds_read_b128 v[106:109], v118 offset:2048
	ds_read_b128 v[118:121], v118 offset:3072
	s_add_i32 s60, s60, 0x20000
	s_mov_b32 m0, s37
	ds_read_b128 v[142:145], v217 offset:32768
	ds_read_b128 v[154:157], v217 offset:33792
	ds_read_b128 v[166:169], v217 offset:34816
	ds_read_b128 v[174:177], v217 offset:35840
	ds_read_b128 v[182:185], v217 offset:36864
	ds_read_b128 v[186:189], v217 offset:37888
	ds_read_b128 v[190:193], v217 offset:38912
	ds_read_b128 v[194:197], v217 offset:39936
	buffer_load_dwordx4 v0, s[16:19], s60 offen lds
	s_mov_b32 m0, s38
	s_nop 0
	buffer_load_dwordx4 v214, s[16:19], s60 offen lds
	s_waitcnt vmcnt(8)
	s_waitcnt lgkmcnt(0)
	s_setprio 3
	s_barrier
	v_mfma_f32_16x16x32_bf16 v[158:161], v[58:61], v[142:145], v[178:181]
	v_mfma_f32_16x16x32_bf16 v[178:181], v[62:65], v[154:157], v[158:161]
	v_mfma_f32_16x16x32_bf16 v[158:161], v[66:69], v[142:145], v[170:173]
	v_mfma_f32_16x16x32_bf16 v[150:153], v[58:61], v[166:169], v[150:153]
	v_mfma_f32_16x16x32_bf16 v[146:149], v[66:69], v[166:169], v[146:149]
	v_mfma_f32_16x16x32_bf16 v[126:129], v[58:61], v[182:185], v[126:129]
	v_mfma_f32_16x16x32_bf16 v[122:125], v[66:69], v[182:185], v[122:125]
	v_mfma_f32_16x16x32_bf16 v[102:105], v[58:61], v[190:193], v[102:105]
	v_mfma_f32_16x16x32_bf16 v[98:101], v[66:69], v[190:193], v[98:101]
	v_mfma_f32_16x16x32_bf16 v[170:173], v[70:73], v[154:157], v[158:161]
	v_mfma_f32_16x16x32_bf16 v[150:153], v[62:65], v[174:177], v[150:153]
	v_mfma_f32_16x16x32_bf16 v[146:149], v[70:73], v[174:177], v[146:149]
	v_mfma_f32_16x16x32_bf16 v[126:129], v[62:65], v[186:189], v[126:129]
	v_mfma_f32_16x16x32_bf16 v[122:125], v[70:73], v[186:189], v[122:125]
	v_mfma_f32_16x16x32_bf16 v[102:105], v[62:65], v[194:197], v[102:105]
	v_mfma_f32_16x16x32_bf16 v[98:101], v[70:73], v[194:197], v[98:101]
	v_mfma_f32_16x16x32_bf16 v[158:161], v[82:85], v[142:145], v[162:165]
	v_mfma_f32_16x16x32_bf16 v[130:133], v[106:109], v[142:145], v[130:133]
	v_mfma_f32_16x16x32_bf16 v[162:165], v[94:97], v[154:157], v[158:161]
	v_mfma_f32_16x16x32_bf16 v[158:161], v[118:121], v[154:157], v[130:133]
	v_mfma_f32_16x16x32_bf16 v[130:133], v[82:85], v[166:169], v[138:141]
	v_mfma_f32_16x16x32_bf16 v[138:141], v[94:97], v[174:177], v[130:133]
	v_mfma_f32_16x16x32_bf16 v[130:133], v[106:109], v[166:169], v[134:137]
	v_mfma_f32_16x16x32_bf16 v[114:117], v[82:85], v[182:185], v[114:117]
	v_mfma_f32_16x16x32_bf16 v[110:113], v[106:109], v[182:185], v[110:113]
	v_mfma_f32_16x16x32_bf16 v[90:93], v[82:85], v[190:193], v[90:93]
	v_mfma_f32_16x16x32_bf16 v[86:89], v[106:109], v[190:193], v[86:89]
	v_mfma_f32_16x16x32_bf16 v[134:137], v[118:121], v[174:177], v[130:133]
	v_mfma_f32_16x16x32_bf16 v[114:117], v[94:97], v[186:189], v[114:117]
	v_mfma_f32_16x16x32_bf16 v[110:113], v[118:121], v[186:189], v[110:113]
	v_mfma_f32_16x16x32_bf16 v[90:93], v[94:97], v[194:197], v[90:93]
	v_mfma_f32_16x16x32_bf16 v[86:89], v[118:121], v[194:197], v[86:89]
	s_barrier
	s_setprio 0
	s_mov_b32 m0, s39
	s_or_b32 s60, s58, 0x80
	ds_read_b128 v[130:133], v217 offset:49152
	ds_read_b128 v[142:145], v217 offset:50176
	ds_read_b128 v[154:157], v217 offset:51200
	ds_read_b128 v[166:169], v217 offset:52224
	ds_read_b128 v[174:177], v217 offset:53248
	ds_read_b128 v[182:185], v217 offset:54272
	ds_read_b128 v[186:189], v217 offset:55296
	ds_read_b128 v[190:193], v217 offset:56320
	buffer_load_dwordx4 v199, s[12:15], s60 offen lds
	s_mov_b32 m0, s40
	s_add_i32 s58, s58, 0x20080
	buffer_load_dwordx4 v215, s[12:15], s60 offen lds
	s_mov_b32 m0, s43
	s_nop 0
	buffer_load_dwordx4 v199, s[12:15], s58 offen lds
	s_mov_b32 m0, s42
	s_nop 0
	buffer_load_dwordx4 v215, s[12:15], s58 offen lds
	s_mov_b32 m0, s41
	s_nop 0
	buffer_load_dwordx4 v0, s[16:19], s59 offen lds
	s_mov_b32 m0, s33
	s_nop 0
	buffer_load_dwordx4 v214, s[16:19], s59 offen lds
	s_waitcnt vmcnt(8)
	s_waitcnt lgkmcnt(0)
	s_setprio 3
	s_barrier
	v_mfma_f32_16x16x32_bf16 v[78:81], v[58:61], v[130:133], v[78:81]
	v_mfma_f32_16x16x32_bf16 v[74:77], v[66:69], v[130:133], v[74:77]
	v_mfma_f32_16x16x32_bf16 v[54:57], v[58:61], v[154:157], v[54:57]
	v_mfma_f32_16x16x32_bf16 v[50:53], v[66:69], v[154:157], v[50:53]
	v_mfma_f32_16x16x32_bf16 v[30:33], v[58:61], v[174:177], v[30:33]
	v_mfma_f32_16x16x32_bf16 v[26:29], v[66:69], v[174:177], v[26:29]
	v_mfma_f32_16x16x32_bf16 v[14:17], v[58:61], v[186:189], v[14:17]
	v_mfma_f32_16x16x32_bf16 v[10:13], v[66:69], v[186:189], v[10:13]
	v_mfma_f32_16x16x32_bf16 v[78:81], v[62:65], v[142:145], v[78:81]
	v_mfma_f32_16x16x32_bf16 v[74:77], v[70:73], v[142:145], v[74:77]
	v_mfma_f32_16x16x32_bf16 v[54:57], v[62:65], v[166:169], v[54:57]
	v_mfma_f32_16x16x32_bf16 v[50:53], v[70:73], v[166:169], v[50:53]
	v_mfma_f32_16x16x32_bf16 v[30:33], v[62:65], v[182:185], v[30:33]
	v_mfma_f32_16x16x32_bf16 v[26:29], v[70:73], v[182:185], v[26:29]
	v_mfma_f32_16x16x32_bf16 v[14:17], v[62:65], v[190:193], v[14:17]
	v_mfma_f32_16x16x32_bf16 v[10:13], v[70:73], v[190:193], v[10:13]
	v_mfma_f32_16x16x32_bf16 v[34:37], v[82:85], v[130:133], v[34:37]
	v_mfma_f32_16x16x32_bf16 v[66:69], v[94:97], v[142:145], v[34:37]
	v_mfma_f32_16x16x32_bf16 v[34:37], v[106:109], v[130:133], v[46:49]
	v_mfma_f32_16x16x32_bf16 v[62:65], v[118:121], v[142:145], v[34:37]
	v_mfma_f32_16x16x32_bf16 v[34:37], v[82:85], v[154:157], v[42:45]
	v_mfma_f32_16x16x32_bf16 v[42:45], v[94:97], v[166:169], v[34:37]
	v_mfma_f32_16x16x32_bf16 v[34:37], v[106:109], v[154:157], v[38:41]
	v_mfma_f32_16x16x32_bf16 v[22:25], v[82:85], v[174:177], v[22:25]
	v_mfma_f32_16x16x32_bf16 v[18:21], v[106:109], v[174:177], v[18:21]
	v_mfma_f32_16x16x32_bf16 v[6:9], v[82:85], v[186:189], v[6:9]
	v_mfma_f32_16x16x32_bf16 v[2:5], v[106:109], v[186:189], v[2:5]
	v_mfma_f32_16x16x32_bf16 v[38:41], v[118:121], v[166:169], v[34:37]
	v_mfma_f32_16x16x32_bf16 v[22:25], v[94:97], v[182:185], v[22:25]
	v_mfma_f32_16x16x32_bf16 v[18:21], v[118:121], v[182:185], v[18:21]
	v_mfma_f32_16x16x32_bf16 v[6:9], v[94:97], v[190:193], v[6:9]
	v_mfma_f32_16x16x32_bf16 v[2:5], v[118:121], v[190:193], v[2:5]
	s_barrier
	s_setprio 0
	s_add_i32 s57, s57, 2
	s_addk_i32 s55, 0x100
	s_addk_i32 s56, 0x100
	s_cmp_gt_u32 s57, 5
	s_cbranch_scc0 .LBB0_702
	v_readlane_b32 s8, v251, 45
	v_readlane_b32 s9, v251, 46
	s_and_b64 vcc, exec, s[8:9]
	s_cbranch_vccz .LBB0_705
	s_barrier

; #define PG8_WAIT_V(n) asm volatile("s_waitcnt vmcnt(" #n ")" ::: "memory")
; template <class Epi, bool ALIGN_EPI, bool SP2, class Hook>
; __device__ __forceinline__ void gemm_phase(LAS unsigned char* lds, const Gemm g, const StaticOrder& S, const Epi& E, Acc& acc, const bool fresh, const Hook& H, const int wave_id) {
;     ...
;         for (int t = t0; t < nt; t += 2) {
;             const bool last = (t == nt - 2);
;             const Src a1 = cA + (size_t)(t + 1) * kstep;
;             const Src a2 = last ? nA : cA + (size_t)(t + 2) * kstep, b2 = last ? nB : cB + (size_t)(t + 2) * kstep;
;             const Src a3 = a2 + kstep, b3 = b2 + kstep;
;             if (last && has_next) H(nxt);
;             if constexpr (SP2) {
;             PG8_TRIP_SP2(PG8_WAIT_V(8));
.LBB0_779:
	v_add_u32_e32 v0, 0x10000, v230
	s_waitcnt vmcnt(0)
	ds_read_b128 v[130:133], v0
	ds_read_b128 v[134:137], v0 offset:1024
	ds_read_b128 v[138:141], v0 offset:2048
	ds_read_b128 v[142:145], v0 offset:3072
	v_add_u32_e32 v0, 0x14000, v230
	ds_read_b128 v[146:149], v0
	ds_read_b128 v[150:153], v0 offset:1024
	ds_read_b128 v[154:157], v0 offset:2048
	ds_read_b128 v[158:161], v0 offset:3072
	s_add_i32 s12, s2, 0xfffe0080
	s_cmp_eq_u32 s63, 4
	s_cselect_b32 s66, s60, s12
	s_cselect_b32 s13, s53, s77
	s_cselect_b32 s12, s52, s76
	s_cselect_b32 s15, s55, s7
	s_cselect_b32 s14, s54, s6
	s_cselect_b32 s64, s61, s3
	s_cselect_b32 s16, s34, s8
	s_cselect_b32 s17, s35, s9
	s_cselect_b32 s18, s50, s10
	s_cselect_b32 s19, s51, s11
	s_or_b32 s65, s66, 0x80
	s_mov_b32 m0, s45
	ds_read_b128 v[162:165], v231
	ds_read_b128 v[166:169], v231 offset:1024
	ds_read_b128 v[170:173], v231 offset:2048
	ds_read_b128 v[174:177], v231 offset:3072
	ds_read_b128 v[178:181], v231 offset:4096
	ds_read_b128 v[182:185], v231 offset:5120
	ds_read_b128 v[186:189], v231 offset:6144
	ds_read_b128 v[190:193], v231 offset:7168
	buffer_load_dwordx4 v199, s[8:11], s2 offen lds
	s_mov_b32 m0, s46
	s_nop 0
	buffer_load_dwordx4 v228, s[8:11], s2 offen lds
	s_waitcnt vmcnt(8)
	s_waitcnt lgkmcnt(0)
	s_setprio 3
	s_barrier
	v_mfma_f32_16x16x32_bf16 v[126:129], v[130:133], v[162:165], v[126:129]
	v_mfma_f32_16x16x32_bf16 v[122:125], v[138:141], v[162:165], v[122:125]
	v_mfma_f32_16x16x32_bf16 v[118:121], v[130:133], v[170:173], v[118:121]
	v_mfma_f32_16x16x32_bf16 v[114:117], v[138:141], v[170:173], v[114:117]
	v_mfma_f32_16x16x32_bf16 v[110:113], v[130:133], v[178:181], v[110:113]
	v_mfma_f32_16x16x32_bf16 v[106:109], v[138:141], v[178:181], v[106:109]
	v_mfma_f32_16x16x32_bf16 v[102:105], v[130:133], v[186:189], v[102:105]
	v_mfma_f32_16x16x32_bf16 v[98:101], v[138:141], v[186:189], v[98:101]
	v_mfma_f32_16x16x32_bf16 v[126:129], v[134:137], v[166:169], v[126:129]
	v_mfma_f32_16x16x32_bf16 v[122:125], v[142:145], v[166:169], v[122:125]
	v_mfma_f32_16x16x32_bf16 v[118:121], v[134:137], v[174:177], v[118:121]
	v_mfma_f32_16x16x32_bf16 v[114:117], v[142:145], v[174:177], v[114:117]
	v_mfma_f32_16x16x32_bf16 v[110:113], v[134:137], v[182:185], v[110:113]
	v_mfma_f32_16x16x32_bf16 v[106:109], v[142:145], v[182:185], v[106:109]
	v_mfma_f32_16x16x32_bf16 v[102:105], v[134:137], v[190:193], v[102:105]
	v_mfma_f32_16x16x32_bf16 v[98:101], v[142:145], v[190:193], v[98:101]
	v_mfma_f32_16x16x32_bf16 v[94:97], v[146:149], v[162:165], v[94:97]
	v_mfma_f32_16x16x32_bf16 v[90:93], v[154:157], v[162:165], v[90:93]
	v_mfma_f32_16x16x32_bf16 v[86:89], v[146:149], v[170:173], v[86:89]
	v_mfma_f32_16x16x32_bf16 v[82:85], v[154:157], v[170:173], v[82:85]
	v_mfma_f32_16x16x32_bf16 v[78:81], v[146:149], v[178:181], v[78:81]
	v_mfma_f32_16x16x32_bf16 v[74:77], v[154:157], v[178:181], v[74:77]
	v_mfma_f32_16x16x32_bf16 v[70:73], v[146:149], v[186:189], v[70:73]
	v_mfma_f32_16x16x32_bf16 v[66:69], v[154:157], v[186:189], v[66:69]
	v_mfma_f32_16x16x32_bf16 v[94:97], v[150:153], v[166:169], v[94:97]
	v_mfma_f32_16x16x32_bf16 v[90:93], v[158:161], v[166:169], v[90:93]
	v_mfma_f32_16x16x32_bf16 v[86:89], v[150:153], v[174:177], v[86:89]
	v_mfma_f32_16x16x32_bf16 v[82:85], v[158:161], v[174:177], v[82:85]
	v_mfma_f32_16x16x32_bf16 v[78:81], v[150:153], v[182:185], v[78:81]
	v_mfma_f32_16x16x32_bf16 v[74:77], v[158:161], v[182:185], v[74:77]
	v_mfma_f32_16x16x32_bf16 v[70:73], v[150:153], v[190:193], v[70:73]
	v_mfma_f32_16x16x32_bf16 v[66:69], v[158:161], v[190:193], v[66:69]
	s_barrier
	s_setprio 0
	s_mov_b32 m0, s92
	ds_read_b128 v[162:165], v231 offset:16384
	ds_read_b128 v[166:169], v231 offset:17408
	ds_read_b128 v[170:173], v231 offset:18432
	ds_read_b128 v[174:177], v231 offset:19456
	ds_read_b128 v[178:181], v231 offset:20480
	ds_read_b128 v[182:185], v231 offset:21504
	ds_read_b128 v[186:189], v231 offset:22528
	ds_read_b128 v[190:193], v231 offset:23552
	buffer_load_dwordx4 v227, s[12:15], s64 offen lds
	s_mov_b32 m0, s93
	s_add_i32 s67, s64, 0x20000
	buffer_load_dwordx4 v229, s[12:15], s64 offen lds
	s_mov_b32 m0, s94
	s_nop 0
	buffer_load_dwordx4 v227, s[12:15], s67 offen lds
	s_mov_b32 m0, s95
	s_nop 0
	buffer_load_dwordx4 v229, s[12:15], s67 offen lds
	s_mov_b32 m0, s44
	s_nop 0
	buffer_load_dwordx4 v199, s[16:19], s66 offen lds
	s_mov_b32 m0, s36
	s_nop 0
	buffer_load_dwordx4 v228, s[16:19], s66 offen lds
	s_waitcnt vmcnt(8)
	s_waitcnt lgkmcnt(0)
	s_setprio 3
	s_barrier
	v_mfma_f32_16x16x32_bf16 v[62:65], v[130:133], v[162:165], v[62:65]
	v_mfma_f32_16x16x32_bf16 v[58:61], v[138:141], v[162:165], v[58:61]
	v_mfma_f32_16x16x32_bf16 v[54:57], v[130:133], v[170:173], v[54:57]
	v_mfma_f32_16x16x32_bf16 v[50:53], v[138:141], v[170:173], v[50:53]
	v_mfma_f32_16x16x32_bf16 v[46:49], v[130:133], v[178:181], v[46:49]
	v_mfma_f32_16x16x32_bf16 v[42:45], v[138:141], v[178:181], v[42:45]
	v_mfma_f32_16x16x32_bf16 v[38:41], v[130:133], v[186:189], v[38:41]
	v_mfma_f32_16x16x32_bf16 v[34:37], v[138:141], v[186:189], v[34:37]
	v_mfma_f32_16x16x32_bf16 v[62:65], v[134:137], v[166:169], v[62:65]
	v_mfma_f32_16x16x32_bf16 v[58:61], v[142:145], v[166:169], v[58:61]
	v_mfma_f32_16x16x32_bf16 v[54:57], v[134:137], v[174:177], v[54:57]
	v_mfma_f32_16x16x32_bf16 v[50:53], v[142:145], v[174:177], v[50:53]
	v_mfma_f32_16x16x32_bf16 v[46:49], v[134:137], v[182:185], v[46:49]
	v_mfma_f32_16x16x32_bf16 v[42:45], v[142:145], v[182:185], v[42:45]
	v_mfma_f32_16x16x32_bf16 v[38:41], v[134:137], v[190:193], v[38:41]
	v_mfma_f32_16x16x32_bf16 v[34:37], v[142:145], v[190:193], v[34:37]
	v_mfma_f32_16x16x32_bf16 v[30:33], v[146:149], v[162:165], v[30:33]
	v_mfma_f32_16x16x32_bf16 v[26:29], v[154:157], v[162:165], v[26:29]
	v_mfma_f32_16x16x32_bf16 v[22:25], v[146:149], v[170:173], v[22:25]
	v_mfma_f32_16x16x32_bf16 v[18:21], v[154:157], v[170:173], v[18:21]
	v_mfma_f32_16x16x32_bf16 v[14:17], v[146:149], v[178:181], v[14:17]
	v_mfma_f32_16x16x32_bf16 v[10:13], v[154:157], v[178:181], v[10:13]
	v_mfma_f32_16x16x32_bf16 v[6:9], v[146:149], v[186:189], v[6:9]
	v_mfma_f32_16x16x32_bf16 v[2:5], v[154:157], v[186:189], v[2:5]
	v_mfma_f32_16x16x32_bf16 v[30:33], v[150:153], v[166:169], v[30:33]
	v_mfma_f32_16x16x32_bf16 v[26:29], v[158:161], v[166:169], v[26:29]
	v_mfma_f32_16x16x32_bf16 v[22:25], v[150:153], v[174:177], v[22:25]
	v_mfma_f32_16x16x32_bf16 v[18:21], v[158:161], v[174:177], v[18:21]
	v_mfma_f32_16x16x32_bf16 v[14:17], v[150:153], v[182:185], v[14:17]
	v_mfma_f32_16x16x32_bf16 v[10:13], v[158:161], v[182:185], v[10:13]
	v_mfma_f32_16x16x32_bf16 v[6:9], v[150:153], v[190:193], v[6:9]
	v_mfma_f32_16x16x32_bf16 v[2:5], v[158:161], v[190:193], v[2:5]
	s_barrier
; #define PG8_STAGE(bufoff, gbase, voff) do { const Src _g = (gbase); _Pragma("unroll") for (int _i = 0; _i < 2; ++_i) \
;         __builtin_amdgcn_raw_ptr_buffer_load_lds(_g.r, (LAS unsigned*)(lds + (bufoff) + ldsw + _i * 8192), 16, (voff)[_i], _g.o, 0, 0); } while (0)
; #define PG8_WAIT_V(n) asm volatile("s_waitcnt vmcnt(" #n ")" ::: "memory")
; template <class Epi, bool ALIGN_EPI, bool SP2, class Hook>
; __device__ __forceinline__ void gemm_phase(LAS unsigned char* lds, const Gemm g, const StaticOrder& S, const Epi& E, Acc& acc, const bool fresh, const Hook& H, const int wave_id) {
;     ...
;         for (int t = t0; t < nt; t += 2) {
;             const bool last = (t == nt - 2);
;             const Src a1 = cA + (size_t)(t + 1) * kstep;
;             const Src a2 = last ? nA : cA + (size_t)(t + 2) * kstep, b2 = last ? nB : cB + (size_t)(t + 2) * kstep;
;             const Src a3 = a2 + kstep, b3 = b2 + kstep;
;             if (last && has_next) H(nxt);
;             if constexpr (SP2) {
;             PG8_TRIP_SP2(PG8_WAIT_V(8));
;             } else {
;             PG8_LDB(B0, 0, 0); PG8_SCHED; PG8_LDA(At, 0, 0); PG8_STAGE(PG8_SA(1, 1), a1 + hstepA, voffA);
;             PG8_WAIT_L(8); PG8_BAR; PG8_WAIT_L(0); PG8_MMA(0, 0, At, B0); PG8_BAR; PG8_SCHED;
;             PG8_LDB(B1, 0, 1); PG8_STAGE(PG8_SB(0, 0), b2, voffB);
;             PG8_BAR; PG8_WAIT_L(0); PG8_MMA(0, 1, At, B1); PG8_BAR;
;             PG8_LDA(At, 0, 1); PG8_STAGE(PG8_SA(0, 0), a2, voffA);
;             PG8_BAR; PG8_WAIT_L(0); PG8_MMA(1, 0, At, B0); PG8_BAR; PG8_SCHED;
;             PG8_STAGE(PG8_SB(0, 1), b2 + hstep, voffB);
;             PG8_WAIT_V(6); PG8_BAR; PG8_MMA(1, 1, At, B1); PG8_BAR;
;             PG8_LDB(B0, 1, 0); PG8_SCHED; PG8_LDA(At, 1, 0); PG8_STAGE(PG8_SA(0, 1), a2 + hstepA, voffA);
;             PG8_WAIT_L(8); PG8_BAR; PG8_WAIT_L(0); PG8_MMA(0, 0, At, B0); PG8_BAR; PG8_SCHED;
;             PG8_LDB(B1, 1, 1); PG8_STAGE(PG8_SB(1, 0), b3, voffB);
;             PG8_BAR; PG8_WAIT_L(0); PG8_MMA(0, 1, At, B1); PG8_BAR;
;             PG8_LDA(At, 1, 1); PG8_STAGE(PG8_SA(1, 0), a3, voffA);
;             PG8_BAR; PG8_WAIT_L(0); PG8_MMA(1, 0, At, B0); PG8_BAR; PG8_SCHED;
;             PG8_STAGE(PG8_SB(1, 1), b3 + hstep, voffB);
;             PG8_WAIT_V(6); PG8_BAR; PG8_MMA(1, 1, At, B1); PG8_BAR;
;             }
;         }
;         if constexpr (ALIGN_EPI) { if (wr == 0) PG8_BAR; }
	s_setprio 0
	v_add_u32_e32 v0, 0x18000, v230
	ds_read_b128 v[130:133], v0
	ds_read_b128 v[134:137], v0 offset:1024
	ds_read_b128 v[138:141], v0 offset:2048
	ds_read_b128 v[142:145], v0 offset:3072
	v_add_u32_e32 v0, 0x1c000, v230
	ds_read_b128 v[146:149], v0
	ds_read_b128 v[150:153], v0 offset:1024
	ds_read_b128 v[154:157], v0 offset:2048
	ds_read_b128 v[158:161], v0 offset:3072
	s_add_i32 s66, s66, 0x20000
	s_mov_b32 m0, s37
	ds_read_b128 v[162:165], v231 offset:32768
	ds_read_b128 v[166:169], v231 offset:33792
	ds_read_b128 v[170:173], v231 offset:34816
	ds_read_b128 v[174:177], v231 offset:35840
	ds_read_b128 v[178:181], v231 offset:36864
	ds_read_b128 v[182:185], v231 offset:37888
	ds_read_b128 v[186:189], v231 offset:38912
	ds_read_b128 v[190:193], v231 offset:39936
	buffer_load_dwordx4 v199, s[16:19], s66 offen lds
	s_mov_b32 m0, s38
	s_nop 0
	buffer_load_dwordx4 v228, s[16:19], s66 offen lds
	s_waitcnt vmcnt(8)
	s_waitcnt lgkmcnt(0)
	s_setprio 3
	s_barrier
	v_mfma_f32_16x16x32_bf16 v[126:129], v[130:133], v[162:165], v[126:129]
	v_mfma_f32_16x16x32_bf16 v[122:125], v[138:141], v[162:165], v[122:125]
	v_mfma_f32_16x16x32_bf16 v[118:121], v[130:133], v[170:173], v[118:121]
	v_mfma_f32_16x16x32_bf16 v[114:117], v[138:141], v[170:173], v[114:117]
	v_mfma_f32_16x16x32_bf16 v[110:113], v[130:133], v[178:181], v[110:113]
	v_mfma_f32_16x16x32_bf16 v[106:109], v[138:141], v[178:181], v[106:109]
	v_mfma_f32_16x16x32_bf16 v[102:105], v[130:133], v[186:189], v[102:105]
	v_mfma_f32_16x16x32_bf16 v[98:101], v[138:141], v[186:189], v[98:101]
	v_mfma_f32_16x16x32_bf16 v[126:129], v[134:137], v[166:169], v[126:129]
	v_mfma_f32_16x16x32_bf16 v[122:125], v[142:145], v[166:169], v[122:125]
	v_mfma_f32_16x16x32_bf16 v[118:121], v[134:137], v[174:177], v[118:121]
	v_mfma_f32_16x16x32_bf16 v[114:117], v[142:145], v[174:177], v[114:117]
	v_mfma_f32_16x16x32_bf16 v[110:113], v[134:137], v[182:185], v[110:113]
	v_mfma_f32_16x16x32_bf16 v[106:109], v[142:145], v[182:185], v[106:109]
	v_mfma_f32_16x16x32_bf16 v[102:105], v[134:137], v[190:193], v[102:105]
	v_mfma_f32_16x16x32_bf16 v[98:101], v[142:145], v[190:193], v[98:101]
	v_mfma_f32_16x16x32_bf16 v[94:97], v[146:149], v[162:165], v[94:97]
	v_mfma_f32_16x16x32_bf16 v[90:93], v[154:157], v[162:165], v[90:93]
	v_mfma_f32_16x16x32_bf16 v[86:89], v[146:149], v[170:173], v[86:89]
	v_mfma_f32_16x16x32_bf16 v[82:85], v[154:157], v[170:173], v[82:85]
	v_mfma_f32_16x16x32_bf16 v[78:81], v[146:149], v[178:181], v[78:81]
	v_mfma_f32_16x16x32_bf16 v[74:77], v[154:157], v[178:181], v[74:77]
	v_mfma_f32_16x16x32_bf16 v[70:73], v[146:149], v[186:189], v[70:73]
	v_mfma_f32_16x16x32_bf16 v[66:69], v[154:157], v[186:189], v[66:69]
	v_mfma_f32_16x16x32_bf16 v[94:97], v[150:153], v[166:169], v[94:97]
	v_mfma_f32_16x16x32_bf16 v[90:93], v[158:161], v[166:169], v[90:93]
	v_mfma_f32_16x16x32_bf16 v[86:89], v[150:153], v[174:177], v[86:89]
	v_mfma_f32_16x16x32_bf16 v[82:85], v[158:161], v[174:177], v[82:85]
	v_mfma_f32_16x16x32_bf16 v[78:81], v[150:153], v[182:185], v[78:81]
	v_mfma_f32_16x16x32_bf16 v[74:77], v[158:161], v[182:185], v[74:77]
	v_mfma_f32_16x16x32_bf16 v[70:73], v[150:153], v[190:193], v[70:73]
	v_mfma_f32_16x16x32_bf16 v[66:69], v[158:161], v[190:193], v[66:69]
	s_barrier
	s_setprio 0
	s_mov_b32 m0, s39
	s_or_b32 s66, s64, 0x80
	ds_read_b128 v[162:165], v231 offset:49152
	ds_read_b128 v[166:169], v231 offset:50176
	ds_read_b128 v[170:173], v231 offset:51200
	ds_read_b128 v[174:177], v231 offset:52224
	ds_read_b128 v[178:181], v231 offset:53248
	ds_read_b128 v[182:185], v231 offset:54272
	ds_read_b128 v[186:189], v231 offset:55296
	ds_read_b128 v[190:193], v231 offset:56320
	buffer_load_dwordx4 v227, s[12:15], s66 offen lds
	s_mov_b32 m0, s40
	s_add_i32 s64, s64, 0x20080
	buffer_load_dwordx4 v229, s[12:15], s66 offen lds
	s_mov_b32 m0, s43
	s_nop 0
	buffer_load_dwordx4 v227, s[12:15], s64 offen lds
	s_mov_b32 m0, s42
	s_nop 0
	buffer_load_dwordx4 v229, s[12:15], s64 offen lds
	s_mov_b32 m0, s41
	s_nop 0
	buffer_load_dwordx4 v199, s[16:19], s65 offen lds
	s_mov_b32 m0, s33
	s_nop 0
	buffer_load_dwordx4 v228, s[16:19], s65 offen lds
	s_waitcnt vmcnt(8)
	s_waitcnt lgkmcnt(0)
	s_setprio 3
	s_barrier
	v_mfma_f32_16x16x32_bf16 v[62:65], v[130:133], v[162:165], v[62:65]
	v_mfma_f32_16x16x32_bf16 v[58:61], v[138:141], v[162:165], v[58:61]
	v_mfma_f32_16x16x32_bf16 v[54:57], v[130:133], v[170:173], v[54:57]
	v_mfma_f32_16x16x32_bf16 v[50:53], v[138:141], v[170:173], v[50:53]
	v_mfma_f32_16x16x32_bf16 v[46:49], v[130:133], v[178:181], v[46:49]
	v_mfma_f32_16x16x32_bf16 v[42:45], v[138:141], v[178:181], v[42:45]
	v_mfma_f32_16x16x32_bf16 v[38:41], v[130:133], v[186:189], v[38:41]
	v_mfma_f32_16x16x32_bf16 v[34:37], v[138:141], v[186:189], v[34:37]
	v_mfma_f32_16x16x32_bf16 v[62:65], v[134:137], v[166:169], v[62:65]
	v_mfma_f32_16x16x32_bf16 v[58:61], v[142:145], v[166:169], v[58:61]
	v_mfma_f32_16x16x32_bf16 v[54:57], v[134:137], v[174:177], v[54:57]
	v_mfma_f32_16x16x32_bf16 v[50:53], v[142:145], v[174:177], v[50:53]
	v_mfma_f32_16x16x32_bf16 v[46:49], v[134:137], v[182:185], v[46:49]
	v_mfma_f32_16x16x32_bf16 v[42:45], v[142:145], v[182:185], v[42:45]
	v_mfma_f32_16x16x32_bf16 v[38:41], v[134:137], v[190:193], v[38:41]
	v_mfma_f32_16x16x32_bf16 v[34:37], v[142:145], v[190:193], v[34:37]
	v_mfma_f32_16x16x32_bf16 v[30:33], v[146:149], v[162:165], v[30:33]
	v_mfma_f32_16x16x32_bf16 v[26:29], v[154:157], v[162:165], v[26:29]
	v_mfma_f32_16x16x32_bf16 v[22:25], v[146:149], v[170:173], v[22:25]
	v_mfma_f32_16x16x32_bf16 v[18:21], v[154:157], v[170:173], v[18:21]
	v_mfma_f32_16x16x32_bf16 v[14:17], v[146:149], v[178:181], v[14:17]
	v_mfma_f32_16x16x32_bf16 v[10:13], v[154:157], v[178:181], v[10:13]
	v_mfma_f32_16x16x32_bf16 v[6:9], v[146:149], v[186:189], v[6:9]
	v_mfma_f32_16x16x32_bf16 v[2:5], v[154:157], v[186:189], v[2:5]
	v_mfma_f32_16x16x32_bf16 v[30:33], v[150:153], v[166:169], v[30:33]
	v_mfma_f32_16x16x32_bf16 v[26:29], v[158:161], v[166:169], v[26:29]
	v_mfma_f32_16x16x32_bf16 v[22:25], v[150:153], v[174:177], v[22:25]
	v_mfma_f32_16x16x32_bf16 v[18:21], v[158:161], v[174:177], v[18:21]
	v_mfma_f32_16x16x32_bf16 v[14:17], v[150:153], v[182:185], v[14:17]
	v_mfma_f32_16x16x32_bf16 v[10:13], v[158:161], v[182:185], v[10:13]
	v_mfma_f32_16x16x32_bf16 v[6:9], v[150:153], v[190:193], v[6:9]
	v_mfma_f32_16x16x32_bf16 v[2:5], v[158:161], v[190:193], v[2:5]
	s_barrier
	s_setprio 0
	s_add_i32 s63, s63, 2
	s_addk_i32 s2, 0x100
	s_addk_i32 s3, 0x100
	s_cmp_gt_u32 s63, 5
	s_cbranch_scc0 .LBB0_779
	v_readlane_b32 s2, v251, 45
	v_readlane_b32 s3, v251, 46
	s_and_b64 vcc, exec, s[2:3]
	s_cbranch_vccz .LBB0_782
	s_barrier

; #define PG8_WAIT_V(n) asm volatile("s_waitcnt vmcnt(" #n ")" ::: "memory")
; template <class Epi, bool ALIGN_EPI, bool SP2, class Hook>
; __device__ __forceinline__ void gemm_phase(LAS unsigned char* lds, const Gemm g, const StaticOrder& S, const Epi& E, Acc& acc, const bool fresh, const Hook& H, const int wave_id) {
;     ...
;         for (int t = t0; t < nt; t += 2) {
;             const bool last = (t == nt - 2);
;             const Src a1 = cA + (size_t)(t + 1) * kstep;
;             const Src a2 = last ? nA : cA + (size_t)(t + 2) * kstep, b2 = last ? nB : cB + (size_t)(t + 2) * kstep;
;             const Src a3 = a2 + kstep, b3 = b2 + kstep;
;             if (last && has_next) H(nxt);
;             if constexpr (SP2) {
;             PG8_TRIP_SP2(PG8_WAIT_V(8));
.LBB0_903:
	v_add_u32_e32 v70, 0x10000, v216
	v_add_u32_e32 v118, 0x14000, v216
	ds_read_b128 v[34:37], v70
	ds_read_b128 v[46:49], v70 offset:1024
	ds_read_b128 v[58:61], v70 offset:2048
	ds_read_b128 v[70:73], v70 offset:3072
	ds_read_b128 v[82:85], v118
	ds_read_b128 v[94:97], v118 offset:1024
	ds_read_b128 v[106:109], v118 offset:2048
	ds_read_b128 v[118:121], v118 offset:3072
	s_add_i32 s12, s55, 0xfffe0080
	s_cmp_eq_u32 s57, 4
	s_cselect_b32 s60, s53, s12
	s_cselect_b32 s13, s29, s77
	s_cselect_b32 s12, s28, s76
	s_cselect_b32 s15, s31, s35
	s_cselect_b32 s14, s30, s34
	s_cselect_b32 s58, s54, s56
	s_cselect_b32 s16, s2, s8
	s_cselect_b32 s17, s3, s9
	s_cselect_b32 s18, s26, s10
	s_cselect_b32 s19, s27, s11
	s_or_b32 s59, s60, 0x80
	s_mov_b32 m0, s45
	ds_read_b128 v[130:133], v217
	ds_read_b128 v[142:145], v217 offset:1024
	ds_read_b128 v[154:157], v217 offset:2048
	ds_read_b128 v[166:169], v217 offset:3072
	ds_read_b128 v[174:177], v217 offset:4096
	ds_read_b128 v[182:185], v217 offset:5120
	ds_read_b128 v[186:189], v217 offset:6144
	ds_read_b128 v[190:193], v217 offset:7168
	buffer_load_dwordx4 v0, s[8:11], s55 offen lds
	s_mov_b32 m0, s46
	s_nop 0
	buffer_load_dwordx4 v214, s[8:11], s55 offen lds
	s_waitcnt vmcnt(8)
	s_waitcnt lgkmcnt(0)
	s_setprio 3
	s_barrier
	v_mfma_f32_16x16x32_bf16 v[178:181], v[34:37], v[130:133], v[178:181]
	v_mfma_f32_16x16x32_bf16 v[170:173], v[58:61], v[130:133], v[170:173]
	v_mfma_f32_16x16x32_bf16 v[150:153], v[34:37], v[154:157], v[150:153]
	v_mfma_f32_16x16x32_bf16 v[146:149], v[58:61], v[154:157], v[146:149]
	v_mfma_f32_16x16x32_bf16 v[126:129], v[34:37], v[174:177], v[126:129]
	v_mfma_f32_16x16x32_bf16 v[122:125], v[58:61], v[174:177], v[122:125]
	v_mfma_f32_16x16x32_bf16 v[102:105], v[34:37], v[186:189], v[102:105]
	v_mfma_f32_16x16x32_bf16 v[98:101], v[58:61], v[186:189], v[98:101]
	v_mfma_f32_16x16x32_bf16 v[178:181], v[46:49], v[142:145], v[178:181]
	v_mfma_f32_16x16x32_bf16 v[170:173], v[70:73], v[142:145], v[170:173]
	v_mfma_f32_16x16x32_bf16 v[150:153], v[46:49], v[166:169], v[150:153]
	v_mfma_f32_16x16x32_bf16 v[146:149], v[70:73], v[166:169], v[146:149]
	v_mfma_f32_16x16x32_bf16 v[126:129], v[46:49], v[182:185], v[126:129]
	v_mfma_f32_16x16x32_bf16 v[122:125], v[70:73], v[182:185], v[122:125]
	v_mfma_f32_16x16x32_bf16 v[102:105], v[46:49], v[190:193], v[102:105]
	v_mfma_f32_16x16x32_bf16 v[98:101], v[70:73], v[190:193], v[98:101]
	v_mfma_f32_16x16x32_bf16 v[162:165], v[82:85], v[130:133], v[162:165]
	v_mfma_f32_16x16x32_bf16 v[138:141], v[82:85], v[154:157], v[138:141]
	v_mfma_f32_16x16x32_bf16 v[134:137], v[106:109], v[154:157], v[134:137]
	v_mfma_f32_16x16x32_bf16 v[114:117], v[82:85], v[174:177], v[114:117]
	v_mfma_f32_16x16x32_bf16 v[110:113], v[106:109], v[174:177], v[110:113]
	v_mfma_f32_16x16x32_bf16 v[90:93], v[82:85], v[186:189], v[90:93]
	v_mfma_f32_16x16x32_bf16 v[86:89], v[106:109], v[186:189], v[86:89]
	v_mfma_f32_16x16x32_bf16 v[162:165], v[94:97], v[142:145], v[162:165]
	v_mfma_f32_16x16x32_bf16 v[130:133], v[106:109], v[130:133], v[158:161]
	v_mfma_f32_16x16x32_bf16 v[138:141], v[94:97], v[166:169], v[138:141]
	v_mfma_f32_16x16x32_bf16 v[134:137], v[118:121], v[166:169], v[134:137]
	v_mfma_f32_16x16x32_bf16 v[114:117], v[94:97], v[182:185], v[114:117]
	v_mfma_f32_16x16x32_bf16 v[110:113], v[118:121], v[182:185], v[110:113]
	v_mfma_f32_16x16x32_bf16 v[90:93], v[94:97], v[190:193], v[90:93]
	v_mfma_f32_16x16x32_bf16 v[86:89], v[118:121], v[190:193], v[86:89]
	v_mfma_f32_16x16x32_bf16 v[130:133], v[118:121], v[142:145], v[130:133]
	s_barrier
	s_setprio 0
	s_mov_b32 m0, s92
	ds_read_b128 v[142:145], v217 offset:16384
	ds_read_b128 v[154:157], v217 offset:17408
	ds_read_b128 v[158:161], v217 offset:18432
	ds_read_b128 v[166:169], v217 offset:19456
	ds_read_b128 v[174:177], v217 offset:20480
	ds_read_b128 v[182:185], v217 offset:21504
	ds_read_b128 v[186:189], v217 offset:22528
	ds_read_b128 v[190:193], v217 offset:23552
	buffer_load_dwordx4 v199, s[12:15], s58 offen lds
	s_mov_b32 m0, s93
	s_add_i32 s61, s58, 0x20000
	buffer_load_dwordx4 v215, s[12:15], s58 offen lds
	s_mov_b32 m0, s94
	s_nop 0
	buffer_load_dwordx4 v199, s[12:15], s61 offen lds
	s_mov_b32 m0, s95
	s_nop 0
	buffer_load_dwordx4 v215, s[12:15], s61 offen lds
	s_mov_b32 m0, s44
	s_nop 0
	buffer_load_dwordx4 v0, s[16:19], s60 offen lds
	s_mov_b32 m0, s36
	s_nop 0
	buffer_load_dwordx4 v214, s[16:19], s60 offen lds
	s_waitcnt vmcnt(8)
	s_waitcnt lgkmcnt(0)
	s_setprio 3
	s_barrier
	v_mfma_f32_16x16x32_bf16 v[78:81], v[34:37], v[142:145], v[78:81]
	v_mfma_f32_16x16x32_bf16 v[74:77], v[58:61], v[142:145], v[74:77]
	v_mfma_f32_16x16x32_bf16 v[54:57], v[34:37], v[158:161], v[54:57]
	v_mfma_f32_16x16x32_bf16 v[50:53], v[58:61], v[158:161], v[50:53]
	v_mfma_f32_16x16x32_bf16 v[30:33], v[34:37], v[174:177], v[30:33]
	v_mfma_f32_16x16x32_bf16 v[26:29], v[58:61], v[174:177], v[26:29]
	v_mfma_f32_16x16x32_bf16 v[14:17], v[34:37], v[186:189], v[14:17]
	v_mfma_f32_16x16x32_bf16 v[10:13], v[58:61], v[186:189], v[10:13]
	v_mfma_f32_16x16x32_bf16 v[78:81], v[46:49], v[154:157], v[78:81]
	v_mfma_f32_16x16x32_bf16 v[74:77], v[70:73], v[154:157], v[74:77]
	v_mfma_f32_16x16x32_bf16 v[54:57], v[46:49], v[166:169], v[54:57]
	v_mfma_f32_16x16x32_bf16 v[50:53], v[70:73], v[166:169], v[50:53]
	v_mfma_f32_16x16x32_bf16 v[30:33], v[46:49], v[182:185], v[30:33]
	v_mfma_f32_16x16x32_bf16 v[26:29], v[70:73], v[182:185], v[26:29]
	v_mfma_f32_16x16x32_bf16 v[14:17], v[46:49], v[190:193], v[14:17]
	v_mfma_f32_16x16x32_bf16 v[10:13], v[70:73], v[190:193], v[10:13]
	v_mfma_f32_16x16x32_bf16 v[42:45], v[82:85], v[158:161], v[42:45]
	v_mfma_f32_16x16x32_bf16 v[38:41], v[106:109], v[158:161], v[38:41]
	v_mfma_f32_16x16x32_bf16 v[22:25], v[82:85], v[174:177], v[22:25]
	v_mfma_f32_16x16x32_bf16 v[18:21], v[106:109], v[174:177], v[18:21]
	v_mfma_f32_16x16x32_bf16 v[6:9], v[82:85], v[186:189], v[6:9]
	v_mfma_f32_16x16x32_bf16 v[2:5], v[106:109], v[186:189], v[2:5]
	v_mfma_f32_16x16x32_bf16 v[34:37], v[82:85], v[142:145], v[66:69]
	v_mfma_f32_16x16x32_bf16 v[46:49], v[106:109], v[142:145], v[62:65]
	v_mfma_f32_16x16x32_bf16 v[42:45], v[94:97], v[166:169], v[42:45]
	v_mfma_f32_16x16x32_bf16 v[38:41], v[118:121], v[166:169], v[38:41]
	v_mfma_f32_16x16x32_bf16 v[22:25], v[94:97], v[182:185], v[22:25]
	v_mfma_f32_16x16x32_bf16 v[18:21], v[118:121], v[182:185], v[18:21]
	v_mfma_f32_16x16x32_bf16 v[6:9], v[94:97], v[190:193], v[6:9]
	v_mfma_f32_16x16x32_bf16 v[2:5], v[118:121], v[190:193], v[2:5]
	v_mfma_f32_16x16x32_bf16 v[34:37], v[94:97], v[154:157], v[34:37]
	v_mfma_f32_16x16x32_bf16 v[46:49], v[118:121], v[154:157], v[46:49]
	s_barrier
; #define PG8_STAGE(bufoff, gbase, voff) do { const Src _g = (gbase); _Pragma("unroll") for (int _i = 0; _i < 2; ++_i) \
;         __builtin_amdgcn_raw_ptr_buffer_load_lds(_g.r, (LAS unsigned*)(lds + (bufoff) + ldsw + _i * 8192), 16, (voff)[_i], _g.o, 0, 0); } while (0)
; #define PG8_WAIT_V(n) asm volatile("s_waitcnt vmcnt(" #n ")" ::: "memory")
; template <class Epi, bool ALIGN_EPI, bool SP2, class Hook>
; __device__ __forceinline__ void gemm_phase(LAS unsigned char* lds, const Gemm g, const StaticOrder& S, const Epi& E, Acc& acc, const bool fresh, const Hook& H, const int wave_id) {
;     ...
;         for (int t = t0; t < nt; t += 2) {
;             const bool last = (t == nt - 2);
;             const Src a1 = cA + (size_t)(t + 1) * kstep;
;             const Src a2 = last ? nA : cA + (size_t)(t + 2) * kstep, b2 = last ? nB : cB + (size_t)(t + 2) * kstep;
;             const Src a3 = a2 + kstep, b3 = b2 + kstep;
;             if (last && has_next) H(nxt);
;             if constexpr (SP2) {
;             PG8_TRIP_SP2(PG8_WAIT_V(8));
;             } else {
;             PG8_LDB(B0, 0, 0); PG8_SCHED; PG8_LDA(At, 0, 0); PG8_STAGE(PG8_SA(1, 1), a1 + hstepA, voffA);
;             PG8_WAIT_L(8); PG8_BAR; PG8_WAIT_L(0); PG8_MMA(0, 0, At, B0); PG8_BAR; PG8_SCHED;
;             PG8_LDB(B1, 0, 1); PG8_STAGE(PG8_SB(0, 0), b2, voffB);
;             PG8_BAR; PG8_WAIT_L(0); PG8_MMA(0, 1, At, B1); PG8_BAR;
;             PG8_LDA(At, 0, 1); PG8_STAGE(PG8_SA(0, 0), a2, voffA);
;             PG8_BAR; PG8_WAIT_L(0); PG8_MMA(1, 0, At, B0); PG8_BAR; PG8_SCHED;
;             PG8_STAGE(PG8_SB(0, 1), b2 + hstep, voffB);
;             PG8_WAIT_V(6); PG8_BAR; PG8_MMA(1, 1, At, B1); PG8_BAR;
;             PG8_LDB(B0, 1, 0); PG8_SCHED; PG8_LDA(At, 1, 0); PG8_STAGE(PG8_SA(0, 1), a2 + hstepA, voffA);
;             PG8_WAIT_L(8); PG8_BAR; PG8_WAIT_L(0); PG8_MMA(0, 0, At, B0); PG8_BAR; PG8_SCHED;
;             PG8_LDB(B1, 1, 1); PG8_STAGE(PG8_SB(1, 0), b3, voffB);
;             PG8_BAR; PG8_WAIT_L(0); PG8_MMA(0, 1, At, B1); PG8_BAR;
;             PG8_LDA(At, 1, 1); PG8_STAGE(PG8_SA(1, 0), a3, voffA);
;             PG8_BAR; PG8_WAIT_L(0); PG8_MMA(1, 0, At, B0); PG8_BAR; PG8_SCHED;
;             PG8_STAGE(PG8_SB(1, 1), b3 + hstep, voffB);
;             PG8_WAIT_V(6); PG8_BAR; PG8_MMA(1, 1, At, B1); PG8_BAR;
;             }
;         }
;         if constexpr (ALIGN_EPI) { if (wr == 0) PG8_BAR; }
	s_setprio 0
	v_add_u32_e32 v70, 0x18000, v216
	v_add_u32_e32 v118, 0x1c000, v216
	ds_read_b128 v[58:61], v70
	ds_read_b128 v[62:65], v70 offset:1024
	ds_read_b128 v[66:69], v70 offset:2048
	ds_read_b128 v[70:73], v70 offset:3072
	ds_read_b128 v[82:85], v118
	ds_read_b128 v[94:97], v118 offset:1024
	ds_read_b128 v[106:109], v118 offset:2048
	ds_read_b128 v[118:121], v118 offset:3072
	s_add_i32 s60, s60, 0x20000
	s_mov_b32 m0, s37
	ds_read_b128 v[142:145], v217 offset:32768
	ds_read_b128 v[154:157], v217 offset:33792
	ds_read_b128 v[166:169], v217 offset:34816
	ds_read_b128 v[174:177], v217 offset:35840
	ds_read_b128 v[182:185], v217 offset:36864
	ds_read_b128 v[186:189], v217 offset:37888
	ds_read_b128 v[190:193], v217 offset:38912
	ds_read_b128 v[194:197], v217 offset:39936
	buffer_load_dwordx4 v0, s[16:19], s60 offen lds
	s_mov_b32 m0, s38
	s_nop 0
	buffer_load_dwordx4 v214, s[16:19], s60 offen lds
	s_waitcnt vmcnt(8)
	s_waitcnt lgkmcnt(0)
	s_setprio 3
	s_barrier
	v_mfma_f32_16x16x32_bf16 v[158:161], v[58:61], v[142:145], v[178:181]
	v_mfma_f32_16x16x32_bf16 v[178:181], v[62:65], v[154:157], v[158:161]
	v_mfma_f32_16x16x32_bf16 v[158:161], v[66:69], v[142:145], v[170:173]
	v_mfma_f32_16x16x32_bf16 v[150:153], v[58:61], v[166:169], v[150:153]
	v_mfma_f32_16x16x32_bf16 v[146:149], v[66:69], v[166:169], v[146:149]
	v_mfma_f32_16x16x32_bf16 v[126:129], v[58:61], v[182:185], v[126:129]
	v_mfma_f32_16x16x32_bf16 v[122:125], v[66:69], v[182:185], v[122:125]
	v_mfma_f32_16x16x32_bf16 v[102:105], v[58:61], v[190:193], v[102:105]
	v_mfma_f32_16x16x32_bf16 v[98:101], v[66:69], v[190:193], v[98:101]
	v_mfma_f32_16x16x32_bf16 v[170:173], v[70:73], v[154:157], v[158:161]
	v_mfma_f32_16x16x32_bf16 v[150:153], v[62:65], v[174:177], v[150:153]
	v_mfma_f32_16x16x32_bf16 v[146:149], v[70:73], v[174:177], v[146:149]
	v_mfma_f32_16x16x32_bf16 v[126:129], v[62:65], v[186:189], v[126:129]
	v_mfma_f32_16x16x32_bf16 v[122:125], v[70:73], v[186:189], v[122:125]
	v_mfma_f32_16x16x32_bf16 v[102:105], v[62:65], v[194:197], v[102:105]
	v_mfma_f32_16x16x32_bf16 v[98:101], v[70:73], v[194:197], v[98:101]
	v_mfma_f32_16x16x32_bf16 v[158:161], v[82:85], v[142:145], v[162:165]
	v_mfma_f32_16x16x32_bf16 v[130:133], v[106:109], v[142:145], v[130:133]
	v_mfma_f32_16x16x32_bf16 v[162:165], v[94:97], v[154:157], v[158:161]
	v_mfma_f32_16x16x32_bf16 v[158:161], v[118:121], v[154:157], v[130:133]
	v_mfma_f32_16x16x32_bf16 v[130:133], v[82:85], v[166:169], v[138:141]
	v_mfma_f32_16x16x32_bf16 v[138:141], v[94:97], v[174:177], v[130:133]
	v_mfma_f32_16x16x32_bf16 v[130:133], v[106:109], v[166:169], v[134:137]
	v_mfma_f32_16x16x32_bf16 v[114:117], v[82:85], v[182:185], v[114:117]
	v_mfma_f32_16x16x32_bf16 v[110:113], v[106:109], v[182:185], v[110:113]
	v_mfma_f32_16x16x32_bf16 v[90:93], v[82:85], v[190:193], v[90:93]
	v_mfma_f32_16x16x32_bf16 v[86:89], v[106:109], v[190:193], v[86:89]
	v_mfma_f32_16x16x32_bf16 v[134:137], v[118:121], v[174:177], v[130:133]
	v_mfma_f32_16x16x32_bf16 v[114:117], v[94:97], v[186:189], v[114:117]
	v_mfma_f32_16x16x32_bf16 v[110:113], v[118:121], v[186:189], v[110:113]
	v_mfma_f32_16x16x32_bf16 v[90:93], v[94:97], v[194:197], v[90:93]
	v_mfma_f32_16x16x32_bf16 v[86:89], v[118:121], v[194:197], v[86:89]
	s_barrier
	s_setprio 0
	s_mov_b32 m0, s39
	s_or_b32 s60, s58, 0x80
	ds_read_b128 v[130:133], v217 offset:49152
	ds_read_b128 v[142:145], v217 offset:50176
	ds_read_b128 v[154:157], v217 offset:51200
	ds_read_b128 v[166:169], v217 offset:52224
	ds_read_b128 v[174:177], v217 offset:53248
	ds_read_b128 v[182:185], v217 offset:54272
	ds_read_b128 v[186:189], v217 offset:55296
	ds_read_b128 v[190:193], v217 offset:56320
	buffer_load_dwordx4 v199, s[12:15], s60 offen lds
	s_mov_b32 m0, s40
	s_add_i32 s58, s58, 0x20080
	buffer_load_dwordx4 v215, s[12:15], s60 offen lds
	s_mov_b32 m0, s43
	s_nop 0
	buffer_load_dwordx4 v199, s[12:15], s58 offen lds
	s_mov_b32 m0, s42
	s_nop 0
	buffer_load_dwordx4 v215, s[12:15], s58 offen lds
	s_mov_b32 m0, s41
	s_nop 0
	buffer_load_dwordx4 v0, s[16:19], s59 offen lds
	s_mov_b32 m0, s33
	s_nop 0
	buffer_load_dwordx4 v214, s[16:19], s59 offen lds
	s_waitcnt vmcnt(8)
	s_waitcnt lgkmcnt(0)
	s_setprio 3
	s_barrier
	v_mfma_f32_16x16x32_bf16 v[78:81], v[58:61], v[130:133], v[78:81]
	v_mfma_f32_16x16x32_bf16 v[74:77], v[66:69], v[130:133], v[74:77]
	v_mfma_f32_16x16x32_bf16 v[54:57], v[58:61], v[154:157], v[54:57]
	v_mfma_f32_16x16x32_bf16 v[50:53], v[66:69], v[154:157], v[50:53]
	v_mfma_f32_16x16x32_bf16 v[30:33], v[58:61], v[174:177], v[30:33]
	v_mfma_f32_16x16x32_bf16 v[26:29], v[66:69], v[174:177], v[26:29]
	v_mfma_f32_16x16x32_bf16 v[14:17], v[58:61], v[186:189], v[14:17]
	v_mfma_f32_16x16x32_bf16 v[10:13], v[66:69], v[186:189], v[10:13]
	v_mfma_f32_16x16x32_bf16 v[78:81], v[62:65], v[142:145], v[78:81]
	v_mfma_f32_16x16x32_bf16 v[74:77], v[70:73], v[142:145], v[74:77]
	v_mfma_f32_16x16x32_bf16 v[54:57], v[62:65], v[166:169], v[54:57]
	v_mfma_f32_16x16x32_bf16 v[50:53], v[70:73], v[166:169], v[50:53]
	v_mfma_f32_16x16x32_bf16 v[30:33], v[62:65], v[182:185], v[30:33]
	v_mfma_f32_16x16x32_bf16 v[26:29], v[70:73], v[182:185], v[26:29]
	v_mfma_f32_16x16x32_bf16 v[14:17], v[62:65], v[190:193], v[14:17]
	v_mfma_f32_16x16x32_bf16 v[10:13], v[70:73], v[190:193], v[10:13]
	v_mfma_f32_16x16x32_bf16 v[34:37], v[82:85], v[130:133], v[34:37]
	v_mfma_f32_16x16x32_bf16 v[66:69], v[94:97], v[142:145], v[34:37]
	v_mfma_f32_16x16x32_bf16 v[34:37], v[106:109], v[130:133], v[46:49]
	v_mfma_f32_16x16x32_bf16 v[62:65], v[118:121], v[142:145], v[34:37]
	v_mfma_f32_16x16x32_bf16 v[34:37], v[82:85], v[154:157], v[42:45]
	v_mfma_f32_16x16x32_bf16 v[42:45], v[94:97], v[166:169], v[34:37]
	v_mfma_f32_16x16x32_bf16 v[34:37], v[106:109], v[154:157], v[38:41]
	v_mfma_f32_16x16x32_bf16 v[22:25], v[82:85], v[174:177], v[22:25]
	v_mfma_f32_16x16x32_bf16 v[18:21], v[106:109], v[174:177], v[18:21]
	v_mfma_f32_16x16x32_bf16 v[6:9], v[82:85], v[186:189], v[6:9]
	v_mfma_f32_16x16x32_bf16 v[2:5], v[106:109], v[186:189], v[2:5]
	v_mfma_f32_16x16x32_bf16 v[38:41], v[118:121], v[166:169], v[34:37]
	v_mfma_f32_16x16x32_bf16 v[22:25], v[94:97], v[182:185], v[22:25]
	v_mfma_f32_16x16x32_bf16 v[18:21], v[118:121], v[182:185], v[18:21]
	v_mfma_f32_16x16x32_bf16 v[6:9], v[94:97], v[190:193], v[6:9]
	v_mfma_f32_16x16x32_bf16 v[2:5], v[118:121], v[190:193], v[2:5]
	s_barrier
	s_setprio 0
	s_add_i32 s57, s57, 2
	s_addk_i32 s55, 0x100
	s_addk_i32 s56, 0x100
	s_cmp_gt_u32 s57, 5
	s_cbranch_scc0 .LBB0_903
	v_readlane_b32 s8, v251, 45
	v_readlane_b32 s9, v251, 46
	s_and_b64 vcc, exec, s[8:9]
	s_cbranch_vccz .LBB0_906
	s_barrier

; #define PG8_WAIT_V(n) asm volatile("s_waitcnt vmcnt(" #n ")" ::: "memory")
; template <class Epi, bool ALIGN_EPI, bool SP2, class Hook>
; __device__ __forceinline__ void gemm_phase(LAS unsigned char* lds, const Gemm g, const StaticOrder& S, const Epi& E, Acc& acc, const bool fresh, const Hook& H, const int wave_id) {
;     ...
;         for (int t = t0; t < nt; t += 2) {
;             const bool last = (t == nt - 2);
;             const Src a1 = cA + (size_t)(t + 1) * kstep;
;             const Src a2 = last ? nA : cA + (size_t)(t + 2) * kstep, b2 = last ? nB : cB + (size_t)(t + 2) * kstep;
;             const Src a3 = a2 + kstep, b3 = b2 + kstep;
;             if (last && has_next) H(nxt);
;             if constexpr (SP2) {
;             PG8_TRIP_SP2(PG8_WAIT_V(8));
.LBB0_1029:
.LBB0_1030:
	v_add_u32_e32 v0, 0x10000, v230
	s_waitcnt vmcnt(0)
	ds_read_b128 v[130:133], v0
	ds_read_b128 v[134:137], v0 offset:1024
	ds_read_b128 v[138:141], v0 offset:2048
	ds_read_b128 v[142:145], v0 offset:3072
	v_add_u32_e32 v0, 0x14000, v230
	ds_read_b128 v[146:149], v0
	ds_read_b128 v[150:153], v0 offset:1024
	ds_read_b128 v[154:157], v0 offset:2048
	ds_read_b128 v[158:161], v0 offset:3072
	s_lshl_b32 s55, s20, 7
	s_add_i32 s18, s73, s55
	s_and_b64 s[12:13], s[16:17], exec
	s_cselect_b32 s13, s31, s9
	s_cselect_b32 s12, s30, s8
	s_cselect_b32 s15, s35, s11
	s_cselect_b32 s14, s34, s10
	s_cselect_b32 s56, s68, s18
	s_add_i32 s21, s74, s55
	s_and_b64 s[16:17], s[16:17], exec
	s_cselect_b32 s54, s69, s21
	s_cselect_b32 s17, s51, s77
	s_cselect_b32 s16, s50, s76
	s_cselect_b32 s19, s53, s7
	s_cselect_b32 s18, s52, s6
	s_or_b32 s21, s56, 0x80
	s_or_b32 s57, s54, 0x80
	s_add_i32 s55, s55, s75
	s_mov_b32 m0, s45
	ds_read_b128 v[162:165], v231
	ds_read_b128 v[166:169], v231 offset:1024
	ds_read_b128 v[170:173], v231 offset:2048
	ds_read_b128 v[174:177], v231 offset:3072
	ds_read_b128 v[178:181], v231 offset:4096
	ds_read_b128 v[182:185], v231 offset:5120
	ds_read_b128 v[186:189], v231 offset:6144
	ds_read_b128 v[190:193], v231 offset:7168
	buffer_load_dwordx4 v199, s[8:11], s55 offen lds
	s_mov_b32 m0, s46
	s_nop 0
	buffer_load_dwordx4 v228, s[8:11], s55 offen lds
	s_waitcnt vmcnt(8)
	s_waitcnt lgkmcnt(0)
	s_setprio 3
	s_barrier
	v_mfma_f32_16x16x32_bf16 v[126:129], v[130:133], v[162:165], v[126:129]
	v_mfma_f32_16x16x32_bf16 v[122:125], v[138:141], v[162:165], v[122:125]
	v_mfma_f32_16x16x32_bf16 v[118:121], v[130:133], v[170:173], v[118:121]
	v_mfma_f32_16x16x32_bf16 v[114:117], v[138:141], v[170:173], v[114:117]
	v_mfma_f32_16x16x32_bf16 v[110:113], v[130:133], v[178:181], v[110:113]
	v_mfma_f32_16x16x32_bf16 v[106:109], v[138:141], v[178:181], v[106:109]
	v_mfma_f32_16x16x32_bf16 v[102:105], v[130:133], v[186:189], v[102:105]
	v_mfma_f32_16x16x32_bf16 v[98:101], v[138:141], v[186:189], v[98:101]
	v_mfma_f32_16x16x32_bf16 v[126:129], v[134:137], v[166:169], v[126:129]
	v_mfma_f32_16x16x32_bf16 v[122:125], v[142:145], v[166:169], v[122:125]
	v_mfma_f32_16x16x32_bf16 v[118:121], v[134:137], v[174:177], v[118:121]
	v_mfma_f32_16x16x32_bf16 v[114:117], v[142:145], v[174:177], v[114:117]
	v_mfma_f32_16x16x32_bf16 v[110:113], v[134:137], v[182:185], v[110:113]
	v_mfma_f32_16x16x32_bf16 v[106:109], v[142:145], v[182:185], v[106:109]
	v_mfma_f32_16x16x32_bf16 v[102:105], v[134:137], v[190:193], v[102:105]
	v_mfma_f32_16x16x32_bf16 v[98:101], v[142:145], v[190:193], v[98:101]
	v_mfma_f32_16x16x32_bf16 v[94:97], v[146:149], v[162:165], v[94:97]
	v_mfma_f32_16x16x32_bf16 v[90:93], v[154:157], v[162:165], v[90:93]
	v_mfma_f32_16x16x32_bf16 v[86:89], v[146:149], v[170:173], v[86:89]
	v_mfma_f32_16x16x32_bf16 v[82:85], v[154:157], v[170:173], v[82:85]
	v_mfma_f32_16x16x32_bf16 v[78:81], v[146:149], v[178:181], v[78:81]
	v_mfma_f32_16x16x32_bf16 v[74:77], v[154:157], v[178:181], v[74:77]
	v_mfma_f32_16x16x32_bf16 v[70:73], v[146:149], v[186:189], v[70:73]
	v_mfma_f32_16x16x32_bf16 v[66:69], v[154:157], v[186:189], v[66:69]
	v_mfma_f32_16x16x32_bf16 v[94:97], v[150:153], v[166:169], v[94:97]
	v_mfma_f32_16x16x32_bf16 v[90:93], v[158:161], v[166:169], v[90:93]
	v_mfma_f32_16x16x32_bf16 v[86:89], v[150:153], v[174:177], v[86:89]
	v_mfma_f32_16x16x32_bf16 v[82:85], v[158:161], v[174:177], v[82:85]
	v_mfma_f32_16x16x32_bf16 v[78:81], v[150:153], v[182:185], v[78:81]
	v_mfma_f32_16x16x32_bf16 v[74:77], v[158:161], v[182:185], v[74:77]
	v_mfma_f32_16x16x32_bf16 v[70:73], v[150:153], v[190:193], v[70:73]
	v_mfma_f32_16x16x32_bf16 v[66:69], v[158:161], v[190:193], v[66:69]
	s_barrier
	s_setprio 0
	s_mov_b32 m0, s92
	ds_read_b128 v[162:165], v231 offset:16384
	ds_read_b128 v[166:169], v231 offset:17408
	ds_read_b128 v[170:173], v231 offset:18432
	ds_read_b128 v[174:177], v231 offset:19456
	ds_read_b128 v[178:181], v231 offset:20480
	ds_read_b128 v[182:185], v231 offset:21504
	ds_read_b128 v[186:189], v231 offset:22528
	ds_read_b128 v[190:193], v231 offset:23552
	buffer_load_dwordx4 v227, s[16:19], s54 offen lds
	s_mov_b32 m0, s93
	s_add_i32 s55, s54, 0x20000
	buffer_load_dwordx4 v229, s[16:19], s54 offen lds
	s_mov_b32 m0, s94
	s_nop 0
	buffer_load_dwordx4 v227, s[16:19], s55 offen lds
	s_mov_b32 m0, s95
	s_nop 0
	buffer_load_dwordx4 v229, s[16:19], s55 offen lds
	s_mov_b32 m0, s44
	s_nop 0
	buffer_load_dwordx4 v199, s[12:15], s56 offen lds
	s_mov_b32 m0, s36
	s_nop 0
	buffer_load_dwordx4 v228, s[12:15], s56 offen lds
	s_waitcnt vmcnt(8)
	s_waitcnt lgkmcnt(0)
	s_setprio 3
	s_barrier
	v_mfma_f32_16x16x32_bf16 v[62:65], v[130:133], v[162:165], v[62:65]
	v_mfma_f32_16x16x32_bf16 v[58:61], v[138:141], v[162:165], v[58:61]
	v_mfma_f32_16x16x32_bf16 v[54:57], v[130:133], v[170:173], v[54:57]
	v_mfma_f32_16x16x32_bf16 v[50:53], v[138:141], v[170:173], v[50:53]
	v_mfma_f32_16x16x32_bf16 v[46:49], v[130:133], v[178:181], v[46:49]
	v_mfma_f32_16x16x32_bf16 v[42:45], v[138:141], v[178:181], v[42:45]
	v_mfma_f32_16x16x32_bf16 v[38:41], v[130:133], v[186:189], v[38:41]
	v_mfma_f32_16x16x32_bf16 v[34:37], v[138:141], v[186:189], v[34:37]
	v_mfma_f32_16x16x32_bf16 v[62:65], v[134:137], v[166:169], v[62:65]
	v_mfma_f32_16x16x32_bf16 v[58:61], v[142:145], v[166:169], v[58:61]
	v_mfma_f32_16x16x32_bf16 v[54:57], v[134:137], v[174:177], v[54:57]
	v_mfma_f32_16x16x32_bf16 v[50:53], v[142:145], v[174:177], v[50:53]
	v_mfma_f32_16x16x32_bf16 v[46:49], v[134:137], v[182:185], v[46:49]
	v_mfma_f32_16x16x32_bf16 v[42:45], v[142:145], v[182:185], v[42:45]
	v_mfma_f32_16x16x32_bf16 v[38:41], v[134:137], v[190:193], v[38:41]
	v_mfma_f32_16x16x32_bf16 v[34:37], v[142:145], v[190:193], v[34:37]
	v_mfma_f32_16x16x32_bf16 v[30:33], v[146:149], v[162:165], v[30:33]
	v_mfma_f32_16x16x32_bf16 v[26:29], v[154:157], v[162:165], v[26:29]
	v_mfma_f32_16x16x32_bf16 v[22:25], v[146:149], v[170:173], v[22:25]
	v_mfma_f32_16x16x32_bf16 v[18:21], v[154:157], v[170:173], v[18:21]
	v_mfma_f32_16x16x32_bf16 v[14:17], v[146:149], v[178:181], v[14:17]
	v_mfma_f32_16x16x32_bf16 v[10:13], v[154:157], v[178:181], v[10:13]
	v_mfma_f32_16x16x32_bf16 v[6:9], v[146:149], v[186:189], v[6:9]
	v_mfma_f32_16x16x32_bf16 v[2:5], v[154:157], v[186:189], v[2:5]
	v_mfma_f32_16x16x32_bf16 v[30:33], v[150:153], v[166:169], v[30:33]
	v_mfma_f32_16x16x32_bf16 v[26:29], v[158:161], v[166:169], v[26:29]
	v_mfma_f32_16x16x32_bf16 v[22:25], v[150:153], v[174:177], v[22:25]
	v_mfma_f32_16x16x32_bf16 v[18:21], v[158:161], v[174:177], v[18:21]
	v_mfma_f32_16x16x32_bf16 v[14:17], v[150:153], v[182:185], v[14:17]
	v_mfma_f32_16x16x32_bf16 v[10:13], v[158:161], v[182:185], v[10:13]
	v_mfma_f32_16x16x32_bf16 v[6:9], v[150:153], v[190:193], v[6:9]
	v_mfma_f32_16x16x32_bf16 v[2:5], v[158:161], v[190:193], v[2:5]
	s_barrier
	s_setprio 0
	v_add_u32_e32 v0, 0x18000, v230
	ds_read_b128 v[130:133], v0
	ds_read_b128 v[134:137], v0 offset:1024
	ds_read_b128 v[138:141], v0 offset:2048
	ds_read_b128 v[142:145], v0 offset:3072
	v_add_u32_e32 v0, 0x1c000, v230
	ds_read_b128 v[146:149], v0
	ds_read_b128 v[150:153], v0 offset:1024
	ds_read_b128 v[154:157], v0 offset:2048
	ds_read_b128 v[158:161], v0 offset:3072
	s_add_i32 s56, s56, 0x20000
	s_mov_b32 m0, s37
	ds_read_b128 v[162:165], v231 offset:32768
	ds_read_b128 v[166:169], v231 offset:33792
	ds_read_b128 v[170:173], v231 offset:34816
	ds_read_b128 v[174:177], v231 offset:35840
	ds_read_b128 v[178:181], v231 offset:36864
	ds_read_b128 v[182:185], v231 offset:37888
	ds_read_b128 v[186:189], v231 offset:38912
	ds_read_b128 v[190:193], v231 offset:39936
	buffer_load_dwordx4 v199, s[12:15], s56 offen lds
	s_mov_b32 m0, s38
	s_nop 0
	buffer_load_dwordx4 v228, s[12:15], s56 offen lds
	s_waitcnt vmcnt(8)
	s_waitcnt lgkmcnt(0)
	s_setprio 3
	s_barrier
	v_mfma_f32_16x16x32_bf16 v[126:129], v[130:133], v[162:165], v[126:129]
	v_mfma_f32_16x16x32_bf16 v[122:125], v[138:141], v[162:165], v[122:125]
	v_mfma_f32_16x16x32_bf16 v[118:121], v[130:133], v[170:173], v[118:121]
	v_mfma_f32_16x16x32_bf16 v[114:117], v[138:141], v[170:173], v[114:117]
	v_mfma_f32_16x16x32_bf16 v[110:113], v[130:133], v[178:181], v[110:113]
	v_mfma_f32_16x16x32_bf16 v[106:109], v[138:141], v[178:181], v[106:109]
	v_mfma_f32_16x16x32_bf16 v[102:105], v[130:133], v[186:189], v[102:105]
	v_mfma_f32_16x16x32_bf16 v[98:101], v[138:141], v[186:189], v[98:101]
	v_mfma_f32_16x16x32_bf16 v[126:129], v[134:137], v[166:169], v[126:129]
	v_mfma_f32_16x16x32_bf16 v[122:125], v[142:145], v[166:169], v[122:125]
	v_mfma_f32_16x16x32_bf16 v[118:121], v[134:137], v[174:177], v[118:121]
	v_mfma_f32_16x16x32_bf16 v[114:117], v[142:145], v[174:177], v[114:117]
	v_mfma_f32_16x16x32_bf16 v[110:113], v[134:137], v[182:185], v[110:113]
	v_mfma_f32_16x16x32_bf16 v[106:109], v[142:145], v[182:185], v[106:109]
	v_mfma_f32_16x16x32_bf16 v[102:105], v[134:137], v[190:193], v[102:105]
	v_mfma_f32_16x16x32_bf16 v[98:101], v[142:145], v[190:193], v[98:101]
	v_mfma_f32_16x16x32_bf16 v[94:97], v[146:149], v[162:165], v[94:97]
	v_mfma_f32_16x16x32_bf16 v[90:93], v[154:157], v[162:165], v[90:93]
	v_mfma_f32_16x16x32_bf16 v[86:89], v[146:149], v[170:173], v[86:89]
	v_mfma_f32_16x16x32_bf16 v[82:85], v[154:157], v[170:173], v[82:85]
	v_mfma_f32_16x16x32_bf16 v[78:81], v[146:149], v[178:181], v[78:81]
	v_mfma_f32_16x16x32_bf16 v[74:77], v[154:157], v[178:181], v[74:77]
	v_mfma_f32_16x16x32_bf16 v[70:73], v[146:149], v[186:189], v[70:73]
	v_mfma_f32_16x16x32_bf16 v[66:69], v[154:157], v[186:189], v[66:69]
	v_mfma_f32_16x16x32_bf16 v[94:97], v[150:153], v[166:169], v[94:97]
	v_mfma_f32_16x16x32_bf16 v[90:93], v[158:161], v[166:169], v[90:93]
	v_mfma_f32_16x16x32_bf16 v[86:89], v[150:153], v[174:177], v[86:89]
	v_mfma_f32_16x16x32_bf16 v[82:85], v[158:161], v[174:177], v[82:85]
	v_mfma_f32_16x16x32_bf16 v[78:81], v[150:153], v[182:185], v[78:81]
	v_mfma_f32_16x16x32_bf16 v[74:77], v[158:161], v[182:185], v[74:77]
	v_mfma_f32_16x16x32_bf16 v[70:73], v[150:153], v[190:193], v[70:73]
	v_mfma_f32_16x16x32_bf16 v[66:69], v[158:161], v[190:193], v[66:69]
	s_barrier
; #define PG8_WAIT_V(n) asm volatile("s_waitcnt vmcnt(" #n ")" ::: "memory")
; template <class Epi, bool ALIGN_EPI, bool SP2, class Hook>
; __device__ __forceinline__ void gemm_phase(LAS unsigned char* lds, const Gemm g, const StaticOrder& S, const Epi& E, Acc& acc, const bool fresh, const Hook& H, const int wave_id) {
;     ...
;         for (int t = t0; t < nt; t += 2) {
;             const bool last = (t == nt - 2);
;             const Src a1 = cA + (size_t)(t + 1) * kstep;
;             const Src a2 = last ? nA : cA + (size_t)(t + 2) * kstep, b2 = last ? nB : cB + (size_t)(t + 2) * kstep;
;             const Src a3 = a2 + kstep, b3 = b2 + kstep;
;             if (last && has_next) H(nxt);
;             if constexpr (SP2) {
;             PG8_TRIP_SP2(PG8_WAIT_V(8));
	s_setprio 0
	s_mov_b32 m0, s39
	ds_read_b128 v[162:165], v231 offset:49152
	ds_read_b128 v[166:169], v231 offset:50176
	ds_read_b128 v[170:173], v231 offset:51200
	ds_read_b128 v[174:177], v231 offset:52224
	ds_read_b128 v[178:181], v231 offset:53248
	ds_read_b128 v[182:185], v231 offset:54272
	ds_read_b128 v[186:189], v231 offset:55296
	ds_read_b128 v[190:193], v231 offset:56320
	buffer_load_dwordx4 v227, s[16:19], s57 offen lds
	s_mov_b32 m0, s40
	s_add_i32 s54, s54, 0x20080
	buffer_load_dwordx4 v229, s[16:19], s57 offen lds
	s_mov_b32 m0, s43
	s_nop 0
	buffer_load_dwordx4 v227, s[16:19], s54 offen lds
	s_mov_b32 m0, s42
	s_nop 0
	buffer_load_dwordx4 v229, s[16:19], s54 offen lds
	s_mov_b32 m0, s41
	s_nop 0
	buffer_load_dwordx4 v199, s[12:15], s21 offen lds
	s_mov_b32 m0, s33
	s_nop 0
	buffer_load_dwordx4 v228, s[12:15], s21 offen lds
	s_waitcnt vmcnt(8)
	s_waitcnt lgkmcnt(0)
	s_setprio 3
	s_barrier
	v_mfma_f32_16x16x32_bf16 v[62:65], v[130:133], v[162:165], v[62:65]
	v_mfma_f32_16x16x32_bf16 v[58:61], v[138:141], v[162:165], v[58:61]
	v_mfma_f32_16x16x32_bf16 v[54:57], v[130:133], v[170:173], v[54:57]
	v_mfma_f32_16x16x32_bf16 v[50:53], v[138:141], v[170:173], v[50:53]
	v_mfma_f32_16x16x32_bf16 v[46:49], v[130:133], v[178:181], v[46:49]
	v_mfma_f32_16x16x32_bf16 v[42:45], v[138:141], v[178:181], v[42:45]
	v_mfma_f32_16x16x32_bf16 v[38:41], v[130:133], v[186:189], v[38:41]
	v_mfma_f32_16x16x32_bf16 v[34:37], v[138:141], v[186:189], v[34:37]
	v_mfma_f32_16x16x32_bf16 v[62:65], v[134:137], v[166:169], v[62:65]
	v_mfma_f32_16x16x32_bf16 v[58:61], v[142:145], v[166:169], v[58:61]
	v_mfma_f32_16x16x32_bf16 v[54:57], v[134:137], v[174:177], v[54:57]
	v_mfma_f32_16x16x32_bf16 v[50:53], v[142:145], v[174:177], v[50:53]
	v_mfma_f32_16x16x32_bf16 v[46:49], v[134:137], v[182:185], v[46:49]
	v_mfma_f32_16x16x32_bf16 v[42:45], v[142:145], v[182:185], v[42:45]
	v_mfma_f32_16x16x32_bf16 v[38:41], v[134:137], v[190:193], v[38:41]
	v_mfma_f32_16x16x32_bf16 v[34:37], v[142:145], v[190:193], v[34:37]
	v_mfma_f32_16x16x32_bf16 v[30:33], v[146:149], v[162:165], v[30:33]
	v_mfma_f32_16x16x32_bf16 v[26:29], v[154:157], v[162:165], v[26:29]
	v_mfma_f32_16x16x32_bf16 v[22:25], v[146:149], v[170:173], v[22:25]
	v_mfma_f32_16x16x32_bf16 v[18:21], v[154:157], v[170:173], v[18:21]
	v_mfma_f32_16x16x32_bf16 v[14:17], v[146:149], v[178:181], v[14:17]
	v_mfma_f32_16x16x32_bf16 v[10:13], v[154:157], v[178:181], v[10:13]
	v_mfma_f32_16x16x32_bf16 v[6:9], v[146:149], v[186:189], v[6:9]
	v_mfma_f32_16x16x32_bf16 v[2:5], v[154:157], v[186:189], v[2:5]
	v_mfma_f32_16x16x32_bf16 v[30:33], v[150:153], v[166:169], v[30:33]
	v_mfma_f32_16x16x32_bf16 v[26:29], v[158:161], v[166:169], v[26:29]
	v_mfma_f32_16x16x32_bf16 v[22:25], v[150:153], v[174:177], v[22:25]
	v_mfma_f32_16x16x32_bf16 v[18:21], v[158:161], v[174:177], v[18:21]
	v_mfma_f32_16x16x32_bf16 v[14:17], v[150:153], v[182:185], v[14:17]
	v_mfma_f32_16x16x32_bf16 v[10:13], v[158:161], v[182:185], v[10:13]
	v_mfma_f32_16x16x32_bf16 v[6:9], v[150:153], v[190:193], v[6:9]
	v_mfma_f32_16x16x32_bf16 v[2:5], v[158:161], v[190:193], v[2:5]
	s_barrier
	s_setprio 0
	s_add_i32 s12, s20, 2
	s_cmp_gt_u32 s20, 5
	s_cbranch_scc1 .LBB0_1032
	s_mov_b32 s20, s12
	s_branch .LBB0_951

; #define PG8_WAIT_V(n) asm volatile("s_waitcnt vmcnt(" #n ")" ::: "memory")
; template <class Epi, bool ALIGN_EPI, bool SP2, class Hook>
; __device__ __forceinline__ void gemm_phase(LAS unsigned char* lds, const Gemm g, const StaticOrder& S, const Epi& E, Acc& acc, const bool fresh, const Hook& H, const int wave_id) {
;     ...
;         for (int t = t0; t < nt; t += 2) {
;             const bool last = (t == nt - 2);
;             const Src a1 = cA + (size_t)(t + 1) * kstep;
;             const Src a2 = last ? nA : cA + (size_t)(t + 2) * kstep, b2 = last ? nB : cB + (size_t)(t + 2) * kstep;
;             const Src a3 = a2 + kstep, b3 = b2 + kstep;
;             if (last && has_next) H(nxt);
;             if constexpr (SP2) {
;             PG8_TRIP_SP2(PG8_WAIT_V(8));
.LBB0_1235:
	v_add_u32_e32 v142, 0x10000, v161
	v_add_u32_e32 v163, 0x14000, v161
	ds_read_b128 v[130:133], v142
	ds_read_b128 v[134:137], v142 offset:1024
	ds_read_b128 v[138:141], v142 offset:2048
	ds_read_b128 v[142:145], v142 offset:3072
	ds_read_b128 v[146:149], v163
	ds_read_b128 v[150:153], v163 offset:1024
	ds_read_b128 v[154:157], v163 offset:2048
	ds_read_b128 v[164:167], v163 offset:3072
	s_add_i32 s16, s2, 0xfffc0080
	s_cmp_eq_u32 s59, 12
	s_cselect_b32 s62, s55, s16
	s_cselect_b32 s17, s31, s9
	s_cselect_b32 s16, s30, s8
	s_cselect_b32 s19, s35, s51
	s_cselect_b32 s18, s34, s50
	s_cselect_b32 s60, s56, s3
	s_cselect_b32 s20, s26, s12
	s_cselect_b32 s21, s27, s13
	s_cselect_b32 s22, s28, s14
	s_cselect_b32 s23, s29, s15
	s_or_b32 s61, s62, 0x80
	s_mov_b32 m0, s45
	ds_read_b128 v[168:171], v162
	ds_read_b128 v[172:175], v162 offset:1024
	ds_read_b128 v[176:179], v162 offset:2048
	ds_read_b128 v[180:183], v162 offset:3072
	ds_read_b128 v[184:187], v162 offset:4096
	ds_read_b128 v[188:191], v162 offset:5120
	ds_read_b128 v[192:195], v162 offset:6144
	ds_read_b128 v[200:203], v162 offset:7168
	buffer_load_dwordx4 v0, s[12:15], s2 offen lds
	s_mov_b32 m0, s46
	s_nop 0
	buffer_load_dwordx4 v159, s[12:15], s2 offen lds
	s_waitcnt vmcnt(8)
	s_waitcnt lgkmcnt(0)
	s_setprio 3
	s_barrier
	v_mfma_f32_16x16x32_bf16 v[126:129], v[130:133], v[168:171], v[126:129]
	v_mfma_f32_16x16x32_bf16 v[122:125], v[138:141], v[168:171], v[122:125]
	v_mfma_f32_16x16x32_bf16 v[110:113], v[130:133], v[176:179], v[110:113]
	v_mfma_f32_16x16x32_bf16 v[106:109], v[138:141], v[176:179], v[106:109]
	v_mfma_f32_16x16x32_bf16 v[94:97], v[130:133], v[184:187], v[94:97]
	v_mfma_f32_16x16x32_bf16 v[90:93], v[138:141], v[184:187], v[90:93]
	v_mfma_f32_16x16x32_bf16 v[78:81], v[130:133], v[192:195], v[78:81]
	v_mfma_f32_16x16x32_bf16 v[74:77], v[138:141], v[192:195], v[74:77]
	v_mfma_f32_16x16x32_bf16 v[126:129], v[134:137], v[172:175], v[126:129]
	v_mfma_f32_16x16x32_bf16 v[122:125], v[142:145], v[172:175], v[122:125]
	v_mfma_f32_16x16x32_bf16 v[110:113], v[134:137], v[180:183], v[110:113]
	v_mfma_f32_16x16x32_bf16 v[106:109], v[142:145], v[180:183], v[106:109]
	v_mfma_f32_16x16x32_bf16 v[94:97], v[134:137], v[188:191], v[94:97]
	v_mfma_f32_16x16x32_bf16 v[90:93], v[142:145], v[188:191], v[90:93]
	v_mfma_f32_16x16x32_bf16 v[78:81], v[134:137], v[200:203], v[78:81]
	v_mfma_f32_16x16x32_bf16 v[74:77], v[142:145], v[200:203], v[74:77]
	v_mfma_f32_16x16x32_bf16 v[118:121], v[146:149], v[168:171], v[118:121]
	v_mfma_f32_16x16x32_bf16 v[114:117], v[154:157], v[168:171], v[114:117]
	v_mfma_f32_16x16x32_bf16 v[102:105], v[146:149], v[176:179], v[102:105]
	v_mfma_f32_16x16x32_bf16 v[98:101], v[154:157], v[176:179], v[98:101]
	v_mfma_f32_16x16x32_bf16 v[86:89], v[146:149], v[184:187], v[86:89]
	v_mfma_f32_16x16x32_bf16 v[82:85], v[154:157], v[184:187], v[82:85]
	v_mfma_f32_16x16x32_bf16 v[70:73], v[146:149], v[192:195], v[70:73]
	v_mfma_f32_16x16x32_bf16 v[66:69], v[154:157], v[192:195], v[66:69]
	v_mfma_f32_16x16x32_bf16 v[118:121], v[150:153], v[172:175], v[118:121]
	v_mfma_f32_16x16x32_bf16 v[114:117], v[164:167], v[172:175], v[114:117]
	v_mfma_f32_16x16x32_bf16 v[102:105], v[150:153], v[180:183], v[102:105]
	v_mfma_f32_16x16x32_bf16 v[98:101], v[164:167], v[180:183], v[98:101]
	v_mfma_f32_16x16x32_bf16 v[86:89], v[150:153], v[188:191], v[86:89]
	v_mfma_f32_16x16x32_bf16 v[82:85], v[164:167], v[188:191], v[82:85]
	v_mfma_f32_16x16x32_bf16 v[70:73], v[150:153], v[200:203], v[70:73]
	v_mfma_f32_16x16x32_bf16 v[66:69], v[164:167], v[200:203], v[66:69]
	s_barrier
	s_setprio 0
	s_mov_b32 m0, s92
	ds_read_b128 v[168:171], v162 offset:16384
	ds_read_b128 v[172:175], v162 offset:17408
	ds_read_b128 v[176:179], v162 offset:18432
	ds_read_b128 v[180:183], v162 offset:19456
	ds_read_b128 v[184:187], v162 offset:20480
	ds_read_b128 v[188:191], v162 offset:21504
	ds_read_b128 v[192:195], v162 offset:22528
	ds_read_b128 v[200:203], v162 offset:23552
	buffer_load_dwordx4 v158, s[16:19], s60 offen lds
	s_mov_b32 m0, s93
	s_add_i32 s63, s60, 0x40000
	buffer_load_dwordx4 v160, s[16:19], s60 offen lds
	s_mov_b32 m0, s94
	s_nop 0
	buffer_load_dwordx4 v158, s[16:19], s63 offen lds
	s_mov_b32 m0, s95
	s_nop 0
	buffer_load_dwordx4 v160, s[16:19], s63 offen lds
	s_mov_b32 m0, s44
	s_nop 0
	buffer_load_dwordx4 v0, s[20:23], s62 offen lds
	s_mov_b32 m0, s36
	s_nop 0
	buffer_load_dwordx4 v159, s[20:23], s62 offen lds
	s_waitcnt vmcnt(8)
	s_waitcnt lgkmcnt(0)
	s_setprio 3
	s_barrier
	v_mfma_f32_16x16x32_bf16 v[62:65], v[130:133], v[168:171], v[62:65]
	v_mfma_f32_16x16x32_bf16 v[58:61], v[138:141], v[168:171], v[58:61]
	v_mfma_f32_16x16x32_bf16 v[46:49], v[130:133], v[176:179], v[46:49]
	v_mfma_f32_16x16x32_bf16 v[42:45], v[138:141], v[176:179], v[42:45]
	v_mfma_f32_16x16x32_bf16 v[30:33], v[130:133], v[184:187], v[30:33]
	v_mfma_f32_16x16x32_bf16 v[26:29], v[138:141], v[184:187], v[26:29]
	v_mfma_f32_16x16x32_bf16 v[14:17], v[130:133], v[192:195], v[14:17]
	v_mfma_f32_16x16x32_bf16 v[10:13], v[138:141], v[192:195], v[10:13]
	v_mfma_f32_16x16x32_bf16 v[62:65], v[134:137], v[172:175], v[62:65]
	v_mfma_f32_16x16x32_bf16 v[58:61], v[142:145], v[172:175], v[58:61]
	v_mfma_f32_16x16x32_bf16 v[46:49], v[134:137], v[180:183], v[46:49]
	v_mfma_f32_16x16x32_bf16 v[42:45], v[142:145], v[180:183], v[42:45]
	v_mfma_f32_16x16x32_bf16 v[30:33], v[134:137], v[188:191], v[30:33]
	v_mfma_f32_16x16x32_bf16 v[26:29], v[142:145], v[188:191], v[26:29]
	v_mfma_f32_16x16x32_bf16 v[14:17], v[134:137], v[200:203], v[14:17]
	v_mfma_f32_16x16x32_bf16 v[10:13], v[142:145], v[200:203], v[10:13]
	v_mfma_f32_16x16x32_bf16 v[54:57], v[146:149], v[168:171], v[54:57]
	v_mfma_f32_16x16x32_bf16 v[50:53], v[154:157], v[168:171], v[50:53]
	v_mfma_f32_16x16x32_bf16 v[38:41], v[146:149], v[176:179], v[38:41]
	v_mfma_f32_16x16x32_bf16 v[34:37], v[154:157], v[176:179], v[34:37]
	v_mfma_f32_16x16x32_bf16 v[22:25], v[146:149], v[184:187], v[22:25]
	v_mfma_f32_16x16x32_bf16 v[18:21], v[154:157], v[184:187], v[18:21]
	v_mfma_f32_16x16x32_bf16 v[6:9], v[146:149], v[192:195], v[6:9]
	v_mfma_f32_16x16x32_bf16 v[2:5], v[154:157], v[192:195], v[2:5]
	v_mfma_f32_16x16x32_bf16 v[54:57], v[150:153], v[172:175], v[54:57]
	v_mfma_f32_16x16x32_bf16 v[50:53], v[164:167], v[172:175], v[50:53]
	v_mfma_f32_16x16x32_bf16 v[38:41], v[150:153], v[180:183], v[38:41]
	v_mfma_f32_16x16x32_bf16 v[34:37], v[164:167], v[180:183], v[34:37]
	v_mfma_f32_16x16x32_bf16 v[22:25], v[150:153], v[188:191], v[22:25]
	v_mfma_f32_16x16x32_bf16 v[18:21], v[164:167], v[188:191], v[18:21]
	v_mfma_f32_16x16x32_bf16 v[6:9], v[150:153], v[200:203], v[6:9]
	v_mfma_f32_16x16x32_bf16 v[2:5], v[164:167], v[200:203], v[2:5]
	s_barrier
; #define PG8_STAGE(bufoff, gbase, voff) do { const Src _g = (gbase); _Pragma("unroll") for (int _i = 0; _i < 2; ++_i) \
;         __builtin_amdgcn_raw_ptr_buffer_load_lds(_g.r, (LAS unsigned*)(lds + (bufoff) + ldsw + _i * 8192), 16, (voff)[_i], _g.o, 0, 0); } while (0)
; #define PG8_WAIT_V(n) asm volatile("s_waitcnt vmcnt(" #n ")" ::: "memory")
; template <class Epi, bool ALIGN_EPI, bool SP2, class Hook>
; __device__ __forceinline__ void gemm_phase(LAS unsigned char* lds, const Gemm g, const StaticOrder& S, const Epi& E, Acc& acc, const bool fresh, const Hook& H, const int wave_id) {
;     ...
;         for (int t = t0; t < nt; t += 2) {
;             const bool last = (t == nt - 2);
;             const Src a1 = cA + (size_t)(t + 1) * kstep;
;             const Src a2 = last ? nA : cA + (size_t)(t + 2) * kstep, b2 = last ? nB : cB + (size_t)(t + 2) * kstep;
;             const Src a3 = a2 + kstep, b3 = b2 + kstep;
;             if (last && has_next) H(nxt);
;             if constexpr (SP2) {
;             PG8_TRIP_SP2(PG8_WAIT_V(8));
;             } else {
;             PG8_LDB(B0, 0, 0); PG8_SCHED; PG8_LDA(At, 0, 0); PG8_STAGE(PG8_SA(1, 1), a1 + hstepA, voffA);
;             PG8_WAIT_L(8); PG8_BAR; PG8_WAIT_L(0); PG8_MMA(0, 0, At, B0); PG8_BAR; PG8_SCHED;
;             PG8_LDB(B1, 0, 1); PG8_STAGE(PG8_SB(0, 0), b2, voffB);
;             PG8_BAR; PG8_WAIT_L(0); PG8_MMA(0, 1, At, B1); PG8_BAR;
;             PG8_LDA(At, 0, 1); PG8_STAGE(PG8_SA(0, 0), a2, voffA);
;             PG8_BAR; PG8_WAIT_L(0); PG8_MMA(1, 0, At, B0); PG8_BAR; PG8_SCHED;
;             PG8_STAGE(PG8_SB(0, 1), b2 + hstep, voffB);
;             PG8_WAIT_V(6); PG8_BAR; PG8_MMA(1, 1, At, B1); PG8_BAR;
;             PG8_LDB(B0, 1, 0); PG8_SCHED; PG8_LDA(At, 1, 0); PG8_STAGE(PG8_SA(0, 1), a2 + hstepA, voffA);
;             PG8_WAIT_L(8); PG8_BAR; PG8_WAIT_L(0); PG8_MMA(0, 0, At, B0); PG8_BAR; PG8_SCHED;
;             PG8_LDB(B1, 1, 1); PG8_STAGE(PG8_SB(1, 0), b3, voffB);
;             PG8_BAR; PG8_WAIT_L(0); PG8_MMA(0, 1, At, B1); PG8_BAR;
;             PG8_LDA(At, 1, 1); PG8_STAGE(PG8_SA(1, 0), a3, voffA);
;             PG8_BAR; PG8_WAIT_L(0); PG8_MMA(1, 0, At, B0); PG8_BAR; PG8_SCHED;
;             PG8_STAGE(PG8_SB(1, 1), b3 + hstep, voffB);
;             PG8_WAIT_V(6); PG8_BAR; PG8_MMA(1, 1, At, B1); PG8_BAR;
;             }
;         }
;         if constexpr (ALIGN_EPI) { if (wr == 0) PG8_BAR; }
	s_setprio 0
	v_add_u32_e32 v142, 0x18000, v161
	v_add_u32_e32 v163, 0x1c000, v161
	ds_read_b128 v[130:133], v142
	ds_read_b128 v[134:137], v142 offset:1024
	ds_read_b128 v[138:141], v142 offset:2048
	ds_read_b128 v[142:145], v142 offset:3072
	ds_read_b128 v[146:149], v163
	ds_read_b128 v[150:153], v163 offset:1024
	ds_read_b128 v[154:157], v163 offset:2048
	ds_read_b128 v[164:167], v163 offset:3072
	s_add_i32 s62, s62, 0x40000
	s_mov_b32 m0, s37
	ds_read_b128 v[168:171], v162 offset:32768
	ds_read_b128 v[172:175], v162 offset:33792
	ds_read_b128 v[176:179], v162 offset:34816
	ds_read_b128 v[180:183], v162 offset:35840
	ds_read_b128 v[184:187], v162 offset:36864
	ds_read_b128 v[188:191], v162 offset:37888
	ds_read_b128 v[192:195], v162 offset:38912
	ds_read_b128 v[200:203], v162 offset:39936
	buffer_load_dwordx4 v0, s[20:23], s62 offen lds
	s_mov_b32 m0, s38
	s_nop 0
	buffer_load_dwordx4 v159, s[20:23], s62 offen lds
	s_waitcnt vmcnt(8)
	s_waitcnt lgkmcnt(0)
	s_setprio 3
	s_barrier
	v_mfma_f32_16x16x32_bf16 v[126:129], v[130:133], v[168:171], v[126:129]
	v_mfma_f32_16x16x32_bf16 v[122:125], v[138:141], v[168:171], v[122:125]
	v_mfma_f32_16x16x32_bf16 v[110:113], v[130:133], v[176:179], v[110:113]
	v_mfma_f32_16x16x32_bf16 v[106:109], v[138:141], v[176:179], v[106:109]
	v_mfma_f32_16x16x32_bf16 v[94:97], v[130:133], v[184:187], v[94:97]
	v_mfma_f32_16x16x32_bf16 v[90:93], v[138:141], v[184:187], v[90:93]
	v_mfma_f32_16x16x32_bf16 v[78:81], v[130:133], v[192:195], v[78:81]
	v_mfma_f32_16x16x32_bf16 v[74:77], v[138:141], v[192:195], v[74:77]
	v_mfma_f32_16x16x32_bf16 v[126:129], v[134:137], v[172:175], v[126:129]
	v_mfma_f32_16x16x32_bf16 v[122:125], v[142:145], v[172:175], v[122:125]
	v_mfma_f32_16x16x32_bf16 v[110:113], v[134:137], v[180:183], v[110:113]
	v_mfma_f32_16x16x32_bf16 v[106:109], v[142:145], v[180:183], v[106:109]
	v_mfma_f32_16x16x32_bf16 v[94:97], v[134:137], v[188:191], v[94:97]
	v_mfma_f32_16x16x32_bf16 v[90:93], v[142:145], v[188:191], v[90:93]
	v_mfma_f32_16x16x32_bf16 v[78:81], v[134:137], v[200:203], v[78:81]
	v_mfma_f32_16x16x32_bf16 v[74:77], v[142:145], v[200:203], v[74:77]
	v_mfma_f32_16x16x32_bf16 v[118:121], v[146:149], v[168:171], v[118:121]
	v_mfma_f32_16x16x32_bf16 v[114:117], v[154:157], v[168:171], v[114:117]
	v_mfma_f32_16x16x32_bf16 v[102:105], v[146:149], v[176:179], v[102:105]
	v_mfma_f32_16x16x32_bf16 v[98:101], v[154:157], v[176:179], v[98:101]
	v_mfma_f32_16x16x32_bf16 v[86:89], v[146:149], v[184:187], v[86:89]
	v_mfma_f32_16x16x32_bf16 v[82:85], v[154:157], v[184:187], v[82:85]
	v_mfma_f32_16x16x32_bf16 v[70:73], v[146:149], v[192:195], v[70:73]
	v_mfma_f32_16x16x32_bf16 v[66:69], v[154:157], v[192:195], v[66:69]
	v_mfma_f32_16x16x32_bf16 v[118:121], v[150:153], v[172:175], v[118:121]
	v_mfma_f32_16x16x32_bf16 v[114:117], v[164:167], v[172:175], v[114:117]
	v_mfma_f32_16x16x32_bf16 v[102:105], v[150:153], v[180:183], v[102:105]
	v_mfma_f32_16x16x32_bf16 v[98:101], v[164:167], v[180:183], v[98:101]
	v_mfma_f32_16x16x32_bf16 v[86:89], v[150:153], v[188:191], v[86:89]
	v_mfma_f32_16x16x32_bf16 v[82:85], v[164:167], v[188:191], v[82:85]
	v_mfma_f32_16x16x32_bf16 v[70:73], v[150:153], v[200:203], v[70:73]
	v_mfma_f32_16x16x32_bf16 v[66:69], v[164:167], v[200:203], v[66:69]
	s_barrier
	s_setprio 0
	s_mov_b32 m0, s39
	s_or_b32 s62, s60, 0x80
	ds_read_b128 v[168:171], v162 offset:49152
	ds_read_b128 v[172:175], v162 offset:50176
	ds_read_b128 v[176:179], v162 offset:51200
	ds_read_b128 v[180:183], v162 offset:52224
	ds_read_b128 v[184:187], v162 offset:53248
	ds_read_b128 v[188:191], v162 offset:54272
	ds_read_b128 v[192:195], v162 offset:55296
	ds_read_b128 v[200:203], v162 offset:56320
	buffer_load_dwordx4 v158, s[16:19], s62 offen lds
	s_mov_b32 m0, s40
	s_add_i32 s60, s60, 0x40080
	buffer_load_dwordx4 v160, s[16:19], s62 offen lds
	s_mov_b32 m0, s43
	s_nop 0
	buffer_load_dwordx4 v158, s[16:19], s60 offen lds
	s_mov_b32 m0, s42
	s_nop 0
	buffer_load_dwordx4 v160, s[16:19], s60 offen lds
	s_mov_b32 m0, s41
	s_nop 0
	buffer_load_dwordx4 v0, s[20:23], s61 offen lds
	s_mov_b32 m0, s33
	s_nop 0
	buffer_load_dwordx4 v159, s[20:23], s61 offen lds
	s_waitcnt vmcnt(8)
	s_waitcnt lgkmcnt(0)
	s_setprio 3
	s_barrier
	v_mfma_f32_16x16x32_bf16 v[62:65], v[130:133], v[168:171], v[62:65]
	v_mfma_f32_16x16x32_bf16 v[58:61], v[138:141], v[168:171], v[58:61]
	v_mfma_f32_16x16x32_bf16 v[46:49], v[130:133], v[176:179], v[46:49]
	v_mfma_f32_16x16x32_bf16 v[42:45], v[138:141], v[176:179], v[42:45]
	v_mfma_f32_16x16x32_bf16 v[30:33], v[130:133], v[184:187], v[30:33]
	v_mfma_f32_16x16x32_bf16 v[26:29], v[138:141], v[184:187], v[26:29]
	v_mfma_f32_16x16x32_bf16 v[14:17], v[130:133], v[192:195], v[14:17]
	v_mfma_f32_16x16x32_bf16 v[10:13], v[138:141], v[192:195], v[10:13]
	v_mfma_f32_16x16x32_bf16 v[62:65], v[134:137], v[172:175], v[62:65]
	v_mfma_f32_16x16x32_bf16 v[58:61], v[142:145], v[172:175], v[58:61]
	v_mfma_f32_16x16x32_bf16 v[46:49], v[134:137], v[180:183], v[46:49]
	v_mfma_f32_16x16x32_bf16 v[42:45], v[142:145], v[180:183], v[42:45]
	v_mfma_f32_16x16x32_bf16 v[30:33], v[134:137], v[188:191], v[30:33]
	v_mfma_f32_16x16x32_bf16 v[26:29], v[142:145], v[188:191], v[26:29]
	v_mfma_f32_16x16x32_bf16 v[14:17], v[134:137], v[200:203], v[14:17]
	v_mfma_f32_16x16x32_bf16 v[10:13], v[142:145], v[200:203], v[10:13]
	v_mfma_f32_16x16x32_bf16 v[54:57], v[146:149], v[168:171], v[54:57]
	v_mfma_f32_16x16x32_bf16 v[50:53], v[154:157], v[168:171], v[50:53]
	v_mfma_f32_16x16x32_bf16 v[38:41], v[146:149], v[176:179], v[38:41]
	v_mfma_f32_16x16x32_bf16 v[34:37], v[154:157], v[176:179], v[34:37]
	v_mfma_f32_16x16x32_bf16 v[22:25], v[146:149], v[184:187], v[22:25]
	v_mfma_f32_16x16x32_bf16 v[18:21], v[154:157], v[184:187], v[18:21]
	v_mfma_f32_16x16x32_bf16 v[6:9], v[146:149], v[192:195], v[6:9]
	v_mfma_f32_16x16x32_bf16 v[2:5], v[154:157], v[192:195], v[2:5]
	v_mfma_f32_16x16x32_bf16 v[54:57], v[150:153], v[172:175], v[54:57]
	v_mfma_f32_16x16x32_bf16 v[50:53], v[164:167], v[172:175], v[50:53]
	v_mfma_f32_16x16x32_bf16 v[38:41], v[150:153], v[180:183], v[38:41]
	v_mfma_f32_16x16x32_bf16 v[34:37], v[164:167], v[180:183], v[34:37]
	v_mfma_f32_16x16x32_bf16 v[22:25], v[150:153], v[188:191], v[22:25]
	v_mfma_f32_16x16x32_bf16 v[18:21], v[164:167], v[188:191], v[18:21]
	v_mfma_f32_16x16x32_bf16 v[6:9], v[150:153], v[200:203], v[6:9]
	v_mfma_f32_16x16x32_bf16 v[2:5], v[164:167], v[200:203], v[2:5]
	s_barrier
	s_setprio 0
	s_add_i32 s59, s59, 2
	s_addk_i32 s2, 0x100
	s_addk_i32 s3, 0x100
	s_cmp_gt_u32 s59, 13
	s_cbranch_scc0 .LBB0_1235
	v_readlane_b32 s2, v251, 45
	v_readlane_b32 s3, v251, 46
	s_and_b64 vcc, exec, s[2:3]
	s_cbranch_vccz .LBB0_1238
	s_barrier

; #define PG8_WAIT_V(n) asm volatile("s_waitcnt vmcnt(" #n ")" ::: "memory")
; template <class Epi, bool ALIGN_EPI, bool SP2, class Hook>
; __device__ __forceinline__ void gemm_phase(LAS unsigned char* lds, const Gemm g, const StaticOrder& S, const Epi& E, Acc& acc, const bool fresh, const Hook& H, const int wave_id) {
;     ...
;         if constexpr (SP2 && Epi::NSTORE > 0) {
;             const Src a1 = cA + kstep, a2 = cA + 2 * kstep, b2 = cB + 2 * kstep, a3 = a2 + kstep, b3 = b2 + kstep;
;             if constexpr (Epi::NSTORE == 16) PG8_TRIP_SP2(PG8_WAIT_V(24)); else PG8_TRIP_SP2(PG8_WAIT_V(16));
.LBB0_1452:
	ds_read_b128 v[2:5], v138
	ds_read_b128 v[6:9], v138 offset:1024
	ds_read_b128 v[10:13], v138 offset:2048
	ds_read_b128 v[14:17], v138 offset:3072
	ds_read_b128 v[18:21], v139
	ds_read_b128 v[22:25], v139 offset:1024
	ds_read_b128 v[26:29], v139 offset:2048
	ds_read_b128 v[30:33], v139 offset:3072
	s_or_b32 s3, s50, 0x100
	s_or_b32 s2, s50, 0x180
	s_or_b32 s12, s51, 0x100
	s_or_b32 s13, s50, 0x40080
	s_mov_b32 m0, s45
	ds_read_b128 v[34:37], v137
	ds_read_b128 v[38:41], v137 offset:1024
	ds_read_b128 v[42:45], v137 offset:2048
	ds_read_b128 v[46:49], v137 offset:3072
	ds_read_b128 v[50:53], v137 offset:4096
	ds_read_b128 v[54:57], v137 offset:5120
	ds_read_b128 v[58:61], v137 offset:6144
	ds_read_b128 v[62:65], v137 offset:7168
	buffer_load_dwordx4 v132, s[4:7], s13 offen lds
	s_mov_b32 m0, s46
	s_nop 0
	buffer_load_dwordx4 v134, s[4:7], s13 offen lds
	s_waitcnt vmcnt(16)
	s_waitcnt lgkmcnt(0)
	s_setprio 3
	s_barrier
	v_mfma_f32_16x16x32_bf16 v[90:93], v[2:5], v[58:61], 0
	v_mfma_f32_16x16x32_bf16 v[66:69], v[2:5], v[34:37], 0
	v_mfma_f32_16x16x32_bf16 v[70:73], v[10:13], v[34:37], 0
	v_mfma_f32_16x16x32_bf16 v[74:77], v[2:5], v[42:45], 0
	v_mfma_f32_16x16x32_bf16 v[78:81], v[10:13], v[42:45], 0
	v_mfma_f32_16x16x32_bf16 v[82:85], v[2:5], v[50:53], 0
	v_mfma_f32_16x16x32_bf16 v[86:89], v[10:13], v[50:53], 0
	v_mfma_f32_16x16x32_bf16 v[96:99], v[6:9], v[62:65], v[90:93]
	v_mfma_f32_16x16x32_bf16 v[90:93], v[10:13], v[58:61], 0
	v_mfma_f32_16x16x32_bf16 v[66:69], v[6:9], v[38:41], v[66:69]
	v_mfma_f32_16x16x32_bf16 v[70:73], v[14:17], v[38:41], v[70:73]
	v_mfma_f32_16x16x32_bf16 v[74:77], v[6:9], v[46:49], v[74:77]
	v_mfma_f32_16x16x32_bf16 v[78:81], v[14:17], v[46:49], v[78:81]
	v_mfma_f32_16x16x32_bf16 v[82:85], v[6:9], v[54:57], v[82:85]
	v_mfma_f32_16x16x32_bf16 v[86:89], v[14:17], v[54:57], v[86:89]
	v_mfma_f32_16x16x32_bf16 v[104:107], v[14:17], v[62:65], v[90:93]
	v_mfma_f32_16x16x32_bf16 v[90:93], v[18:21], v[34:37], 0
	v_mfma_f32_16x16x32_bf16 v[34:37], v[26:29], v[34:37], 0
	v_mfma_f32_16x16x32_bf16 v[112:115], v[22:25], v[38:41], v[90:93]
	v_mfma_f32_16x16x32_bf16 v[34:37], v[30:33], v[38:41], v[34:37]
	v_mfma_f32_16x16x32_bf16 v[38:41], v[18:21], v[42:45], 0
	v_mfma_f32_16x16x32_bf16 v[42:45], v[26:29], v[42:45], 0
	v_mfma_f32_16x16x32_bf16 v[38:41], v[22:25], v[46:49], v[38:41]
	v_mfma_f32_16x16x32_bf16 v[42:45], v[30:33], v[46:49], v[42:45]
	v_mfma_f32_16x16x32_bf16 v[46:49], v[18:21], v[50:53], 0
	v_mfma_f32_16x16x32_bf16 v[50:53], v[26:29], v[50:53], 0
	v_mfma_f32_16x16x32_bf16 v[46:49], v[22:25], v[54:57], v[46:49]
	v_mfma_f32_16x16x32_bf16 v[50:53], v[30:33], v[54:57], v[50:53]
	v_mfma_f32_16x16x32_bf16 v[54:57], v[18:21], v[58:61], 0
	v_mfma_f32_16x16x32_bf16 v[58:61], v[26:29], v[58:61], 0
	v_mfma_f32_16x16x32_bf16 v[54:57], v[22:25], v[62:65], v[54:57]
	v_mfma_f32_16x16x32_bf16 v[58:61], v[30:33], v[62:65], v[58:61]
	s_barrier
	s_setprio 0
	s_mov_b32 m0, s92
	ds_read_b128 v[62:65], v137 offset:16384
	ds_read_b128 v[90:93], v137 offset:17408
	ds_read_b128 v[100:103], v137 offset:18432
	ds_read_b128 v[108:111], v137 offset:19456
	ds_read_b128 v[116:119], v137 offset:20480
	ds_read_b128 v[120:123], v137 offset:21504
	ds_read_b128 v[124:127], v137 offset:22528
	ds_read_b128 v[128:131], v137 offset:23552
	buffer_load_dwordx4 v133, s[8:11], s12 offen lds
	s_mov_b32 m0, s93
	s_nop 0
	buffer_load_dwordx4 v135, s[8:11], s12 offen lds
	s_or_b32 s12, s51, 0x40100
	s_mov_b32 m0, s94
	s_nop 0
	buffer_load_dwordx4 v133, s[8:11], s12 offen lds
	s_mov_b32 m0, s95
	s_nop 0
	buffer_load_dwordx4 v135, s[8:11], s12 offen lds
	s_mov_b32 m0, s44
	s_nop 0
	buffer_load_dwordx4 v132, s[4:7], s3 offen lds
	s_mov_b32 m0, s36
	s_nop 0
	buffer_load_dwordx4 v134, s[4:7], s3 offen lds
	s_waitcnt vmcnt(16)
	s_waitcnt lgkmcnt(0)
	s_setprio 3
	s_barrier
	v_mfma_f32_16x16x32_bf16 v[142:145], v[2:5], v[62:65], 0
	v_mfma_f32_16x16x32_bf16 v[150:153], v[2:5], v[100:103], 0
	v_mfma_f32_16x16x32_bf16 v[158:161], v[2:5], v[116:119], 0
	v_mfma_f32_16x16x32_bf16 v[2:5], v[2:5], v[124:127], 0
	v_mfma_f32_16x16x32_bf16 v[142:145], v[6:9], v[90:93], v[142:145]
	v_mfma_f32_16x16x32_bf16 v[150:153], v[6:9], v[108:111], v[150:153]
	v_mfma_f32_16x16x32_bf16 v[158:161], v[6:9], v[120:123], v[158:161]
	v_mfma_f32_16x16x32_bf16 v[2:5], v[6:9], v[128:131], v[2:5]
	v_mfma_f32_16x16x32_bf16 v[6:9], v[10:13], v[124:127], 0
	v_mfma_f32_16x16x32_bf16 v[146:149], v[10:13], v[62:65], 0
	v_mfma_f32_16x16x32_bf16 v[154:157], v[10:13], v[100:103], 0
	v_mfma_f32_16x16x32_bf16 v[162:165], v[10:13], v[116:119], 0
	v_mfma_f32_16x16x32_bf16 v[6:9], v[14:17], v[128:131], v[6:9]
	v_mfma_f32_16x16x32_bf16 v[146:149], v[14:17], v[90:93], v[146:149]
	v_mfma_f32_16x16x32_bf16 v[154:157], v[14:17], v[108:111], v[154:157]
	v_mfma_f32_16x16x32_bf16 v[162:165], v[14:17], v[120:123], v[162:165]
	v_mfma_f32_16x16x32_bf16 v[10:13], v[18:21], v[62:65], 0
	v_mfma_f32_16x16x32_bf16 v[166:169], v[22:25], v[90:93], v[10:13]
	v_mfma_f32_16x16x32_bf16 v[10:13], v[26:29], v[62:65], 0
	v_mfma_f32_16x16x32_bf16 v[170:173], v[30:33], v[90:93], v[10:13]
	v_mfma_f32_16x16x32_bf16 v[10:13], v[18:21], v[100:103], 0
	v_mfma_f32_16x16x32_bf16 v[174:177], v[22:25], v[108:111], v[10:13]
	v_mfma_f32_16x16x32_bf16 v[10:13], v[26:29], v[100:103], 0
	v_mfma_f32_16x16x32_bf16 v[178:181], v[30:33], v[108:111], v[10:13]
	v_mfma_f32_16x16x32_bf16 v[10:13], v[18:21], v[116:119], 0
	v_mfma_f32_16x16x32_bf16 v[182:185], v[22:25], v[120:123], v[10:13]
	v_mfma_f32_16x16x32_bf16 v[10:13], v[26:29], v[116:119], 0
	v_mfma_f32_16x16x32_bf16 v[186:189], v[30:33], v[120:123], v[10:13]
	v_mfma_f32_16x16x32_bf16 v[10:13], v[18:21], v[124:127], 0
	v_mfma_f32_16x16x32_bf16 v[16:19], v[22:25], v[128:131], v[10:13]
	v_mfma_f32_16x16x32_bf16 v[10:13], v[26:29], v[124:127], 0
	v_mfma_f32_16x16x32_bf16 v[190:193], v[30:33], v[128:131], v[10:13]
	s_barrier
	s_setprio 0
	s_nop 4
	ds_read_b128 v[10:13], v140
	ds_read_b128 v[24:27], v140 offset:1024
	ds_read_b128 v[194:197], v140 offset:2048
	ds_read_b128 v[200:203], v140 offset:3072
	ds_read_b128 v[204:207], v141
	ds_read_b128 v[208:211], v141 offset:1024
	ds_read_b128 v[212:215], v141 offset:2048
	ds_read_b128 v[138:141], v141 offset:3072
	s_or_b32 s3, s50, 0x40100
	s_mov_b32 m0, s37
	ds_read_b128 v[20:23], v137 offset:32768
	ds_read_b128 v[28:31], v137 offset:33792
	ds_read_b128 v[216:219], v137 offset:34816
	ds_read_b128 v[220:223], v137 offset:35840
	ds_read_b128 v[228:231], v137 offset:36864
	ds_read_b128 v[232:235], v137 offset:37888
	ds_read_b128 v[236:239], v137 offset:38912
	ds_read_b128 v[240:243], v137 offset:39936
	buffer_load_dwordx4 v132, s[4:7], s3 offen lds
	s_mov_b32 m0, s38
	s_nop 0
	buffer_load_dwordx4 v134, s[4:7], s3 offen lds
	s_waitcnt vmcnt(8)
	s_waitcnt lgkmcnt(0)
	s_setprio 3
	s_barrier
	v_mfma_f32_16x16x32_bf16 v[62:65], v[10:13], v[20:23], v[66:69]
	v_mfma_f32_16x16x32_bf16 v[124:127], v[24:27], v[28:31], v[62:65]
	v_mfma_f32_16x16x32_bf16 v[62:65], v[194:197], v[20:23], v[70:73]
	v_mfma_f32_16x16x32_bf16 v[116:119], v[200:203], v[28:31], v[62:65]
	v_mfma_f32_16x16x32_bf16 v[62:65], v[10:13], v[216:219], v[74:77]
	v_mfma_f32_16x16x32_bf16 v[108:111], v[24:27], v[220:223], v[62:65]
	v_mfma_f32_16x16x32_bf16 v[62:65], v[194:197], v[216:219], v[78:81]
	v_mfma_f32_16x16x32_bf16 v[100:103], v[200:203], v[220:223], v[62:65]
	v_mfma_f32_16x16x32_bf16 v[62:65], v[10:13], v[228:231], v[82:85]
	v_mfma_f32_16x16x32_bf16 v[92:95], v[24:27], v[232:235], v[62:65]
	v_mfma_f32_16x16x32_bf16 v[62:65], v[194:197], v[228:231], v[86:89]
	v_mfma_f32_16x16x32_bf16 v[84:87], v[200:203], v[232:235], v[62:65]
	v_mfma_f32_16x16x32_bf16 v[62:65], v[10:13], v[236:239], v[96:99]
	v_mfma_f32_16x16x32_bf16 v[76:79], v[24:27], v[240:243], v[62:65]
	v_mfma_f32_16x16x32_bf16 v[62:65], v[194:197], v[236:239], v[104:107]
	v_mfma_f32_16x16x32_bf16 v[64:67], v[200:203], v[240:243], v[62:65]
	v_mfma_f32_16x16x32_bf16 v[68:71], v[204:207], v[20:23], v[112:115]
	v_mfma_f32_16x16x32_bf16 v[20:23], v[212:215], v[20:23], v[34:37]
	v_mfma_f32_16x16x32_bf16 v[120:123], v[138:141], v[28:31], v[20:23]
	v_mfma_f32_16x16x32_bf16 v[20:23], v[204:207], v[216:219], v[38:41]
	v_mfma_f32_16x16x32_bf16 v[112:115], v[208:211], v[220:223], v[20:23]
	v_mfma_f32_16x16x32_bf16 v[20:23], v[212:215], v[216:219], v[42:45]
	v_mfma_f32_16x16x32_bf16 v[104:107], v[138:141], v[220:223], v[20:23]
	v_mfma_f32_16x16x32_bf16 v[20:23], v[204:207], v[228:231], v[46:49]
	v_mfma_f32_16x16x32_bf16 v[96:99], v[208:211], v[232:235], v[20:23]
	v_mfma_f32_16x16x32_bf16 v[20:23], v[212:215], v[228:231], v[50:53]
	v_mfma_f32_16x16x32_bf16 v[88:91], v[138:141], v[232:235], v[20:23]
	v_mfma_f32_16x16x32_bf16 v[20:23], v[204:207], v[236:239], v[54:57]
	v_mfma_f32_16x16x32_bf16 v[80:83], v[208:211], v[240:243], v[20:23]
	v_mfma_f32_16x16x32_bf16 v[20:23], v[212:215], v[236:239], v[58:61]
	v_mfma_f32_16x16x32_bf16 v[128:131], v[208:211], v[28:31], v[68:71]
	v_mfma_f32_16x16x32_bf16 v[68:71], v[138:141], v[240:243], v[20:23]
	s_barrier
	s_setprio 0
	s_mov_b32 m0, s39
	s_or_b32 s3, s51, 0x180
	ds_read_b128 v[32:35], v137 offset:49152
	ds_read_b128 v[40:43], v137 offset:50176
	ds_read_b128 v[216:219], v137 offset:51200
	ds_read_b128 v[220:223], v137 offset:52224
	ds_read_b128 v[228:231], v137 offset:53248
	ds_read_b128 v[232:235], v137 offset:54272
	ds_read_b128 v[236:239], v137 offset:55296
	ds_read_b128 v[240:243], v137 offset:56320
	buffer_load_dwordx4 v133, s[8:11], s3 offen lds
	s_mov_b32 m0, s40
	s_nop 0
	buffer_load_dwordx4 v135, s[8:11], s3 offen lds
	s_or_b32 s3, s51, 0x40180
	s_mov_b32 m0, s43
	s_nop 0
	buffer_load_dwordx4 v133, s[8:11], s3 offen lds
	s_mov_b32 m0, s42
	s_nop 0
	buffer_load_dwordx4 v135, s[8:11], s3 offen lds
	s_mov_b32 m0, s41
	s_nop 0
	buffer_load_dwordx4 v132, s[4:7], s2 offen lds
	s_mov_b32 m0, s33
	s_nop 0
	buffer_load_dwordx4 v134, s[4:7], s2 offen lds
	s_waitcnt vmcnt(8)
	s_waitcnt lgkmcnt(0)
	s_setprio 3
	s_barrier
	v_mfma_f32_16x16x32_bf16 v[20:23], v[10:13], v[32:35], v[142:145]
	v_mfma_f32_16x16x32_bf16 v[60:63], v[24:27], v[40:43], v[20:23]
	v_mfma_f32_16x16x32_bf16 v[20:23], v[194:197], v[32:35], v[146:149]
	v_mfma_f32_16x16x32_bf16 v[52:55], v[200:203], v[40:43], v[20:23]
	v_mfma_f32_16x16x32_bf16 v[20:23], v[10:13], v[216:219], v[150:153]
	v_mfma_f32_16x16x32_bf16 v[44:47], v[24:27], v[220:223], v[20:23]
	v_mfma_f32_16x16x32_bf16 v[20:23], v[194:197], v[216:219], v[154:157]
	v_mfma_f32_16x16x32_bf16 v[36:39], v[200:203], v[220:223], v[20:23]
	v_mfma_f32_16x16x32_bf16 v[20:23], v[10:13], v[228:231], v[158:161]
	v_mfma_f32_16x16x32_bf16 v[2:5], v[10:13], v[236:239], v[2:5]
	v_mfma_f32_16x16x32_bf16 v[28:31], v[24:27], v[232:235], v[20:23]
	v_mfma_f32_16x16x32_bf16 v[20:23], v[194:197], v[228:231], v[162:165]
	v_mfma_f32_16x16x32_bf16 v[12:15], v[24:27], v[240:243], v[2:5]
	v_mfma_f32_16x16x32_bf16 v[2:5], v[194:197], v[236:239], v[6:9]
	v_mfma_f32_16x16x32_bf16 v[20:23], v[200:203], v[232:235], v[20:23]
	v_mfma_f32_16x16x32_bf16 v[4:7], v[200:203], v[240:243], v[2:5]
	v_mfma_f32_16x16x32_bf16 v[8:11], v[204:207], v[32:35], v[166:169]
	v_mfma_f32_16x16x32_bf16 v[72:75], v[208:211], v[40:43], v[8:11]
	v_mfma_f32_16x16x32_bf16 v[8:11], v[212:215], v[32:35], v[170:173]
	v_mfma_f32_16x16x32_bf16 v[56:59], v[138:141], v[40:43], v[8:11]
	v_mfma_f32_16x16x32_bf16 v[8:11], v[204:207], v[216:219], v[174:177]
	v_mfma_f32_16x16x32_bf16 v[48:51], v[208:211], v[220:223], v[8:11]
	v_mfma_f32_16x16x32_bf16 v[8:11], v[212:215], v[216:219], v[178:181]
	v_mfma_f32_16x16x32_bf16 v[40:43], v[138:141], v[220:223], v[8:11]
	v_mfma_f32_16x16x32_bf16 v[8:11], v[204:207], v[228:231], v[182:185]
	v_mfma_f32_16x16x32_bf16 v[32:35], v[208:211], v[232:235], v[8:11]
	v_mfma_f32_16x16x32_bf16 v[8:11], v[212:215], v[228:231], v[186:189]
	v_mfma_f32_16x16x32_bf16 v[24:27], v[138:141], v[232:235], v[8:11]
	v_mfma_f32_16x16x32_bf16 v[8:11], v[204:207], v[236:239], v[16:19]
	v_mfma_f32_16x16x32_bf16 v[16:19], v[208:211], v[240:243], v[8:11]
	v_mfma_f32_16x16x32_bf16 v[8:11], v[212:215], v[236:239], v[190:193]
	v_mfma_f32_16x16x32_bf16 v[8:11], v[138:141], v[240:243], v[8:11]
	s_barrier
	s_setprio 0
	s_mov_b64 s[2:3], 0
	v_mov_b64_e32 v[234:235], v[226:227]
	v_mov_b32_e32 v226, v0
	v_mov_b64_e32 v[236:237], v[198:199]
	v_mov_b32_e32 v198, v225

; #define PG8_WAIT_V(n) asm volatile("s_waitcnt vmcnt(" #n ")" ::: "memory")
; template <class Epi, bool ALIGN_EPI, bool SP2, class Hook>
; __device__ __forceinline__ void gemm_phase(LAS unsigned char* lds, const Gemm g, const StaticOrder& S, const Epi& E, Acc& acc, const bool fresh, const Hook& H, const int wave_id) {
;     ...
;         for (int t = t0; t < nt; t += 2) {
;             const bool last = (t == nt - 2);
;             const Src a1 = cA + (size_t)(t + 1) * kstep;
;             const Src a2 = last ? nA : cA + (size_t)(t + 2) * kstep, b2 = last ? nB : cB + (size_t)(t + 2) * kstep;
;             const Src a3 = a2 + kstep, b3 = b2 + kstep;
;             if (last && has_next) H(nxt);
;             if constexpr (SP2) {
;             PG8_TRIP_SP2(PG8_WAIT_V(8));
.LBB0_1461:
	v_add_u32_e32 v138, 0x10000, v136
	v_add_u32_e32 v139, 0x14000, v136
	ds_read_b128 v[140:143], v138
	ds_read_b128 v[144:147], v138 offset:1024
	ds_read_b128 v[148:151], v138 offset:2048
	ds_read_b128 v[152:155], v138 offset:3072
	ds_read_b128 v[156:159], v139
	ds_read_b128 v[160:163], v139 offset:1024
	ds_read_b128 v[164:167], v139 offset:2048
	ds_read_b128 v[168:171], v139 offset:3072
	s_add_i32 s16, s55, 0xfffc0080
	s_cmp_eq_u32 s54, 12
	s_cselect_b32 s59, s50, s16
	s_cselect_b32 s17, s9, s77
	s_cselect_b32 s16, s8, s76
	s_cselect_b32 s19, s11, s29
	s_cselect_b32 s18, s10, s28
	s_cselect_b32 s57, s51, s56
	s_cselect_b32 s20, s4, s12
	s_cselect_b32 s21, s5, s13
	s_cselect_b32 s22, s6, s14
	s_cselect_b32 s23, s7, s15
	s_or_b32 s58, s59, 0x80
	s_mov_b32 m0, s45
	ds_read_b128 v[172:175], v137
	ds_read_b128 v[176:179], v137 offset:1024
	ds_read_b128 v[180:183], v137 offset:2048
	ds_read_b128 v[184:187], v137 offset:3072
	ds_read_b128 v[188:191], v137 offset:4096
	ds_read_b128 v[192:195], v137 offset:5120
	ds_read_b128 v[200:203], v137 offset:6144
	ds_read_b128 v[204:207], v137 offset:7168
	buffer_load_dwordx4 v132, s[12:15], s55 offen lds
	s_mov_b32 m0, s46
	s_nop 0
	buffer_load_dwordx4 v134, s[12:15], s55 offen lds
	s_waitcnt vmcnt(8)
	s_waitcnt lgkmcnt(0)
	s_setprio 3
	s_barrier
	v_mfma_f32_16x16x32_bf16 v[124:127], v[140:143], v[172:175], v[124:127]
	v_mfma_f32_16x16x32_bf16 v[116:119], v[148:151], v[172:175], v[116:119]
	v_mfma_f32_16x16x32_bf16 v[108:111], v[140:143], v[180:183], v[108:111]
	v_mfma_f32_16x16x32_bf16 v[100:103], v[148:151], v[180:183], v[100:103]
	v_mfma_f32_16x16x32_bf16 v[92:95], v[140:143], v[188:191], v[92:95]
	v_mfma_f32_16x16x32_bf16 v[84:87], v[148:151], v[188:191], v[84:87]
	v_mfma_f32_16x16x32_bf16 v[76:79], v[140:143], v[200:203], v[76:79]
	v_mfma_f32_16x16x32_bf16 v[64:67], v[148:151], v[200:203], v[64:67]
	v_mfma_f32_16x16x32_bf16 v[124:127], v[144:147], v[176:179], v[124:127]
	v_mfma_f32_16x16x32_bf16 v[116:119], v[152:155], v[176:179], v[116:119]
	v_mfma_f32_16x16x32_bf16 v[108:111], v[144:147], v[184:187], v[108:111]
	v_mfma_f32_16x16x32_bf16 v[100:103], v[152:155], v[184:187], v[100:103]
	v_mfma_f32_16x16x32_bf16 v[92:95], v[144:147], v[192:195], v[92:95]
	v_mfma_f32_16x16x32_bf16 v[84:87], v[152:155], v[192:195], v[84:87]
	v_mfma_f32_16x16x32_bf16 v[76:79], v[144:147], v[204:207], v[76:79]
	v_mfma_f32_16x16x32_bf16 v[64:67], v[152:155], v[204:207], v[64:67]
	v_mfma_f32_16x16x32_bf16 v[128:131], v[156:159], v[172:175], v[128:131]
	v_mfma_f32_16x16x32_bf16 v[120:123], v[164:167], v[172:175], v[120:123]
	v_mfma_f32_16x16x32_bf16 v[112:115], v[156:159], v[180:183], v[112:115]
	v_mfma_f32_16x16x32_bf16 v[104:107], v[164:167], v[180:183], v[104:107]
	v_mfma_f32_16x16x32_bf16 v[96:99], v[156:159], v[188:191], v[96:99]
	v_mfma_f32_16x16x32_bf16 v[88:91], v[164:167], v[188:191], v[88:91]
	v_mfma_f32_16x16x32_bf16 v[80:83], v[156:159], v[200:203], v[80:83]
	v_mfma_f32_16x16x32_bf16 v[68:71], v[164:167], v[200:203], v[68:71]
	v_mfma_f32_16x16x32_bf16 v[128:131], v[160:163], v[176:179], v[128:131]
	v_mfma_f32_16x16x32_bf16 v[120:123], v[168:171], v[176:179], v[120:123]
	v_mfma_f32_16x16x32_bf16 v[112:115], v[160:163], v[184:187], v[112:115]
	v_mfma_f32_16x16x32_bf16 v[104:107], v[168:171], v[184:187], v[104:107]
	v_mfma_f32_16x16x32_bf16 v[96:99], v[160:163], v[192:195], v[96:99]
	v_mfma_f32_16x16x32_bf16 v[88:91], v[168:171], v[192:195], v[88:91]
	v_mfma_f32_16x16x32_bf16 v[80:83], v[160:163], v[204:207], v[80:83]
	v_mfma_f32_16x16x32_bf16 v[68:71], v[168:171], v[204:207], v[68:71]
	s_barrier
	s_setprio 0
	s_mov_b32 m0, s92
	ds_read_b128 v[172:175], v137 offset:16384
	ds_read_b128 v[176:179], v137 offset:17408
	ds_read_b128 v[180:183], v137 offset:18432
	ds_read_b128 v[184:187], v137 offset:19456
	ds_read_b128 v[188:191], v137 offset:20480
	ds_read_b128 v[192:195], v137 offset:21504
	ds_read_b128 v[200:203], v137 offset:22528
	ds_read_b128 v[204:207], v137 offset:23552
	buffer_load_dwordx4 v133, s[16:19], s57 offen lds
	s_mov_b32 m0, s93
	s_add_i32 s60, s57, 0x40000
	buffer_load_dwordx4 v135, s[16:19], s57 offen lds
	s_mov_b32 m0, s94
	s_nop 0
	buffer_load_dwordx4 v133, s[16:19], s60 offen lds
	s_mov_b32 m0, s95
	s_nop 0
	buffer_load_dwordx4 v135, s[16:19], s60 offen lds
	s_mov_b32 m0, s44
	s_nop 0
	buffer_load_dwordx4 v132, s[20:23], s59 offen lds
	s_mov_b32 m0, s36
	s_nop 0
	buffer_load_dwordx4 v134, s[20:23], s59 offen lds
	s_waitcnt vmcnt(8)
	s_waitcnt lgkmcnt(0)
	s_setprio 3
	s_barrier
	v_mfma_f32_16x16x32_bf16 v[60:63], v[140:143], v[172:175], v[60:63]
	v_mfma_f32_16x16x32_bf16 v[52:55], v[148:151], v[172:175], v[52:55]
	v_mfma_f32_16x16x32_bf16 v[44:47], v[140:143], v[180:183], v[44:47]
	v_mfma_f32_16x16x32_bf16 v[36:39], v[148:151], v[180:183], v[36:39]
	v_mfma_f32_16x16x32_bf16 v[28:31], v[140:143], v[188:191], v[28:31]
	v_mfma_f32_16x16x32_bf16 v[20:23], v[148:151], v[188:191], v[20:23]
	v_mfma_f32_16x16x32_bf16 v[12:15], v[140:143], v[200:203], v[12:15]
	v_mfma_f32_16x16x32_bf16 v[2:5], v[148:151], v[200:203], v[4:7]
	v_mfma_f32_16x16x32_bf16 v[60:63], v[144:147], v[176:179], v[60:63]
	v_mfma_f32_16x16x32_bf16 v[52:55], v[152:155], v[176:179], v[52:55]
	v_mfma_f32_16x16x32_bf16 v[44:47], v[144:147], v[184:187], v[44:47]
	v_mfma_f32_16x16x32_bf16 v[36:39], v[152:155], v[184:187], v[36:39]
	v_mfma_f32_16x16x32_bf16 v[28:31], v[144:147], v[192:195], v[28:31]
	v_mfma_f32_16x16x32_bf16 v[20:23], v[152:155], v[192:195], v[20:23]
	v_mfma_f32_16x16x32_bf16 v[12:15], v[144:147], v[204:207], v[12:15]
	v_mfma_f32_16x16x32_bf16 v[2:5], v[152:155], v[204:207], v[2:5]
	v_mfma_f32_16x16x32_bf16 v[72:75], v[156:159], v[172:175], v[72:75]
	v_mfma_f32_16x16x32_bf16 v[56:59], v[164:167], v[172:175], v[56:59]
	v_mfma_f32_16x16x32_bf16 v[48:51], v[156:159], v[180:183], v[48:51]
	v_mfma_f32_16x16x32_bf16 v[40:43], v[164:167], v[180:183], v[40:43]
	v_mfma_f32_16x16x32_bf16 v[32:35], v[156:159], v[188:191], v[32:35]
	v_mfma_f32_16x16x32_bf16 v[24:27], v[164:167], v[188:191], v[24:27]
	v_mfma_f32_16x16x32_bf16 v[16:19], v[156:159], v[200:203], v[16:19]
	v_mfma_f32_16x16x32_bf16 v[6:9], v[164:167], v[200:203], v[8:11]
	v_mfma_f32_16x16x32_bf16 v[72:75], v[160:163], v[176:179], v[72:75]
	v_mfma_f32_16x16x32_bf16 v[56:59], v[168:171], v[176:179], v[56:59]
	v_mfma_f32_16x16x32_bf16 v[48:51], v[160:163], v[184:187], v[48:51]
	v_mfma_f32_16x16x32_bf16 v[40:43], v[168:171], v[184:187], v[40:43]
	v_mfma_f32_16x16x32_bf16 v[32:35], v[160:163], v[192:195], v[32:35]
	v_mfma_f32_16x16x32_bf16 v[24:27], v[168:171], v[192:195], v[24:27]
	v_mfma_f32_16x16x32_bf16 v[16:19], v[160:163], v[204:207], v[16:19]
	v_mfma_f32_16x16x32_bf16 v[8:11], v[168:171], v[204:207], v[6:9]
	s_barrier
; #define PG8_WAIT_V(n) asm volatile("s_waitcnt vmcnt(" #n ")" ::: "memory")
; template <class Epi, bool ALIGN_EPI, bool SP2, class Hook>
; __device__ __forceinline__ void gemm_phase(LAS unsigned char* lds, const Gemm g, const StaticOrder& S, const Epi& E, Acc& acc, const bool fresh, const Hook& H, const int wave_id) {
;     ...
;         for (int t = t0; t < nt; t += 2) {
;             const bool last = (t == nt - 2);
;             const Src a1 = cA + (size_t)(t + 1) * kstep;
;             const Src a2 = last ? nA : cA + (size_t)(t + 2) * kstep, b2 = last ? nB : cB + (size_t)(t + 2) * kstep;
;             const Src a3 = a2 + kstep, b3 = b2 + kstep;
;             if (last && has_next) H(nxt);
;             if constexpr (SP2) {
;             PG8_TRIP_SP2(PG8_WAIT_V(8));
	s_setprio 0
	v_add_u32_e32 v140, 0x18000, v136
	v_add_u32_e32 v141, 0x1c000, v136
	ds_read_b128 v[142:145], v140
	ds_read_b128 v[146:149], v140 offset:1024
	ds_read_b128 v[150:153], v140 offset:2048
	ds_read_b128 v[154:157], v140 offset:3072
	ds_read_b128 v[158:161], v141
	ds_read_b128 v[162:165], v141 offset:1024
	ds_read_b128 v[166:169], v141 offset:2048
	ds_read_b128 v[170:173], v141 offset:3072
	s_add_i32 s59, s59, 0x40000
	s_mov_b32 m0, s37
	ds_read_b128 v[174:177], v137 offset:32768
	ds_read_b128 v[178:181], v137 offset:33792
	ds_read_b128 v[182:185], v137 offset:34816
	ds_read_b128 v[186:189], v137 offset:35840
	ds_read_b128 v[190:193], v137 offset:36864
	ds_read_b128 v[194:197], v137 offset:37888
	ds_read_b128 v[200:203], v137 offset:38912
	ds_read_b128 v[204:207], v137 offset:39936
	buffer_load_dwordx4 v132, s[20:23], s59 offen lds
	s_mov_b32 m0, s38
	s_nop 0
	buffer_load_dwordx4 v134, s[20:23], s59 offen lds
	s_waitcnt vmcnt(8)
	s_waitcnt lgkmcnt(0)
	s_setprio 3
	s_barrier
	v_mfma_f32_16x16x32_bf16 v[124:127], v[142:145], v[174:177], v[124:127]
	v_mfma_f32_16x16x32_bf16 v[116:119], v[150:153], v[174:177], v[116:119]
	v_mfma_f32_16x16x32_bf16 v[108:111], v[142:145], v[182:185], v[108:111]
	v_mfma_f32_16x16x32_bf16 v[100:103], v[150:153], v[182:185], v[100:103]
	v_mfma_f32_16x16x32_bf16 v[92:95], v[142:145], v[190:193], v[92:95]
	v_mfma_f32_16x16x32_bf16 v[84:87], v[150:153], v[190:193], v[84:87]
	v_mfma_f32_16x16x32_bf16 v[76:79], v[142:145], v[200:203], v[76:79]
	v_mfma_f32_16x16x32_bf16 v[64:67], v[150:153], v[200:203], v[64:67]
	v_mfma_f32_16x16x32_bf16 v[124:127], v[146:149], v[178:181], v[124:127]
	v_mfma_f32_16x16x32_bf16 v[116:119], v[154:157], v[178:181], v[116:119]
	v_mfma_f32_16x16x32_bf16 v[108:111], v[146:149], v[186:189], v[108:111]
	v_mfma_f32_16x16x32_bf16 v[100:103], v[154:157], v[186:189], v[100:103]
	v_mfma_f32_16x16x32_bf16 v[92:95], v[146:149], v[194:197], v[92:95]
	v_mfma_f32_16x16x32_bf16 v[84:87], v[154:157], v[194:197], v[84:87]
	v_mfma_f32_16x16x32_bf16 v[76:79], v[146:149], v[204:207], v[76:79]
	v_mfma_f32_16x16x32_bf16 v[64:67], v[154:157], v[204:207], v[64:67]
	v_mfma_f32_16x16x32_bf16 v[128:131], v[158:161], v[174:177], v[128:131]
	v_mfma_f32_16x16x32_bf16 v[120:123], v[166:169], v[174:177], v[120:123]
	v_mfma_f32_16x16x32_bf16 v[112:115], v[158:161], v[182:185], v[112:115]
	v_mfma_f32_16x16x32_bf16 v[104:107], v[166:169], v[182:185], v[104:107]
	v_mfma_f32_16x16x32_bf16 v[96:99], v[158:161], v[190:193], v[96:99]
	v_mfma_f32_16x16x32_bf16 v[88:91], v[166:169], v[190:193], v[88:91]
	v_mfma_f32_16x16x32_bf16 v[80:83], v[158:161], v[200:203], v[80:83]
	v_mfma_f32_16x16x32_bf16 v[68:71], v[166:169], v[200:203], v[68:71]
	v_mfma_f32_16x16x32_bf16 v[128:131], v[162:165], v[178:181], v[128:131]
	v_mfma_f32_16x16x32_bf16 v[120:123], v[170:173], v[178:181], v[120:123]
	v_mfma_f32_16x16x32_bf16 v[112:115], v[162:165], v[186:189], v[112:115]
	v_mfma_f32_16x16x32_bf16 v[104:107], v[170:173], v[186:189], v[104:107]
	v_mfma_f32_16x16x32_bf16 v[96:99], v[162:165], v[194:197], v[96:99]
	v_mfma_f32_16x16x32_bf16 v[88:91], v[170:173], v[194:197], v[88:91]
	v_mfma_f32_16x16x32_bf16 v[80:83], v[162:165], v[204:207], v[80:83]
	v_mfma_f32_16x16x32_bf16 v[68:71], v[170:173], v[204:207], v[68:71]
	s_barrier
	s_setprio 0
	s_mov_b32 m0, s39
	s_or_b32 s59, s57, 0x80
	ds_read_b128 v[174:177], v137 offset:49152
	ds_read_b128 v[178:181], v137 offset:50176
	ds_read_b128 v[182:185], v137 offset:51200
	ds_read_b128 v[186:189], v137 offset:52224
	ds_read_b128 v[190:193], v137 offset:53248
	ds_read_b128 v[194:197], v137 offset:54272
	ds_read_b128 v[200:203], v137 offset:55296
	ds_read_b128 v[204:207], v137 offset:56320
	buffer_load_dwordx4 v133, s[16:19], s59 offen lds
	s_mov_b32 m0, s40
	s_add_i32 s57, s57, 0x40080
	buffer_load_dwordx4 v135, s[16:19], s59 offen lds
	s_mov_b32 m0, s43
	s_nop 0
	buffer_load_dwordx4 v133, s[16:19], s57 offen lds
	s_mov_b32 m0, s42
	s_nop 0
	buffer_load_dwordx4 v135, s[16:19], s57 offen lds
	s_mov_b32 m0, s41
	s_nop 0
	buffer_load_dwordx4 v132, s[20:23], s58 offen lds
	s_mov_b32 m0, s33
	s_nop 0
	buffer_load_dwordx4 v134, s[20:23], s58 offen lds
	s_waitcnt vmcnt(8)
	s_waitcnt lgkmcnt(0)
	s_setprio 3
	s_barrier
	v_mfma_f32_16x16x32_bf16 v[60:63], v[142:145], v[174:177], v[60:63]
	v_mfma_f32_16x16x32_bf16 v[52:55], v[150:153], v[174:177], v[52:55]
	v_mfma_f32_16x16x32_bf16 v[44:47], v[142:145], v[182:185], v[44:47]
	v_mfma_f32_16x16x32_bf16 v[36:39], v[150:153], v[182:185], v[36:39]
	v_mfma_f32_16x16x32_bf16 v[28:31], v[142:145], v[190:193], v[28:31]
	v_mfma_f32_16x16x32_bf16 v[20:23], v[150:153], v[190:193], v[20:23]
	v_mfma_f32_16x16x32_bf16 v[12:15], v[142:145], v[200:203], v[12:15]
	v_mfma_f32_16x16x32_bf16 v[2:5], v[150:153], v[200:203], v[2:5]
	v_mfma_f32_16x16x32_bf16 v[60:63], v[146:149], v[178:181], v[60:63]
	v_mfma_f32_16x16x32_bf16 v[52:55], v[154:157], v[178:181], v[52:55]
	v_mfma_f32_16x16x32_bf16 v[44:47], v[146:149], v[186:189], v[44:47]
	v_mfma_f32_16x16x32_bf16 v[36:39], v[154:157], v[186:189], v[36:39]
	v_mfma_f32_16x16x32_bf16 v[28:31], v[146:149], v[194:197], v[28:31]
	v_mfma_f32_16x16x32_bf16 v[20:23], v[154:157], v[194:197], v[20:23]
	v_mfma_f32_16x16x32_bf16 v[12:15], v[146:149], v[204:207], v[12:15]
	v_mfma_f32_16x16x32_bf16 v[4:7], v[154:157], v[204:207], v[2:5]
	v_mfma_f32_16x16x32_bf16 v[72:75], v[158:161], v[174:177], v[72:75]
	v_mfma_f32_16x16x32_bf16 v[56:59], v[166:169], v[174:177], v[56:59]
	v_mfma_f32_16x16x32_bf16 v[48:51], v[158:161], v[182:185], v[48:51]
	v_mfma_f32_16x16x32_bf16 v[40:43], v[166:169], v[182:185], v[40:43]
	v_mfma_f32_16x16x32_bf16 v[32:35], v[158:161], v[190:193], v[32:35]
	v_mfma_f32_16x16x32_bf16 v[24:27], v[166:169], v[190:193], v[24:27]
	v_mfma_f32_16x16x32_bf16 v[16:19], v[158:161], v[200:203], v[16:19]
	v_mfma_f32_16x16x32_bf16 v[8:11], v[166:169], v[200:203], v[8:11]
	v_mfma_f32_16x16x32_bf16 v[72:75], v[162:165], v[178:181], v[72:75]
	v_mfma_f32_16x16x32_bf16 v[56:59], v[170:173], v[178:181], v[56:59]
	v_mfma_f32_16x16x32_bf16 v[48:51], v[162:165], v[186:189], v[48:51]
	v_mfma_f32_16x16x32_bf16 v[40:43], v[170:173], v[186:189], v[40:43]
	v_mfma_f32_16x16x32_bf16 v[32:35], v[162:165], v[194:197], v[32:35]
	v_mfma_f32_16x16x32_bf16 v[24:27], v[170:173], v[194:197], v[24:27]
	v_mfma_f32_16x16x32_bf16 v[16:19], v[162:165], v[204:207], v[16:19]
	v_mfma_f32_16x16x32_bf16 v[8:11], v[170:173], v[204:207], v[8:11]
	s_barrier
	s_setprio 0
	s_add_i32 s54, s54, 2
	s_addk_i32 s55, 0x100
	s_addk_i32 s56, 0x100
	s_cmp_gt_u32 s54, 13
	s_cbranch_scc0 .LBB0_1461
	v_readlane_b32 s12, v251, 45
	v_readlane_b32 s13, v251, 46
	s_and_b64 vcc, exec, s[12:13]
	s_cbranch_vccz .LBB0_1464
	s_barrier

; #define PG8_WAIT_V(n) asm volatile("s_waitcnt vmcnt(" #n ")" ::: "memory")
; template <class Epi, bool ALIGN_EPI, bool SP2, class Hook>
; __device__ __forceinline__ void gemm_phase(LAS unsigned char* lds, const Gemm g, const StaticOrder& S, const Epi& E, Acc& acc, const bool fresh, const Hook& H, const int wave_id) {
;     ...
;         for (int t = t0; t < nt; t += 2) {
;             const bool last = (t == nt - 2);
;             const Src a1 = cA + (size_t)(t + 1) * kstep;
;             const Src a2 = last ? nA : cA + (size_t)(t + 2) * kstep, b2 = last ? nB : cB + (size_t)(t + 2) * kstep;
;             const Src a3 = a2 + kstep, b3 = b2 + kstep;
;             if (last && has_next) H(nxt);
;             if constexpr (SP2) {
;             PG8_TRIP_SP2(PG8_WAIT_V(8));
.LBB0_1572:
	v_add_u32_e32 v142, 0x10000, v161
	v_add_u32_e32 v163, 0x14000, v161
	ds_read_b128 v[130:133], v142
	ds_read_b128 v[134:137], v142 offset:1024
	ds_read_b128 v[138:141], v142 offset:2048
	ds_read_b128 v[142:145], v142 offset:3072
	ds_read_b128 v[146:149], v163
	ds_read_b128 v[150:153], v163 offset:1024
	ds_read_b128 v[154:157], v163 offset:2048
	ds_read_b128 v[164:167], v163 offset:3072
	s_add_i32 s16, s2, 0xfff40080
	s_cmp_eq_u32 s61, 40
	s_cselect_b32 s64, s57, s16
	s_cselect_b32 s17, s35, s9
	s_cselect_b32 s16, s34, s8
	s_cselect_b32 s19, s51, s53
	s_cselect_b32 s18, s50, s52
	s_cselect_b32 s62, s58, s3
	s_cselect_b32 s20, s10, s12
	s_cselect_b32 s21, s11, s13
	s_cselect_b32 s22, s30, s14
	s_cselect_b32 s23, s31, s15
	s_or_b32 s63, s64, 0x80
	s_mov_b32 m0, s45
	ds_read_b128 v[168:171], v162
	ds_read_b128 v[172:175], v162 offset:1024
	ds_read_b128 v[176:179], v162 offset:2048
	ds_read_b128 v[180:183], v162 offset:3072
	ds_read_b128 v[184:187], v162 offset:4096
	ds_read_b128 v[188:191], v162 offset:5120
	ds_read_b128 v[192:195], v162 offset:6144
	ds_read_b128 v[200:203], v162 offset:7168
	buffer_load_dwordx4 v0, s[12:15], s2 offen lds
	s_mov_b32 m0, s46
	s_nop 0
	buffer_load_dwordx4 v159, s[12:15], s2 offen lds
	s_waitcnt vmcnt(8)
	s_waitcnt lgkmcnt(0)
	s_setprio 3
	s_barrier
	v_mfma_f32_16x16x32_bf16 v[126:129], v[130:133], v[168:171], v[126:129]
	v_mfma_f32_16x16x32_bf16 v[122:125], v[138:141], v[168:171], v[122:125]
	v_mfma_f32_16x16x32_bf16 v[110:113], v[130:133], v[176:179], v[110:113]
	v_mfma_f32_16x16x32_bf16 v[106:109], v[138:141], v[176:179], v[106:109]
	v_mfma_f32_16x16x32_bf16 v[94:97], v[130:133], v[184:187], v[94:97]
	v_mfma_f32_16x16x32_bf16 v[90:93], v[138:141], v[184:187], v[90:93]
	v_mfma_f32_16x16x32_bf16 v[78:81], v[130:133], v[192:195], v[78:81]
	v_mfma_f32_16x16x32_bf16 v[74:77], v[138:141], v[192:195], v[74:77]
	v_mfma_f32_16x16x32_bf16 v[126:129], v[134:137], v[172:175], v[126:129]
	v_mfma_f32_16x16x32_bf16 v[122:125], v[142:145], v[172:175], v[122:125]
	v_mfma_f32_16x16x32_bf16 v[110:113], v[134:137], v[180:183], v[110:113]
	v_mfma_f32_16x16x32_bf16 v[106:109], v[142:145], v[180:183], v[106:109]
	v_mfma_f32_16x16x32_bf16 v[94:97], v[134:137], v[188:191], v[94:97]
	v_mfma_f32_16x16x32_bf16 v[90:93], v[142:145], v[188:191], v[90:93]
	v_mfma_f32_16x16x32_bf16 v[78:81], v[134:137], v[200:203], v[78:81]
	v_mfma_f32_16x16x32_bf16 v[74:77], v[142:145], v[200:203], v[74:77]
	v_mfma_f32_16x16x32_bf16 v[118:121], v[146:149], v[168:171], v[118:121]
	v_mfma_f32_16x16x32_bf16 v[114:117], v[154:157], v[168:171], v[114:117]
	v_mfma_f32_16x16x32_bf16 v[102:105], v[146:149], v[176:179], v[102:105]
	v_mfma_f32_16x16x32_bf16 v[98:101], v[154:157], v[176:179], v[98:101]
	v_mfma_f32_16x16x32_bf16 v[86:89], v[146:149], v[184:187], v[86:89]
	v_mfma_f32_16x16x32_bf16 v[82:85], v[154:157], v[184:187], v[82:85]
	v_mfma_f32_16x16x32_bf16 v[70:73], v[146:149], v[192:195], v[70:73]
	v_mfma_f32_16x16x32_bf16 v[66:69], v[154:157], v[192:195], v[66:69]
	v_mfma_f32_16x16x32_bf16 v[118:121], v[150:153], v[172:175], v[118:121]
	v_mfma_f32_16x16x32_bf16 v[114:117], v[164:167], v[172:175], v[114:117]
	v_mfma_f32_16x16x32_bf16 v[102:105], v[150:153], v[180:183], v[102:105]
	v_mfma_f32_16x16x32_bf16 v[98:101], v[164:167], v[180:183], v[98:101]
	v_mfma_f32_16x16x32_bf16 v[86:89], v[150:153], v[188:191], v[86:89]
	v_mfma_f32_16x16x32_bf16 v[82:85], v[164:167], v[188:191], v[82:85]
	v_mfma_f32_16x16x32_bf16 v[70:73], v[150:153], v[200:203], v[70:73]
	v_mfma_f32_16x16x32_bf16 v[66:69], v[164:167], v[200:203], v[66:69]
	s_barrier
	s_setprio 0
	s_mov_b32 m0, s92
	ds_read_b128 v[168:171], v162 offset:16384
	ds_read_b128 v[172:175], v162 offset:17408
	ds_read_b128 v[176:179], v162 offset:18432
	ds_read_b128 v[180:183], v162 offset:19456
	ds_read_b128 v[184:187], v162 offset:20480
	ds_read_b128 v[188:191], v162 offset:21504
	ds_read_b128 v[192:195], v162 offset:22528
	ds_read_b128 v[200:203], v162 offset:23552
	buffer_load_dwordx4 v158, s[16:19], s62 offen lds
	s_mov_b32 m0, s93
	s_add_i32 s65, s62, 0xb0000
	buffer_load_dwordx4 v160, s[16:19], s62 offen lds
	s_mov_b32 m0, s94
	s_nop 0
	buffer_load_dwordx4 v158, s[16:19], s65 offen lds
	s_mov_b32 m0, s95
	s_nop 0
	buffer_load_dwordx4 v160, s[16:19], s65 offen lds
	s_mov_b32 m0, s44
	s_nop 0
	buffer_load_dwordx4 v0, s[20:23], s64 offen lds
	s_mov_b32 m0, s36
	s_nop 0
	buffer_load_dwordx4 v159, s[20:23], s64 offen lds
	s_waitcnt vmcnt(8)
	s_waitcnt lgkmcnt(0)
	s_setprio 3
	s_barrier
	v_mfma_f32_16x16x32_bf16 v[62:65], v[130:133], v[168:171], v[62:65]
	v_mfma_f32_16x16x32_bf16 v[58:61], v[138:141], v[168:171], v[58:61]
	v_mfma_f32_16x16x32_bf16 v[46:49], v[130:133], v[176:179], v[46:49]
	v_mfma_f32_16x16x32_bf16 v[42:45], v[138:141], v[176:179], v[42:45]
	v_mfma_f32_16x16x32_bf16 v[30:33], v[130:133], v[184:187], v[30:33]
	v_mfma_f32_16x16x32_bf16 v[26:29], v[138:141], v[184:187], v[26:29]
	v_mfma_f32_16x16x32_bf16 v[14:17], v[130:133], v[192:195], v[14:17]
	v_mfma_f32_16x16x32_bf16 v[10:13], v[138:141], v[192:195], v[10:13]
	v_mfma_f32_16x16x32_bf16 v[62:65], v[134:137], v[172:175], v[62:65]
	v_mfma_f32_16x16x32_bf16 v[58:61], v[142:145], v[172:175], v[58:61]
	v_mfma_f32_16x16x32_bf16 v[46:49], v[134:137], v[180:183], v[46:49]
	v_mfma_f32_16x16x32_bf16 v[42:45], v[142:145], v[180:183], v[42:45]
	v_mfma_f32_16x16x32_bf16 v[30:33], v[134:137], v[188:191], v[30:33]
	v_mfma_f32_16x16x32_bf16 v[26:29], v[142:145], v[188:191], v[26:29]
	v_mfma_f32_16x16x32_bf16 v[14:17], v[134:137], v[200:203], v[14:17]
	v_mfma_f32_16x16x32_bf16 v[10:13], v[142:145], v[200:203], v[10:13]
	v_mfma_f32_16x16x32_bf16 v[54:57], v[146:149], v[168:171], v[54:57]
	v_mfma_f32_16x16x32_bf16 v[50:53], v[154:157], v[168:171], v[50:53]
	v_mfma_f32_16x16x32_bf16 v[38:41], v[146:149], v[176:179], v[38:41]
	v_mfma_f32_16x16x32_bf16 v[34:37], v[154:157], v[176:179], v[34:37]
	v_mfma_f32_16x16x32_bf16 v[22:25], v[146:149], v[184:187], v[22:25]
	v_mfma_f32_16x16x32_bf16 v[18:21], v[154:157], v[184:187], v[18:21]
	v_mfma_f32_16x16x32_bf16 v[6:9], v[146:149], v[192:195], v[6:9]
	v_mfma_f32_16x16x32_bf16 v[2:5], v[154:157], v[192:195], v[2:5]
	v_mfma_f32_16x16x32_bf16 v[54:57], v[150:153], v[172:175], v[54:57]
	v_mfma_f32_16x16x32_bf16 v[50:53], v[164:167], v[172:175], v[50:53]
	v_mfma_f32_16x16x32_bf16 v[38:41], v[150:153], v[180:183], v[38:41]
	v_mfma_f32_16x16x32_bf16 v[34:37], v[164:167], v[180:183], v[34:37]
	v_mfma_f32_16x16x32_bf16 v[22:25], v[150:153], v[188:191], v[22:25]
	v_mfma_f32_16x16x32_bf16 v[18:21], v[164:167], v[188:191], v[18:21]
	v_mfma_f32_16x16x32_bf16 v[6:9], v[150:153], v[200:203], v[6:9]
	v_mfma_f32_16x16x32_bf16 v[2:5], v[164:167], v[200:203], v[2:5]
	s_barrier
; #define PG8_WAIT_V(n) asm volatile("s_waitcnt vmcnt(" #n ")" ::: "memory")
; template <class Epi, bool ALIGN_EPI, bool SP2, class Hook>
; __device__ __forceinline__ void gemm_phase(LAS unsigned char* lds, const Gemm g, const StaticOrder& S, const Epi& E, Acc& acc, const bool fresh, const Hook& H, const int wave_id) {
;     ...
;         for (int t = t0; t < nt; t += 2) {
;             const bool last = (t == nt - 2);
;             const Src a1 = cA + (size_t)(t + 1) * kstep;
;             const Src a2 = last ? nA : cA + (size_t)(t + 2) * kstep, b2 = last ? nB : cB + (size_t)(t + 2) * kstep;
;             const Src a3 = a2 + kstep, b3 = b2 + kstep;
;             if (last && has_next) H(nxt);
;             if constexpr (SP2) {
;             PG8_TRIP_SP2(PG8_WAIT_V(8));
	s_setprio 0
	v_add_u32_e32 v142, 0x18000, v161
	v_add_u32_e32 v163, 0x1c000, v161
	ds_read_b128 v[130:133], v142
	ds_read_b128 v[134:137], v142 offset:1024
	ds_read_b128 v[138:141], v142 offset:2048
	ds_read_b128 v[142:145], v142 offset:3072
	ds_read_b128 v[146:149], v163
	ds_read_b128 v[150:153], v163 offset:1024
	ds_read_b128 v[154:157], v163 offset:2048
	ds_read_b128 v[164:167], v163 offset:3072
	s_add_i32 s64, s64, 0xc0000
	s_mov_b32 m0, s37
	ds_read_b128 v[168:171], v162 offset:32768
	ds_read_b128 v[172:175], v162 offset:33792
	ds_read_b128 v[176:179], v162 offset:34816
	ds_read_b128 v[180:183], v162 offset:35840
	ds_read_b128 v[184:187], v162 offset:36864
	ds_read_b128 v[188:191], v162 offset:37888
	ds_read_b128 v[192:195], v162 offset:38912
	ds_read_b128 v[200:203], v162 offset:39936
	buffer_load_dwordx4 v0, s[20:23], s64 offen lds
	s_mov_b32 m0, s38
	s_nop 0
	buffer_load_dwordx4 v159, s[20:23], s64 offen lds
	s_waitcnt vmcnt(8)
	s_waitcnt lgkmcnt(0)
	s_setprio 3
	s_barrier
	v_mfma_f32_16x16x32_bf16 v[126:129], v[130:133], v[168:171], v[126:129]
	v_mfma_f32_16x16x32_bf16 v[122:125], v[138:141], v[168:171], v[122:125]
	v_mfma_f32_16x16x32_bf16 v[110:113], v[130:133], v[176:179], v[110:113]
	v_mfma_f32_16x16x32_bf16 v[106:109], v[138:141], v[176:179], v[106:109]
	v_mfma_f32_16x16x32_bf16 v[94:97], v[130:133], v[184:187], v[94:97]
	v_mfma_f32_16x16x32_bf16 v[90:93], v[138:141], v[184:187], v[90:93]
	v_mfma_f32_16x16x32_bf16 v[78:81], v[130:133], v[192:195], v[78:81]
	v_mfma_f32_16x16x32_bf16 v[74:77], v[138:141], v[192:195], v[74:77]
	v_mfma_f32_16x16x32_bf16 v[126:129], v[134:137], v[172:175], v[126:129]
	v_mfma_f32_16x16x32_bf16 v[122:125], v[142:145], v[172:175], v[122:125]
	v_mfma_f32_16x16x32_bf16 v[110:113], v[134:137], v[180:183], v[110:113]
	v_mfma_f32_16x16x32_bf16 v[106:109], v[142:145], v[180:183], v[106:109]
	v_mfma_f32_16x16x32_bf16 v[94:97], v[134:137], v[188:191], v[94:97]
	v_mfma_f32_16x16x32_bf16 v[90:93], v[142:145], v[188:191], v[90:93]
	v_mfma_f32_16x16x32_bf16 v[78:81], v[134:137], v[200:203], v[78:81]
	v_mfma_f32_16x16x32_bf16 v[74:77], v[142:145], v[200:203], v[74:77]
	v_mfma_f32_16x16x32_bf16 v[118:121], v[146:149], v[168:171], v[118:121]
	v_mfma_f32_16x16x32_bf16 v[114:117], v[154:157], v[168:171], v[114:117]
	v_mfma_f32_16x16x32_bf16 v[102:105], v[146:149], v[176:179], v[102:105]
	v_mfma_f32_16x16x32_bf16 v[98:101], v[154:157], v[176:179], v[98:101]
	v_mfma_f32_16x16x32_bf16 v[86:89], v[146:149], v[184:187], v[86:89]
	v_mfma_f32_16x16x32_bf16 v[82:85], v[154:157], v[184:187], v[82:85]
	v_mfma_f32_16x16x32_bf16 v[70:73], v[146:149], v[192:195], v[70:73]
	v_mfma_f32_16x16x32_bf16 v[66:69], v[154:157], v[192:195], v[66:69]
	v_mfma_f32_16x16x32_bf16 v[118:121], v[150:153], v[172:175], v[118:121]
	v_mfma_f32_16x16x32_bf16 v[114:117], v[164:167], v[172:175], v[114:117]
	v_mfma_f32_16x16x32_bf16 v[102:105], v[150:153], v[180:183], v[102:105]
	v_mfma_f32_16x16x32_bf16 v[98:101], v[164:167], v[180:183], v[98:101]
	v_mfma_f32_16x16x32_bf16 v[86:89], v[150:153], v[188:191], v[86:89]
	v_mfma_f32_16x16x32_bf16 v[82:85], v[164:167], v[188:191], v[82:85]
	v_mfma_f32_16x16x32_bf16 v[70:73], v[150:153], v[200:203], v[70:73]
	v_mfma_f32_16x16x32_bf16 v[66:69], v[164:167], v[200:203], v[66:69]
	s_barrier
	s_setprio 0
	s_mov_b32 m0, s39
	s_or_b32 s64, s62, 0x80
	ds_read_b128 v[168:171], v162 offset:49152
	ds_read_b128 v[172:175], v162 offset:50176
	ds_read_b128 v[176:179], v162 offset:51200
	ds_read_b128 v[180:183], v162 offset:52224
	ds_read_b128 v[184:187], v162 offset:53248
	ds_read_b128 v[188:191], v162 offset:54272
	ds_read_b128 v[192:195], v162 offset:55296
	ds_read_b128 v[200:203], v162 offset:56320
	buffer_load_dwordx4 v158, s[16:19], s64 offen lds
	s_mov_b32 m0, s40
	s_add_i32 s62, s62, 0xb0080
	buffer_load_dwordx4 v160, s[16:19], s64 offen lds
	s_mov_b32 m0, s43
	s_nop 0
	buffer_load_dwordx4 v158, s[16:19], s62 offen lds
	s_mov_b32 m0, s42
	s_nop 0
	buffer_load_dwordx4 v160, s[16:19], s62 offen lds
	s_mov_b32 m0, s41
	s_nop 0
	buffer_load_dwordx4 v0, s[20:23], s63 offen lds
	s_mov_b32 m0, s33
	s_nop 0
	buffer_load_dwordx4 v159, s[20:23], s63 offen lds
	s_waitcnt vmcnt(8)
	s_waitcnt lgkmcnt(0)
	s_setprio 3
	s_barrier
	v_mfma_f32_16x16x32_bf16 v[62:65], v[130:133], v[168:171], v[62:65]
	v_mfma_f32_16x16x32_bf16 v[58:61], v[138:141], v[168:171], v[58:61]
	v_mfma_f32_16x16x32_bf16 v[46:49], v[130:133], v[176:179], v[46:49]
	v_mfma_f32_16x16x32_bf16 v[42:45], v[138:141], v[176:179], v[42:45]
	v_mfma_f32_16x16x32_bf16 v[30:33], v[130:133], v[184:187], v[30:33]
	v_mfma_f32_16x16x32_bf16 v[26:29], v[138:141], v[184:187], v[26:29]
	v_mfma_f32_16x16x32_bf16 v[14:17], v[130:133], v[192:195], v[14:17]
	v_mfma_f32_16x16x32_bf16 v[10:13], v[138:141], v[192:195], v[10:13]
	v_mfma_f32_16x16x32_bf16 v[62:65], v[134:137], v[172:175], v[62:65]
	v_mfma_f32_16x16x32_bf16 v[58:61], v[142:145], v[172:175], v[58:61]
	v_mfma_f32_16x16x32_bf16 v[46:49], v[134:137], v[180:183], v[46:49]
	v_mfma_f32_16x16x32_bf16 v[42:45], v[142:145], v[180:183], v[42:45]
	v_mfma_f32_16x16x32_bf16 v[30:33], v[134:137], v[188:191], v[30:33]
	v_mfma_f32_16x16x32_bf16 v[26:29], v[142:145], v[188:191], v[26:29]
	v_mfma_f32_16x16x32_bf16 v[14:17], v[134:137], v[200:203], v[14:17]
	v_mfma_f32_16x16x32_bf16 v[10:13], v[142:145], v[200:203], v[10:13]
	v_mfma_f32_16x16x32_bf16 v[54:57], v[146:149], v[168:171], v[54:57]
	v_mfma_f32_16x16x32_bf16 v[50:53], v[154:157], v[168:171], v[50:53]
	v_mfma_f32_16x16x32_bf16 v[38:41], v[146:149], v[176:179], v[38:41]
	v_mfma_f32_16x16x32_bf16 v[34:37], v[154:157], v[176:179], v[34:37]
	v_mfma_f32_16x16x32_bf16 v[22:25], v[146:149], v[184:187], v[22:25]
	v_mfma_f32_16x16x32_bf16 v[18:21], v[154:157], v[184:187], v[18:21]
	v_mfma_f32_16x16x32_bf16 v[6:9], v[146:149], v[192:195], v[6:9]
	v_mfma_f32_16x16x32_bf16 v[2:5], v[154:157], v[192:195], v[2:5]
	v_mfma_f32_16x16x32_bf16 v[54:57], v[150:153], v[172:175], v[54:57]
	v_mfma_f32_16x16x32_bf16 v[50:53], v[164:167], v[172:175], v[50:53]
	v_mfma_f32_16x16x32_bf16 v[38:41], v[150:153], v[180:183], v[38:41]
	v_mfma_f32_16x16x32_bf16 v[34:37], v[164:167], v[180:183], v[34:37]
	v_mfma_f32_16x16x32_bf16 v[22:25], v[150:153], v[188:191], v[22:25]
	v_mfma_f32_16x16x32_bf16 v[18:21], v[164:167], v[188:191], v[18:21]
	v_mfma_f32_16x16x32_bf16 v[6:9], v[150:153], v[200:203], v[6:9]
	v_mfma_f32_16x16x32_bf16 v[2:5], v[164:167], v[200:203], v[2:5]
	s_barrier
	s_setprio 0
	s_add_i32 s61, s61, 2
	s_addk_i32 s2, 0x100
	s_addk_i32 s3, 0x100
	s_cmp_gt_u32 s61, 41
	s_cbranch_scc0 .LBB0_1572
	v_readlane_b32 s2, v251, 45
	v_readlane_b32 s3, v251, 46
	s_and_b64 vcc, exec, s[2:3]
	s_cbranch_vccz .LBB0_1575
	s_barrier

; #define PG8_WAIT_V(n) asm volatile("s_waitcnt vmcnt(" #n ")" ::: "memory")
; template <class Epi, bool ALIGN_EPI, bool SP2, class Hook>
; __device__ __forceinline__ void gemm_phase(LAS unsigned char* lds, const Gemm g, const StaticOrder& S, const Epi& E, Acc& acc, const bool fresh, const Hook& H, const int wave_id) {
;     ...
;         for (int t = t0; t < nt; t += 2) {
;             const bool last = (t == nt - 2);
;             const Src a1 = cA + (size_t)(t + 1) * kstep;
;             const Src a2 = last ? nA : cA + (size_t)(t + 2) * kstep, b2 = last ? nB : cB + (size_t)(t + 2) * kstep;
;             const Src a3 = a2 + kstep, b3 = b2 + kstep;
;             if (last && has_next) H(nxt);
;             if constexpr (SP2) {
;             PG8_TRIP_SP2(PG8_WAIT_V(8));
.LBB0_1614:
	v_add_u32_e32 v0, 0x10000, v172
	ds_read_b128 v[130:133], v0
	ds_read_b128 v[134:137], v0 offset:1024
	ds_read_b128 v[138:141], v0 offset:2048
	ds_read_b128 v[142:145], v0 offset:3072
	v_add_u32_e32 v0, 0x14000, v172
	ds_read_b128 v[146:149], v0
	ds_read_b128 v[150:153], v0 offset:1024
	ds_read_b128 v[154:157], v0 offset:2048
	ds_read_b128 v[158:161], v0 offset:3072
	s_add_i32 s12, s2, 0xfff40080
	s_cmp_eq_u32 s59, 40
	s_cselect_b32 s62, s55, s12
	s_cselect_b32 s13, s31, s77
	s_cselect_b32 s12, s30, s76
	s_cselect_b32 s15, s35, s51
	s_cselect_b32 s14, s34, s50
	s_cselect_b32 s60, s56, s3
	s_cselect_b32 s16, s20, s8
	s_cselect_b32 s17, s21, s9
	s_cselect_b32 s18, s22, s10
	s_cselect_b32 s19, s23, s11
	s_or_b32 s61, s62, 0x80
	s_mov_b32 m0, s45
	ds_read_b128 v[162:165], v173
	ds_read_b128 v[174:177], v173 offset:1024
	ds_read_b128 v[178:181], v173 offset:2048
	ds_read_b128 v[182:185], v173 offset:3072
	ds_read_b128 v[186:189], v173 offset:4096
	ds_read_b128 v[190:193], v173 offset:5120
	ds_read_b128 v[194:197], v173 offset:6144
	ds_read_b128 v[200:203], v173 offset:7168
	buffer_load_dwordx4 v168, s[8:11], s2 offen lds
	s_mov_b32 m0, s46
	s_nop 0
	buffer_load_dwordx4 v170, s[8:11], s2 offen lds
	s_waitcnt vmcnt(8)
	s_waitcnt lgkmcnt(0)
	s_setprio 3
	s_barrier
	v_mfma_f32_16x16x32_bf16 v[126:129], v[130:133], v[162:165], v[126:129]
	v_mfma_f32_16x16x32_bf16 v[122:125], v[138:141], v[162:165], v[122:125]
	v_mfma_f32_16x16x32_bf16 v[110:113], v[130:133], v[178:181], v[110:113]
	v_mfma_f32_16x16x32_bf16 v[106:109], v[138:141], v[178:181], v[106:109]
	v_mfma_f32_16x16x32_bf16 v[94:97], v[130:133], v[186:189], v[94:97]
	v_mfma_f32_16x16x32_bf16 v[90:93], v[138:141], v[186:189], v[90:93]
	v_mfma_f32_16x16x32_bf16 v[78:81], v[130:133], v[194:197], v[78:81]
	v_mfma_f32_16x16x32_bf16 v[74:77], v[138:141], v[194:197], v[74:77]
	v_mfma_f32_16x16x32_bf16 v[126:129], v[134:137], v[174:177], v[126:129]
	v_mfma_f32_16x16x32_bf16 v[122:125], v[142:145], v[174:177], v[122:125]
	v_mfma_f32_16x16x32_bf16 v[110:113], v[134:137], v[182:185], v[110:113]
	v_mfma_f32_16x16x32_bf16 v[106:109], v[142:145], v[182:185], v[106:109]
	v_mfma_f32_16x16x32_bf16 v[94:97], v[134:137], v[190:193], v[94:97]
	v_mfma_f32_16x16x32_bf16 v[90:93], v[142:145], v[190:193], v[90:93]
	v_mfma_f32_16x16x32_bf16 v[78:81], v[134:137], v[200:203], v[78:81]
	v_mfma_f32_16x16x32_bf16 v[74:77], v[142:145], v[200:203], v[74:77]
	v_mfma_f32_16x16x32_bf16 v[118:121], v[146:149], v[162:165], v[118:121]
	v_mfma_f32_16x16x32_bf16 v[114:117], v[154:157], v[162:165], v[114:117]
	v_mfma_f32_16x16x32_bf16 v[102:105], v[146:149], v[178:181], v[102:105]
	v_mfma_f32_16x16x32_bf16 v[98:101], v[154:157], v[178:181], v[98:101]
	v_mfma_f32_16x16x32_bf16 v[86:89], v[146:149], v[186:189], v[86:89]
	v_mfma_f32_16x16x32_bf16 v[82:85], v[154:157], v[186:189], v[82:85]
	v_mfma_f32_16x16x32_bf16 v[70:73], v[146:149], v[194:197], v[70:73]
	v_mfma_f32_16x16x32_bf16 v[66:69], v[154:157], v[194:197], v[66:69]
	v_mfma_f32_16x16x32_bf16 v[118:121], v[150:153], v[174:177], v[118:121]
	v_mfma_f32_16x16x32_bf16 v[114:117], v[158:161], v[174:177], v[114:117]
	v_mfma_f32_16x16x32_bf16 v[102:105], v[150:153], v[182:185], v[102:105]
	v_mfma_f32_16x16x32_bf16 v[98:101], v[158:161], v[182:185], v[98:101]
	v_mfma_f32_16x16x32_bf16 v[86:89], v[150:153], v[190:193], v[86:89]
	v_mfma_f32_16x16x32_bf16 v[82:85], v[158:161], v[190:193], v[82:85]
	v_mfma_f32_16x16x32_bf16 v[70:73], v[150:153], v[200:203], v[70:73]
	v_mfma_f32_16x16x32_bf16 v[66:69], v[158:161], v[200:203], v[66:69]
	s_barrier
	s_setprio 0
	s_mov_b32 m0, s92
	ds_read_b128 v[162:165], v173 offset:16384
	ds_read_b128 v[174:177], v173 offset:17408
	ds_read_b128 v[178:181], v173 offset:18432
	ds_read_b128 v[182:185], v173 offset:19456
	ds_read_b128 v[186:189], v173 offset:20480
	ds_read_b128 v[190:193], v173 offset:21504
	ds_read_b128 v[194:197], v173 offset:22528
	ds_read_b128 v[200:203], v173 offset:23552
	buffer_load_dwordx4 v169, s[12:15], s60 offen lds
	s_mov_b32 m0, s93
	s_add_i32 s63, s60, 0xb0000
	buffer_load_dwordx4 v171, s[12:15], s60 offen lds
	s_mov_b32 m0, s94
	s_nop 0
	buffer_load_dwordx4 v169, s[12:15], s63 offen lds
	s_mov_b32 m0, s95
	s_nop 0
	buffer_load_dwordx4 v171, s[12:15], s63 offen lds
	s_mov_b32 m0, s44
	s_nop 0
	buffer_load_dwordx4 v168, s[16:19], s62 offen lds
	s_mov_b32 m0, s36
	s_nop 0
	buffer_load_dwordx4 v170, s[16:19], s62 offen lds
	s_waitcnt vmcnt(8)
	s_waitcnt lgkmcnt(0)
	s_setprio 3
	s_barrier
	v_mfma_f32_16x16x32_bf16 v[62:65], v[130:133], v[162:165], v[62:65]
	v_mfma_f32_16x16x32_bf16 v[58:61], v[138:141], v[162:165], v[58:61]
	v_mfma_f32_16x16x32_bf16 v[46:49], v[130:133], v[178:181], v[46:49]
	v_mfma_f32_16x16x32_bf16 v[42:45], v[138:141], v[178:181], v[42:45]
	v_mfma_f32_16x16x32_bf16 v[30:33], v[130:133], v[186:189], v[30:33]
	v_mfma_f32_16x16x32_bf16 v[26:29], v[138:141], v[186:189], v[26:29]
	v_mfma_f32_16x16x32_bf16 v[14:17], v[130:133], v[194:197], v[14:17]
	v_mfma_f32_16x16x32_bf16 v[10:13], v[138:141], v[194:197], v[10:13]
	v_mfma_f32_16x16x32_bf16 v[62:65], v[134:137], v[174:177], v[62:65]
	v_mfma_f32_16x16x32_bf16 v[58:61], v[142:145], v[174:177], v[58:61]
	v_mfma_f32_16x16x32_bf16 v[46:49], v[134:137], v[182:185], v[46:49]
	v_mfma_f32_16x16x32_bf16 v[42:45], v[142:145], v[182:185], v[42:45]
	v_mfma_f32_16x16x32_bf16 v[30:33], v[134:137], v[190:193], v[30:33]
	v_mfma_f32_16x16x32_bf16 v[26:29], v[142:145], v[190:193], v[26:29]
	v_mfma_f32_16x16x32_bf16 v[14:17], v[134:137], v[200:203], v[14:17]
	v_mfma_f32_16x16x32_bf16 v[10:13], v[142:145], v[200:203], v[10:13]
	v_mfma_f32_16x16x32_bf16 v[54:57], v[146:149], v[162:165], v[54:57]
	v_mfma_f32_16x16x32_bf16 v[50:53], v[154:157], v[162:165], v[50:53]
	v_mfma_f32_16x16x32_bf16 v[38:41], v[146:149], v[178:181], v[38:41]
	v_mfma_f32_16x16x32_bf16 v[34:37], v[154:157], v[178:181], v[34:37]
	v_mfma_f32_16x16x32_bf16 v[22:25], v[146:149], v[186:189], v[22:25]
	v_mfma_f32_16x16x32_bf16 v[18:21], v[154:157], v[186:189], v[18:21]
	v_mfma_f32_16x16x32_bf16 v[6:9], v[146:149], v[194:197], v[6:9]
	v_mfma_f32_16x16x32_bf16 v[2:5], v[154:157], v[194:197], v[2:5]
	v_mfma_f32_16x16x32_bf16 v[54:57], v[150:153], v[174:177], v[54:57]
	v_mfma_f32_16x16x32_bf16 v[50:53], v[158:161], v[174:177], v[50:53]
	v_mfma_f32_16x16x32_bf16 v[38:41], v[150:153], v[182:185], v[38:41]
	v_mfma_f32_16x16x32_bf16 v[34:37], v[158:161], v[182:185], v[34:37]
	v_mfma_f32_16x16x32_bf16 v[22:25], v[150:153], v[190:193], v[22:25]
	v_mfma_f32_16x16x32_bf16 v[18:21], v[158:161], v[190:193], v[18:21]
	v_mfma_f32_16x16x32_bf16 v[6:9], v[150:153], v[200:203], v[6:9]
	v_mfma_f32_16x16x32_bf16 v[2:5], v[158:161], v[200:203], v[2:5]
	s_barrier
; #define PG8_WAIT_V(n) asm volatile("s_waitcnt vmcnt(" #n ")" ::: "memory")
; template <class Epi, bool ALIGN_EPI, bool SP2, class Hook>
; __device__ __forceinline__ void gemm_phase(LAS unsigned char* lds, const Gemm g, const StaticOrder& S, const Epi& E, Acc& acc, const bool fresh, const Hook& H, const int wave_id) {
;     ...
;         for (int t = t0; t < nt; t += 2) {
;             const bool last = (t == nt - 2);
;             const Src a1 = cA + (size_t)(t + 1) * kstep;
;             const Src a2 = last ? nA : cA + (size_t)(t + 2) * kstep, b2 = last ? nB : cB + (size_t)(t + 2) * kstep;
;             const Src a3 = a2 + kstep, b3 = b2 + kstep;
;             if (last && has_next) H(nxt);
;             if constexpr (SP2) {
;             PG8_TRIP_SP2(PG8_WAIT_V(8));
	s_setprio 0
	v_add_u32_e32 v0, 0x18000, v172
	ds_read_b128 v[130:133], v0
	ds_read_b128 v[134:137], v0 offset:1024
	ds_read_b128 v[138:141], v0 offset:2048
	ds_read_b128 v[142:145], v0 offset:3072
	v_add_u32_e32 v0, 0x1c000, v172
	ds_read_b128 v[146:149], v0
	ds_read_b128 v[150:153], v0 offset:1024
	ds_read_b128 v[154:157], v0 offset:2048
	ds_read_b128 v[158:161], v0 offset:3072
	s_add_i32 s62, s62, 0xc0000
	s_mov_b32 m0, s37
	ds_read_b128 v[162:165], v173 offset:32768
	ds_read_b128 v[174:177], v173 offset:33792
	ds_read_b128 v[178:181], v173 offset:34816
	ds_read_b128 v[182:185], v173 offset:35840
	ds_read_b128 v[186:189], v173 offset:36864
	ds_read_b128 v[190:193], v173 offset:37888
	ds_read_b128 v[194:197], v173 offset:38912
	ds_read_b128 v[200:203], v173 offset:39936
	buffer_load_dwordx4 v168, s[16:19], s62 offen lds
	s_mov_b32 m0, s38
	s_nop 0
	buffer_load_dwordx4 v170, s[16:19], s62 offen lds
	s_waitcnt vmcnt(8)
	s_waitcnt lgkmcnt(0)
	s_setprio 3
	s_barrier
	v_mfma_f32_16x16x32_bf16 v[126:129], v[130:133], v[162:165], v[126:129]
	v_mfma_f32_16x16x32_bf16 v[122:125], v[138:141], v[162:165], v[122:125]
	v_mfma_f32_16x16x32_bf16 v[110:113], v[130:133], v[178:181], v[110:113]
	v_mfma_f32_16x16x32_bf16 v[106:109], v[138:141], v[178:181], v[106:109]
	v_mfma_f32_16x16x32_bf16 v[94:97], v[130:133], v[186:189], v[94:97]
	v_mfma_f32_16x16x32_bf16 v[90:93], v[138:141], v[186:189], v[90:93]
	v_mfma_f32_16x16x32_bf16 v[78:81], v[130:133], v[194:197], v[78:81]
	v_mfma_f32_16x16x32_bf16 v[74:77], v[138:141], v[194:197], v[74:77]
	v_mfma_f32_16x16x32_bf16 v[126:129], v[134:137], v[174:177], v[126:129]
	v_mfma_f32_16x16x32_bf16 v[122:125], v[142:145], v[174:177], v[122:125]
	v_mfma_f32_16x16x32_bf16 v[110:113], v[134:137], v[182:185], v[110:113]
	v_mfma_f32_16x16x32_bf16 v[106:109], v[142:145], v[182:185], v[106:109]
	v_mfma_f32_16x16x32_bf16 v[94:97], v[134:137], v[190:193], v[94:97]
	v_mfma_f32_16x16x32_bf16 v[90:93], v[142:145], v[190:193], v[90:93]
	v_mfma_f32_16x16x32_bf16 v[78:81], v[134:137], v[200:203], v[78:81]
	v_mfma_f32_16x16x32_bf16 v[74:77], v[142:145], v[200:203], v[74:77]
	v_mfma_f32_16x16x32_bf16 v[118:121], v[146:149], v[162:165], v[118:121]
	v_mfma_f32_16x16x32_bf16 v[114:117], v[154:157], v[162:165], v[114:117]
	v_mfma_f32_16x16x32_bf16 v[102:105], v[146:149], v[178:181], v[102:105]
	v_mfma_f32_16x16x32_bf16 v[98:101], v[154:157], v[178:181], v[98:101]
	v_mfma_f32_16x16x32_bf16 v[86:89], v[146:149], v[186:189], v[86:89]
	v_mfma_f32_16x16x32_bf16 v[82:85], v[154:157], v[186:189], v[82:85]
	v_mfma_f32_16x16x32_bf16 v[70:73], v[146:149], v[194:197], v[70:73]
	v_mfma_f32_16x16x32_bf16 v[66:69], v[154:157], v[194:197], v[66:69]
	v_mfma_f32_16x16x32_bf16 v[118:121], v[150:153], v[174:177], v[118:121]
	v_mfma_f32_16x16x32_bf16 v[114:117], v[158:161], v[174:177], v[114:117]
	v_mfma_f32_16x16x32_bf16 v[102:105], v[150:153], v[182:185], v[102:105]
	v_mfma_f32_16x16x32_bf16 v[98:101], v[158:161], v[182:185], v[98:101]
	v_mfma_f32_16x16x32_bf16 v[86:89], v[150:153], v[190:193], v[86:89]
	v_mfma_f32_16x16x32_bf16 v[82:85], v[158:161], v[190:193], v[82:85]
	v_mfma_f32_16x16x32_bf16 v[70:73], v[150:153], v[200:203], v[70:73]
	v_mfma_f32_16x16x32_bf16 v[66:69], v[158:161], v[200:203], v[66:69]
	s_barrier
	s_setprio 0
	s_mov_b32 m0, s39
	s_or_b32 s62, s60, 0x80
	ds_read_b128 v[162:165], v173 offset:49152
	ds_read_b128 v[174:177], v173 offset:50176
	ds_read_b128 v[178:181], v173 offset:51200
	ds_read_b128 v[182:185], v173 offset:52224
	ds_read_b128 v[186:189], v173 offset:53248
	ds_read_b128 v[190:193], v173 offset:54272
	ds_read_b128 v[194:197], v173 offset:55296
	ds_read_b128 v[200:203], v173 offset:56320
	buffer_load_dwordx4 v169, s[12:15], s62 offen lds
	s_mov_b32 m0, s40
	s_add_i32 s60, s60, 0xb0080
	buffer_load_dwordx4 v171, s[12:15], s62 offen lds
	s_mov_b32 m0, s43
	s_nop 0
	buffer_load_dwordx4 v169, s[12:15], s60 offen lds
	s_mov_b32 m0, s42
	s_nop 0
	buffer_load_dwordx4 v171, s[12:15], s60 offen lds
	s_mov_b32 m0, s41
	s_nop 0
	buffer_load_dwordx4 v168, s[16:19], s61 offen lds
	s_mov_b32 m0, s33
	s_nop 0
	buffer_load_dwordx4 v170, s[16:19], s61 offen lds
	s_waitcnt vmcnt(8)
	s_waitcnt lgkmcnt(0)
	s_setprio 3
	s_barrier
	v_mfma_f32_16x16x32_bf16 v[62:65], v[130:133], v[162:165], v[62:65]
	v_mfma_f32_16x16x32_bf16 v[58:61], v[138:141], v[162:165], v[58:61]
	v_mfma_f32_16x16x32_bf16 v[46:49], v[130:133], v[178:181], v[46:49]
	v_mfma_f32_16x16x32_bf16 v[42:45], v[138:141], v[178:181], v[42:45]
	v_mfma_f32_16x16x32_bf16 v[30:33], v[130:133], v[186:189], v[30:33]
	v_mfma_f32_16x16x32_bf16 v[26:29], v[138:141], v[186:189], v[26:29]
	v_mfma_f32_16x16x32_bf16 v[14:17], v[130:133], v[194:197], v[14:17]
	v_mfma_f32_16x16x32_bf16 v[10:13], v[138:141], v[194:197], v[10:13]
	v_mfma_f32_16x16x32_bf16 v[62:65], v[134:137], v[174:177], v[62:65]
	v_mfma_f32_16x16x32_bf16 v[58:61], v[142:145], v[174:177], v[58:61]
	v_mfma_f32_16x16x32_bf16 v[46:49], v[134:137], v[182:185], v[46:49]
	v_mfma_f32_16x16x32_bf16 v[42:45], v[142:145], v[182:185], v[42:45]
	v_mfma_f32_16x16x32_bf16 v[30:33], v[134:137], v[190:193], v[30:33]
	v_mfma_f32_16x16x32_bf16 v[26:29], v[142:145], v[190:193], v[26:29]
	v_mfma_f32_16x16x32_bf16 v[14:17], v[134:137], v[200:203], v[14:17]
	v_mfma_f32_16x16x32_bf16 v[10:13], v[142:145], v[200:203], v[10:13]
	v_mfma_f32_16x16x32_bf16 v[54:57], v[146:149], v[162:165], v[54:57]
	v_mfma_f32_16x16x32_bf16 v[50:53], v[154:157], v[162:165], v[50:53]
	v_mfma_f32_16x16x32_bf16 v[38:41], v[146:149], v[178:181], v[38:41]
	v_mfma_f32_16x16x32_bf16 v[34:37], v[154:157], v[178:181], v[34:37]
	v_mfma_f32_16x16x32_bf16 v[22:25], v[146:149], v[186:189], v[22:25]
	v_mfma_f32_16x16x32_bf16 v[18:21], v[154:157], v[186:189], v[18:21]
	v_mfma_f32_16x16x32_bf16 v[6:9], v[146:149], v[194:197], v[6:9]
	v_mfma_f32_16x16x32_bf16 v[2:5], v[154:157], v[194:197], v[2:5]
	v_mfma_f32_16x16x32_bf16 v[54:57], v[150:153], v[174:177], v[54:57]
	v_mfma_f32_16x16x32_bf16 v[50:53], v[158:161], v[174:177], v[50:53]
	v_mfma_f32_16x16x32_bf16 v[38:41], v[150:153], v[182:185], v[38:41]
	v_mfma_f32_16x16x32_bf16 v[34:37], v[158:161], v[182:185], v[34:37]
	v_mfma_f32_16x16x32_bf16 v[22:25], v[150:153], v[190:193], v[22:25]
	v_mfma_f32_16x16x32_bf16 v[18:21], v[158:161], v[190:193], v[18:21]
	v_mfma_f32_16x16x32_bf16 v[6:9], v[150:153], v[200:203], v[6:9]
	v_mfma_f32_16x16x32_bf16 v[2:5], v[158:161], v[200:203], v[2:5]
	s_barrier
	s_setprio 0
	s_add_i32 s59, s59, 2
	s_addk_i32 s2, 0x100
	s_addk_i32 s3, 0x100
	s_cmp_gt_u32 s59, 41
	s_cbranch_scc0 .LBB0_1614
	v_readlane_b32 s2, v251, 45
	v_readlane_b32 s3, v251, 46
	s_and_b64 vcc, exec, s[2:3]
	s_cbranch_vccz .LBB0_1617
	s_barrier
